# GEMM K-loops (14): back-edge rotation - loop-carried SALU bookkeeping moved above the iteration's last s_barrier
# speedup vs baseline: 1.0000x; 1.0000x over previous
; #define PG8_STAGE(bufoff, gbase, voff) do { _Pragma("unroll") for (int _i = 0; _i < 2; ++_i) \
;         __builtin_amdgcn_global_load_lds((const unsigned*)((const char*)(gbase) + (voff)[_i]), (PG8_LAS unsigned*)(lds + (bufoff) + ldsw + _i * 8192), 16, 0, 0); } while (0)
; #define PG8_LDA(dst, b, h) do { _Pragma("unroll") for (int m = 0; m < 4; ++m) _Pragma("unroll") for (int k = 0; k < 2; ++k) dst[m][k] = *(const PG8_LAS bf16x8*)(lds + PG8_SA(b, h) + aoff + m * 2048 + k * 1024); } while (0)
; #define PG8_LDB(dst, b, h) do { _Pragma("unroll") for (int n = 0; n < 2; ++n) _Pragma("unroll") for (int k = 0; k < 2; ++k) dst[n][k] = *(const PG8_LAS bf16x8*)(lds + PG8_SB(b, h) + boff + n * 2048 + k * 1024); } while (0)
; #define PG8_MMA(ai, bj, At, Bt) do { __builtin_amdgcn_s_setprio(1); _Pragma("unroll") for (int m = 0; m < 4; ++m) _Pragma("unroll") for (int n = 0; n < 2; ++n) _Pragma("unroll") for (int k = 0; k < 2; ++k) \
;         acc[ai][bj][m][n] = __builtin_amdgcn_mfma_f32_16x16x32_bf16(Bt[n][k], At[m][k], acc[ai][bj][m][n], 0, 0, 0); __builtin_amdgcn_s_setprio(0); } while (0)
; #define PG8_WAIT_V(n) asm volatile("s_waitcnt vmcnt(" #n ")" ::: "memory")
; #define PG8_WAIT_L(n) asm volatile("s_waitcnt lgkmcnt(" #n ")" ::: "memory")
; #define PG8_BAR __builtin_amdgcn_s_barrier()
; template <class Epi, class Sched, bool ALIGN_EPI = false, bool SP2 = false>
; __device__ __forceinline__ void gemm_phase(PG8_LAS unsigned char* lds, const Gemm g, const Sched& S, const Epi& E, const int wave_in) {
;     ...
;         for (int t = 0; t < nt; t += 2) {
;             const bool last = (t == nt - 2);
;             const char* a1 = cA + (size_t)(t + 1) * kstep;
;             const char* a2 = last ? nA : cA + (size_t)(t + 2) * kstep; const char* b2 = last ? nB : cB + (size_t)(t + 2) * kstep;
;             const char* a3 = a2 + kstep; const char* b3 = b2 + kstep;
;             if (last && has_next) S.a_ready(nxt);
;             if constexpr (SP2) {
;             PG8_LDB(B0, 0, 0); PG8_LDB(B1, 0, 1); PG8_SCHED; PG8_LDA(At, 0, 0); PG8_STAGE(PG8_SA(1, 1), a1 + hstepA, voffA);
;             PG8_WAIT_V(8); PG8_WAIT_L(0); PG8_BAR; PG8_MMA(0, 0, At, B0); PG8_MMA(0, 1, At, B1); PG8_BAR; PG8_SCHED;
;             PG8_LDA(At, 0, 1); PG8_STAGE(PG8_SB(0, 0), b2, voffB); PG8_STAGE(PG8_SB(0, 1), b2 + hstep, voffB); PG8_STAGE(PG8_SA(0, 0), a2, voffA);
.LBB0_498:
	ds_read_b128 v[144:147], v153
	ds_read_b128 v[158:161], v153 offset:1024
	ds_read_b128 v[162:165], v153 offset:2048
	ds_read_b128 v[166:169], v153 offset:3072
	ds_read_b128 v[170:173], v154
	ds_read_b128 v[174:177], v154 offset:1024
	ds_read_b128 v[178:181], v154 offset:2048
	ds_read_b128 v[182:185], v154 offset:3072
	s_add_u32 s4, s68, 0xfff80080
	s_addc_u32 s5, s69, -1
	s_cmp_eq_u32 s78, 28
	s_cselect_b32 s71, s36, s5
	s_cselect_b32 s70, s37, s4
	s_cselect_b32 s5, s61, s73
	s_cselect_b32 s4, s63, s72
	v_lshl_add_u64 v[148:149], s[68:69], 0, v[136:137]
	s_add_i32 m0, s19, 0xc000
	ds_read_b128 v[186:189], v155
	ds_read_b128 v[190:193], v155 offset:1024
	ds_read_b128 v[194:197], v155 offset:2048
	ds_read_b128 v[198:201], v155 offset:3072
	ds_read_b128 v[202:205], v155 offset:4096
	ds_read_b128 v[206:209], v155 offset:5120
	ds_read_b128 v[210:213], v155 offset:6144
	ds_read_b128 v[214:217], v155 offset:7168
	global_load_lds_dwordx4 v[148:149], off
	v_lshl_add_u64 v[148:149], s[68:69], 0, v[138:139]
	s_add_i32 m0, s19, 0xe000
	s_nop 0
	global_load_lds_dwordx4 v[148:149], off
	s_waitcnt vmcnt(8)
	s_waitcnt lgkmcnt(0)
	s_barrier
	s_setprio 1
	s_waitcnt lgkmcnt(0)
	v_mfma_f32_16x16x32_bf16 v[120:123], v[144:147], v[186:189], v[120:123]
	v_mfma_f32_16x16x32_bf16 v[116:119], v[162:165], v[186:189], v[116:119]
	v_mfma_f32_16x16x32_bf16 v[104:107], v[144:147], v[194:197], v[104:107]
	v_mfma_f32_16x16x32_bf16 v[100:103], v[162:165], v[194:197], v[100:103]
	v_mfma_f32_16x16x32_bf16 v[88:91], v[144:147], v[202:205], v[88:91]
	v_mfma_f32_16x16x32_bf16 v[84:87], v[162:165], v[202:205], v[84:87]
	v_mfma_f32_16x16x32_bf16 v[72:75], v[144:147], v[210:213], v[72:75]
	v_mfma_f32_16x16x32_bf16 v[68:71], v[162:165], v[210:213], v[68:71]
	v_mfma_f32_16x16x32_bf16 v[120:123], v[158:161], v[190:193], v[120:123]
	v_mfma_f32_16x16x32_bf16 v[116:119], v[166:169], v[190:193], v[116:119]
	v_mfma_f32_16x16x32_bf16 v[104:107], v[158:161], v[198:201], v[104:107]
	v_mfma_f32_16x16x32_bf16 v[100:103], v[166:169], v[198:201], v[100:103]
	v_mfma_f32_16x16x32_bf16 v[88:91], v[158:161], v[206:209], v[88:91]
	v_mfma_f32_16x16x32_bf16 v[84:87], v[166:169], v[206:209], v[84:87]
	v_mfma_f32_16x16x32_bf16 v[72:75], v[158:161], v[214:217], v[72:75]
	v_mfma_f32_16x16x32_bf16 v[68:71], v[166:169], v[214:217], v[68:71]
	s_setprio 0
	s_setprio 1
	v_mfma_f32_16x16x32_bf16 v[124:127], v[170:173], v[186:189], v[124:127]
	v_mfma_f32_16x16x32_bf16 v[112:115], v[178:181], v[186:189], v[112:115]
	v_mfma_f32_16x16x32_bf16 v[108:111], v[170:173], v[194:197], v[108:111]
	v_mfma_f32_16x16x32_bf16 v[96:99], v[178:181], v[194:197], v[96:99]
	v_mfma_f32_16x16x32_bf16 v[92:95], v[170:173], v[202:205], v[92:95]
	v_mfma_f32_16x16x32_bf16 v[80:83], v[178:181], v[202:205], v[80:83]
	v_mfma_f32_16x16x32_bf16 v[76:79], v[170:173], v[210:213], v[76:79]
	v_mfma_f32_16x16x32_bf16 v[64:67], v[178:181], v[210:213], v[64:67]
	v_mfma_f32_16x16x32_bf16 v[124:127], v[174:177], v[190:193], v[124:127]
	v_mfma_f32_16x16x32_bf16 v[112:115], v[182:185], v[190:193], v[112:115]
	v_mfma_f32_16x16x32_bf16 v[108:111], v[174:177], v[198:201], v[108:111]
	v_mfma_f32_16x16x32_bf16 v[96:99], v[182:185], v[198:201], v[96:99]
	v_mfma_f32_16x16x32_bf16 v[92:95], v[174:177], v[206:209], v[92:95]
	v_mfma_f32_16x16x32_bf16 v[80:83], v[182:185], v[206:209], v[80:83]
	v_mfma_f32_16x16x32_bf16 v[76:79], v[174:177], v[214:217], v[76:79]
	v_mfma_f32_16x16x32_bf16 v[64:67], v[182:185], v[214:217], v[64:67]
	s_setprio 0
	s_barrier
	s_add_i32 s79, s48, s11
	v_lshl_add_u64 v[148:149], s[4:5], 0, v[132:133]
	s_mov_b32 m0, s79
	ds_read_b128 v[186:189], v155 offset:16384
	ds_read_b128 v[190:193], v155 offset:17408
	ds_read_b128 v[194:197], v155 offset:18432
	ds_read_b128 v[198:201], v155 offset:19456
	ds_read_b128 v[202:205], v155 offset:20480
	ds_read_b128 v[206:209], v155 offset:21504
	ds_read_b128 v[210:213], v155 offset:22528
	ds_read_b128 v[214:217], v155 offset:23552
	global_load_lds_dwordx4 v[148:149], off
	s_add_i32 m0, s79, 0x2000
	s_add_u32 s84, s4, 0x80000
	v_lshl_add_u64 v[218:219], s[4:5], 0, v[128:129]
	s_addc_u32 s85, s5, 0
	s_add_i32 s79, s49, s11
	global_load_lds_dwordx4 v[218:219], off
	v_lshl_add_u64 v[220:221], s[84:85], 0, v[132:133]
	s_mov_b32 m0, s79
	v_lshl_add_u64 v[222:223], s[70:71], 0, v[130:131]
	global_load_lds_dwordx4 v[220:221], off
	v_lshl_add_u64 v[220:221], s[84:85], 0, v[128:129]
	s_add_i32 m0, s79, 0x2000
	s_nop 0
	global_load_lds_dwordx4 v[220:221], off
	v_lshl_add_u64 v[220:221], s[70:71], 0, v[134:135]
	s_mov_b32 m0, s19
	s_nop 0
	global_load_lds_dwordx4 v[220:221], off
	s_mov_b32 m0, s38
	s_nop 0
	global_load_lds_dwordx4 v[222:223], off
	s_waitcnt vmcnt(8)
	s_waitcnt lgkmcnt(0)
	s_barrier
; #define PG8_STAGE(bufoff, gbase, voff) do { _Pragma("unroll") for (int _i = 0; _i < 2; ++_i) \
;         __builtin_amdgcn_global_load_lds((const unsigned*)((const char*)(gbase) + (voff)[_i]), (PG8_LAS unsigned*)(lds + (bufoff) + ldsw + _i * 8192), 16, 0, 0); } while (0)
; #define PG8_LDA(dst, b, h) do { _Pragma("unroll") for (int m = 0; m < 4; ++m) _Pragma("unroll") for (int k = 0; k < 2; ++k) dst[m][k] = *(const PG8_LAS bf16x8*)(lds + PG8_SA(b, h) + aoff + m * 2048 + k * 1024); } while (0)
; #define PG8_LDB(dst, b, h) do { _Pragma("unroll") for (int n = 0; n < 2; ++n) _Pragma("unroll") for (int k = 0; k < 2; ++k) dst[n][k] = *(const PG8_LAS bf16x8*)(lds + PG8_SB(b, h) + boff + n * 2048 + k * 1024); } while (0)
; #define PG8_MMA(ai, bj, At, Bt) do { __builtin_amdgcn_s_setprio(1); _Pragma("unroll") for (int m = 0; m < 4; ++m) _Pragma("unroll") for (int n = 0; n < 2; ++n) _Pragma("unroll") for (int k = 0; k < 2; ++k) \
;         acc[ai][bj][m][n] = __builtin_amdgcn_mfma_f32_16x16x32_bf16(Bt[n][k], At[m][k], acc[ai][bj][m][n], 0, 0, 0); __builtin_amdgcn_s_setprio(0); } while (0)
; #define PG8_WAIT_V(n) asm volatile("s_waitcnt vmcnt(" #n ")" ::: "memory")
; #define PG8_WAIT_L(n) asm volatile("s_waitcnt lgkmcnt(" #n ")" ::: "memory")
; #define PG8_BAR __builtin_amdgcn_s_barrier()
; #define PG8_SCHED __builtin_amdgcn_sched_barrier(0)
; template <class Epi, class Sched, bool ALIGN_EPI = false, bool SP2 = false>
; __device__ __forceinline__ void gemm_phase(PG8_LAS unsigned char* lds, const Gemm g, const Sched& S, const Epi& E, const int wave_in) {
;     ...
;             PG8_WAIT_V(8); PG8_WAIT_L(0); PG8_BAR; PG8_MMA(1, 0, At, B0); PG8_MMA(1, 1, At, B1); PG8_BAR; PG8_SCHED;
;             PG8_LDB(B0, 1, 0); PG8_LDB(B1, 1, 1); PG8_SCHED; PG8_LDA(At, 1, 0); PG8_STAGE(PG8_SA(0, 1), a2 + hstepA, voffA);
;             PG8_WAIT_V(8); PG8_WAIT_L(0); PG8_BAR; PG8_MMA(0, 0, At, B0); PG8_MMA(0, 1, At, B1); PG8_BAR; PG8_SCHED;
	s_setprio 1
	s_waitcnt lgkmcnt(0)
	v_mfma_f32_16x16x32_bf16 v[56:59], v[144:147], v[186:189], v[56:59]
	v_mfma_f32_16x16x32_bf16 v[52:55], v[162:165], v[186:189], v[52:55]
	v_mfma_f32_16x16x32_bf16 v[40:43], v[144:147], v[194:197], v[40:43]
	v_mfma_f32_16x16x32_bf16 v[36:39], v[162:165], v[194:197], v[36:39]
	v_mfma_f32_16x16x32_bf16 v[24:27], v[144:147], v[202:205], v[24:27]
	v_mfma_f32_16x16x32_bf16 v[20:23], v[162:165], v[202:205], v[20:23]
	v_mfma_f32_16x16x32_bf16 v[8:11], v[144:147], v[210:213], v[8:11]
	v_mfma_f32_16x16x32_bf16 v[4:7], v[162:165], v[210:213], v[4:7]
	v_mfma_f32_16x16x32_bf16 v[56:59], v[158:161], v[190:193], v[56:59]
	v_mfma_f32_16x16x32_bf16 v[52:55], v[166:169], v[190:193], v[52:55]
	v_mfma_f32_16x16x32_bf16 v[40:43], v[158:161], v[198:201], v[40:43]
	v_mfma_f32_16x16x32_bf16 v[36:39], v[166:169], v[198:201], v[36:39]
	v_mfma_f32_16x16x32_bf16 v[24:27], v[158:161], v[206:209], v[24:27]
	v_mfma_f32_16x16x32_bf16 v[20:23], v[166:169], v[206:209], v[20:23]
	v_mfma_f32_16x16x32_bf16 v[8:11], v[158:161], v[214:217], v[8:11]
	v_mfma_f32_16x16x32_bf16 v[4:7], v[166:169], v[214:217], v[4:7]
	s_setprio 0
	s_setprio 1
	v_mfma_f32_16x16x32_bf16 v[60:63], v[170:173], v[186:189], v[60:63]
	v_mfma_f32_16x16x32_bf16 v[48:51], v[178:181], v[186:189], v[48:51]
	v_mfma_f32_16x16x32_bf16 v[44:47], v[170:173], v[194:197], v[44:47]
	v_mfma_f32_16x16x32_bf16 v[32:35], v[178:181], v[194:197], v[32:35]
	v_mfma_f32_16x16x32_bf16 v[28:31], v[170:173], v[202:205], v[28:31]
	v_mfma_f32_16x16x32_bf16 v[16:19], v[178:181], v[202:205], v[16:19]
	v_mfma_f32_16x16x32_bf16 v[12:15], v[170:173], v[210:213], v[12:15]
	v_mfma_f32_16x16x32_bf16 v[0:3], v[178:181], v[210:213], v[0:3]
	v_mfma_f32_16x16x32_bf16 v[60:63], v[174:177], v[190:193], v[60:63]
	v_mfma_f32_16x16x32_bf16 v[48:51], v[182:185], v[190:193], v[48:51]
	v_mfma_f32_16x16x32_bf16 v[44:47], v[174:177], v[198:201], v[44:47]
	v_mfma_f32_16x16x32_bf16 v[32:35], v[182:185], v[198:201], v[32:35]
	v_mfma_f32_16x16x32_bf16 v[28:31], v[174:177], v[206:209], v[28:31]
	v_mfma_f32_16x16x32_bf16 v[16:19], v[182:185], v[206:209], v[16:19]
	v_mfma_f32_16x16x32_bf16 v[12:15], v[174:177], v[214:217], v[12:15]
	v_mfma_f32_16x16x32_bf16 v[0:3], v[182:185], v[214:217], v[0:3]
	s_setprio 0
	s_barrier
	s_add_i32 s79, 0, 0x18000
	v_add_u32_e32 v157, s79, v151
	s_add_i32 s84, 0, 0x1c000
	ds_read_b128 v[144:147], v157
	ds_read_b128 v[158:161], v157 offset:1024
	ds_read_b128 v[162:165], v157 offset:2048
	ds_read_b128 v[166:169], v157 offset:3072
	v_add_u32_e32 v157, s84, v151
	ds_read_b128 v[170:173], v157
	ds_read_b128 v[174:177], v157 offset:1024
	ds_read_b128 v[178:181], v157 offset:2048
	ds_read_b128 v[182:185], v157 offset:3072
	s_add_u32 s70, s70, 0x80000
	s_addc_u32 s71, s71, 0
	s_mov_b32 m0, s39
	v_lshl_add_u64 v[224:225], s[70:71], 0, v[134:135]
	ds_read_b128 v[186:189], v155 offset:32768
	ds_read_b128 v[190:193], v155 offset:33792
	ds_read_b128 v[194:197], v155 offset:34816
	ds_read_b128 v[198:201], v155 offset:35840
	ds_read_b128 v[202:205], v155 offset:36864
	ds_read_b128 v[206:209], v155 offset:37888
	ds_read_b128 v[210:213], v155 offset:38912
	ds_read_b128 v[214:217], v155 offset:39936
	global_load_lds_dwordx4 v[224:225], off
	v_lshl_add_u64 v[224:225], s[70:71], 0, v[130:131]
	s_mov_b32 m0, s40
	s_nop 0
	global_load_lds_dwordx4 v[224:225], off
	s_waitcnt vmcnt(8)
	s_waitcnt lgkmcnt(0)
	s_barrier
	s_setprio 1
	s_waitcnt lgkmcnt(0)
	v_mfma_f32_16x16x32_bf16 v[120:123], v[144:147], v[186:189], v[120:123]
	v_mfma_f32_16x16x32_bf16 v[116:119], v[162:165], v[186:189], v[116:119]
	v_mfma_f32_16x16x32_bf16 v[104:107], v[144:147], v[194:197], v[104:107]
	v_mfma_f32_16x16x32_bf16 v[100:103], v[162:165], v[194:197], v[100:103]
	v_mfma_f32_16x16x32_bf16 v[88:91], v[144:147], v[202:205], v[88:91]
	v_mfma_f32_16x16x32_bf16 v[84:87], v[162:165], v[202:205], v[84:87]
	v_mfma_f32_16x16x32_bf16 v[72:75], v[144:147], v[210:213], v[72:75]
	v_mfma_f32_16x16x32_bf16 v[68:71], v[162:165], v[210:213], v[68:71]
	v_mfma_f32_16x16x32_bf16 v[120:123], v[158:161], v[190:193], v[120:123]
	v_mfma_f32_16x16x32_bf16 v[116:119], v[166:169], v[190:193], v[116:119]
	v_mfma_f32_16x16x32_bf16 v[104:107], v[158:161], v[198:201], v[104:107]
	v_mfma_f32_16x16x32_bf16 v[100:103], v[166:169], v[198:201], v[100:103]
	v_mfma_f32_16x16x32_bf16 v[88:91], v[158:161], v[206:209], v[88:91]
	v_mfma_f32_16x16x32_bf16 v[84:87], v[166:169], v[206:209], v[84:87]
	v_mfma_f32_16x16x32_bf16 v[72:75], v[158:161], v[214:217], v[72:75]
	v_mfma_f32_16x16x32_bf16 v[68:71], v[166:169], v[214:217], v[68:71]
	s_setprio 0
	s_setprio 1
	v_mfma_f32_16x16x32_bf16 v[124:127], v[170:173], v[186:189], v[124:127]
	v_mfma_f32_16x16x32_bf16 v[112:115], v[178:181], v[186:189], v[112:115]
	v_mfma_f32_16x16x32_bf16 v[108:111], v[170:173], v[194:197], v[108:111]
	v_mfma_f32_16x16x32_bf16 v[96:99], v[178:181], v[194:197], v[96:99]
	v_mfma_f32_16x16x32_bf16 v[92:95], v[170:173], v[202:205], v[92:95]
	v_mfma_f32_16x16x32_bf16 v[80:83], v[178:181], v[202:205], v[80:83]
	v_mfma_f32_16x16x32_bf16 v[76:79], v[170:173], v[210:213], v[76:79]
	v_mfma_f32_16x16x32_bf16 v[64:67], v[178:181], v[210:213], v[64:67]
	v_mfma_f32_16x16x32_bf16 v[124:127], v[174:177], v[190:193], v[124:127]
	v_mfma_f32_16x16x32_bf16 v[112:115], v[182:185], v[190:193], v[112:115]
	v_mfma_f32_16x16x32_bf16 v[108:111], v[174:177], v[198:201], v[108:111]
	v_mfma_f32_16x16x32_bf16 v[96:99], v[182:185], v[198:201], v[96:99]
	v_mfma_f32_16x16x32_bf16 v[92:95], v[174:177], v[206:209], v[92:95]
	v_mfma_f32_16x16x32_bf16 v[80:83], v[182:185], v[206:209], v[80:83]
	v_mfma_f32_16x16x32_bf16 v[76:79], v[174:177], v[214:217], v[76:79]
	v_mfma_f32_16x16x32_bf16 v[64:67], v[182:185], v[214:217], v[64:67]
	s_setprio 0
	s_barrier
; #define PG8_STAGE(bufoff, gbase, voff) do { _Pragma("unroll") for (int _i = 0; _i < 2; ++_i) \
;         __builtin_amdgcn_global_load_lds((const unsigned*)((const char*)(gbase) + (voff)[_i]), (PG8_LAS unsigned*)(lds + (bufoff) + ldsw + _i * 8192), 16, 0, 0); } while (0)
; #define PG8_LDA(dst, b, h) do { _Pragma("unroll") for (int m = 0; m < 4; ++m) _Pragma("unroll") for (int k = 0; k < 2; ++k) dst[m][k] = *(const PG8_LAS bf16x8*)(lds + PG8_SA(b, h) + aoff + m * 2048 + k * 1024); } while (0)
; #define PG8_MMA(ai, bj, At, Bt) do { __builtin_amdgcn_s_setprio(1); _Pragma("unroll") for (int m = 0; m < 4; ++m) _Pragma("unroll") for (int n = 0; n < 2; ++n) _Pragma("unroll") for (int k = 0; k < 2; ++k) \
;         acc[ai][bj][m][n] = __builtin_amdgcn_mfma_f32_16x16x32_bf16(Bt[n][k], At[m][k], acc[ai][bj][m][n], 0, 0, 0); __builtin_amdgcn_s_setprio(0); } while (0)
; #define PG8_WAIT_V(n) asm volatile("s_waitcnt vmcnt(" #n ")" ::: "memory")
; #define PG8_WAIT_L(n) asm volatile("s_waitcnt lgkmcnt(" #n ")" ::: "memory")
; #define PG8_BAR __builtin_amdgcn_s_barrier()
; #define PG8_SCHED __builtin_amdgcn_sched_barrier(0)
; template <class Epi, class Sched, bool ALIGN_EPI = false, bool SP2 = false>
; __device__ __forceinline__ void gemm_phase(PG8_LAS unsigned char* lds, const Gemm g, const Sched& S, const Epi& E, const int wave_in) {
;     ...
;         for (int t = 0; t < nt; t += 2) {
;             const bool last = (t == nt - 2);
;             const char* a1 = cA + (size_t)(t + 1) * kstep;
;             const char* a2 = last ? nA : cA + (size_t)(t + 2) * kstep; const char* b2 = last ? nB : cB + (size_t)(t + 2) * kstep;
;             const char* a3 = a2 + kstep; const char* b3 = b2 + kstep;
;     ...
;             PG8_LDA(At, 1, 1); PG8_STAGE(PG8_SB(1, 0), b3, voffB); PG8_STAGE(PG8_SB(1, 1), b3 + hstep, voffB); PG8_STAGE(PG8_SA(1, 0), a3, voffA);
;             PG8_WAIT_V(8); PG8_WAIT_L(0); PG8_BAR; PG8_MMA(1, 0, At, B0); PG8_MMA(1, 1, At, B1); PG8_BAR; PG8_SCHED;
	s_add_i32 s70, s79, s11
	v_lshl_add_u64 v[148:149], v[148:149], 0, s[56:57]
	s_mov_b32 m0, s70
	ds_read_b128 v[186:189], v155 offset:49152
	ds_read_b128 v[190:193], v155 offset:50176
	ds_read_b128 v[194:197], v155 offset:51200
	ds_read_b128 v[198:201], v155 offset:52224
	ds_read_b128 v[202:205], v155 offset:53248
	ds_read_b128 v[206:209], v155 offset:54272
	ds_read_b128 v[210:213], v155 offset:55296
	ds_read_b128 v[214:217], v155 offset:56320
	global_load_lds_dwordx4 v[148:149], off
	s_add_i32 m0, s70, 0x2000
	s_add_u32 s4, s4, 0x80080
	v_lshl_add_u64 v[148:149], v[218:219], 0, s[56:57]
	s_addc_u32 s5, s5, 0
	s_add_i32 s70, s84, s11
	global_load_lds_dwordx4 v[148:149], off
	v_lshl_add_u64 v[148:149], s[4:5], 0, v[132:133]
	s_mov_b32 m0, s70
	s_nop 0
	global_load_lds_dwordx4 v[148:149], off
	v_lshl_add_u64 v[148:149], s[4:5], 0, v[128:129]
	s_add_i32 m0, s70, 0x2000
	s_nop 0
	global_load_lds_dwordx4 v[148:149], off
	v_lshl_add_u64 v[148:149], v[220:221], 0, s[56:57]
	s_mov_b32 m0, s42
	s_nop 0
	global_load_lds_dwordx4 v[148:149], off
	v_lshl_add_u64 v[148:149], v[222:223], 0, s[56:57]
	s_mov_b32 m0, s43
	s_nop 0
	global_load_lds_dwordx4 v[148:149], off
	s_waitcnt vmcnt(8)
	s_waitcnt lgkmcnt(0)
	s_barrier
	s_setprio 1
	s_waitcnt lgkmcnt(0)
	v_mfma_f32_16x16x32_bf16 v[56:59], v[144:147], v[186:189], v[56:59]
	v_mfma_f32_16x16x32_bf16 v[52:55], v[162:165], v[186:189], v[52:55]
	v_mfma_f32_16x16x32_bf16 v[40:43], v[144:147], v[194:197], v[40:43]
	v_mfma_f32_16x16x32_bf16 v[36:39], v[162:165], v[194:197], v[36:39]
	v_mfma_f32_16x16x32_bf16 v[24:27], v[144:147], v[202:205], v[24:27]
	v_mfma_f32_16x16x32_bf16 v[20:23], v[162:165], v[202:205], v[20:23]
	v_mfma_f32_16x16x32_bf16 v[8:11], v[144:147], v[210:213], v[8:11]
	v_mfma_f32_16x16x32_bf16 v[4:7], v[162:165], v[210:213], v[4:7]
	v_mfma_f32_16x16x32_bf16 v[56:59], v[158:161], v[190:193], v[56:59]
	v_mfma_f32_16x16x32_bf16 v[52:55], v[166:169], v[190:193], v[52:55]
	v_mfma_f32_16x16x32_bf16 v[40:43], v[158:161], v[198:201], v[40:43]
	v_mfma_f32_16x16x32_bf16 v[36:39], v[166:169], v[198:201], v[36:39]
	v_mfma_f32_16x16x32_bf16 v[24:27], v[158:161], v[206:209], v[24:27]
	v_mfma_f32_16x16x32_bf16 v[20:23], v[166:169], v[206:209], v[20:23]
	v_mfma_f32_16x16x32_bf16 v[8:11], v[158:161], v[214:217], v[8:11]
	v_mfma_f32_16x16x32_bf16 v[4:7], v[166:169], v[214:217], v[4:7]
	s_setprio 0
	s_setprio 1
	v_mfma_f32_16x16x32_bf16 v[60:63], v[170:173], v[186:189], v[60:63]
	v_mfma_f32_16x16x32_bf16 v[48:51], v[178:181], v[186:189], v[48:51]
	v_mfma_f32_16x16x32_bf16 v[44:47], v[170:173], v[194:197], v[44:47]
	v_mfma_f32_16x16x32_bf16 v[32:35], v[178:181], v[194:197], v[32:35]
	v_mfma_f32_16x16x32_bf16 v[28:31], v[170:173], v[202:205], v[28:31]
	v_mfma_f32_16x16x32_bf16 v[16:19], v[178:181], v[202:205], v[16:19]
	v_mfma_f32_16x16x32_bf16 v[12:15], v[170:173], v[210:213], v[12:15]
	v_mfma_f32_16x16x32_bf16 v[0:3], v[178:181], v[210:213], v[0:3]
	v_mfma_f32_16x16x32_bf16 v[60:63], v[174:177], v[190:193], v[60:63]
	v_mfma_f32_16x16x32_bf16 v[48:51], v[182:185], v[190:193], v[48:51]
	v_mfma_f32_16x16x32_bf16 v[44:47], v[174:177], v[198:201], v[44:47]
	v_mfma_f32_16x16x32_bf16 v[32:35], v[182:185], v[198:201], v[32:35]
	v_mfma_f32_16x16x32_bf16 v[28:31], v[174:177], v[206:209], v[28:31]
	v_mfma_f32_16x16x32_bf16 v[16:19], v[182:185], v[206:209], v[16:19]
	v_mfma_f32_16x16x32_bf16 v[12:15], v[174:177], v[214:217], v[12:15]
	v_mfma_f32_16x16x32_bf16 v[0:3], v[182:185], v[214:217], v[0:3]
	s_setprio 0
	s_add_i32 s78, s78, 2
	s_add_u32 s68, s68, 0x100
	s_addc_u32 s69, s69, 0
	s_add_u32 s72, s72, 0x100
	s_addc_u32 s73, s73, 0
	s_cmp_gt_u32 s78, 29
	s_barrier
	s_cbranch_scc0 .LBB0_498
	s_and_b64 vcc, exec, s[58:59]
	s_cbranch_vccz .LBB0_501
	s_barrier

; #define PG8_STAGE(bufoff, gbase, voff) do { _Pragma("unroll") for (int _i = 0; _i < 2; ++_i) \
;         __builtin_amdgcn_global_load_lds((const unsigned*)((const char*)(gbase) + (voff)[_i]), (PG8_LAS unsigned*)(lds + (bufoff) + ldsw + _i * 8192), 16, 0, 0); } while (0)
; #define PG8_LDA(dst, b, h) do { _Pragma("unroll") for (int m = 0; m < 4; ++m) _Pragma("unroll") for (int k = 0; k < 2; ++k) dst[m][k] = *(const PG8_LAS bf16x8*)(lds + PG8_SA(b, h) + aoff + m * 2048 + k * 1024); } while (0)
; #define PG8_LDB(dst, b, h) do { _Pragma("unroll") for (int n = 0; n < 2; ++n) _Pragma("unroll") for (int k = 0; k < 2; ++k) dst[n][k] = *(const PG8_LAS bf16x8*)(lds + PG8_SB(b, h) + boff + n * 2048 + k * 1024); } while (0)
; #define PG8_MMA(ai, bj, At, Bt) do { __builtin_amdgcn_s_setprio(1); _Pragma("unroll") for (int m = 0; m < 4; ++m) _Pragma("unroll") for (int n = 0; n < 2; ++n) _Pragma("unroll") for (int k = 0; k < 2; ++k) \
;         acc[ai][bj][m][n] = __builtin_amdgcn_mfma_f32_16x16x32_bf16(Bt[n][k], At[m][k], acc[ai][bj][m][n], 0, 0, 0); __builtin_amdgcn_s_setprio(0); } while (0)
; #define PG8_WAIT_V(n) asm volatile("s_waitcnt vmcnt(" #n ")" ::: "memory")
; #define PG8_WAIT_L(n) asm volatile("s_waitcnt lgkmcnt(" #n ")" ::: "memory")
; #define PG8_BAR __builtin_amdgcn_s_barrier()
; template <class Epi, class Sched, bool ALIGN_EPI = false, bool SP2 = false>
; __device__ __forceinline__ void gemm_phase(PG8_LAS unsigned char* lds, const Gemm g, const Sched& S, const Epi& E, const int wave_in) {
;     ...
;         for (int t = 0; t < nt; t += 2) {
;             const bool last = (t == nt - 2);
;             const char* a1 = cA + (size_t)(t + 1) * kstep;
;             const char* a2 = last ? nA : cA + (size_t)(t + 2) * kstep; const char* b2 = last ? nB : cB + (size_t)(t + 2) * kstep;
;             const char* a3 = a2 + kstep; const char* b3 = b2 + kstep;
;             if (last && has_next) S.a_ready(nxt);
;             if constexpr (SP2) {
;             PG8_LDB(B0, 0, 0); PG8_LDB(B1, 0, 1); PG8_SCHED; PG8_LDA(At, 0, 0); PG8_STAGE(PG8_SA(1, 1), a1 + hstepA, voffA);
;             PG8_WAIT_V(8); PG8_WAIT_L(0); PG8_BAR; PG8_MMA(0, 0, At, B0); PG8_MMA(0, 1, At, B1); PG8_BAR; PG8_SCHED;
;             PG8_LDA(At, 0, 1); PG8_STAGE(PG8_SB(0, 0), b2, voffB); PG8_STAGE(PG8_SB(0, 1), b2 + hstep, voffB); PG8_STAGE(PG8_SA(0, 0), a2, voffA);
.LBB0_583:
	ds_read_b128 v[144:147], v151
	ds_read_b128 v[156:159], v151 offset:1024
	ds_read_b128 v[160:163], v151 offset:2048
	ds_read_b128 v[164:167], v151 offset:3072
	ds_read_b128 v[168:171], v152
	ds_read_b128 v[172:175], v152 offset:1024
	ds_read_b128 v[176:179], v152 offset:2048
	ds_read_b128 v[180:183], v152 offset:3072
	s_add_u32 s64, s62, 0x100
	s_addc_u32 s65, s63, 0
	s_cmpk_eq_i32 s72, 0x54
	s_cselect_b32 s69, s7, s65
	s_cselect_b32 s68, s6, s64
	s_cselect_b32 s67, s61, s71
	s_cselect_b32 s66, s60, s70
	v_lshl_add_u64 v[216:217], s[62:63], 0, v[136:137]
	s_add_i32 m0, s33, 0xc000
	ds_read_b128 v[184:187], v153
	ds_read_b128 v[188:191], v153 offset:1024
	ds_read_b128 v[192:195], v153 offset:2048
	ds_read_b128 v[196:199], v153 offset:3072
	ds_read_b128 v[200:203], v153 offset:4096
	ds_read_b128 v[204:207], v153 offset:5120
	ds_read_b128 v[208:211], v153 offset:6144
	ds_read_b128 v[212:215], v153 offset:7168
	global_load_lds_dwordx4 v[216:217], off
	v_lshl_add_u64 v[216:217], s[62:63], 0, v[138:139]
	s_add_i32 m0, s33, 0xe000
	s_nop 0
	global_load_lds_dwordx4 v[216:217], off
	s_waitcnt vmcnt(8)
	s_waitcnt lgkmcnt(0)
	s_barrier
	s_setprio 1
	s_waitcnt lgkmcnt(0)
	v_mfma_f32_16x16x32_bf16 v[124:127], v[144:147], v[184:187], v[124:127]
	v_mfma_f32_16x16x32_bf16 v[120:123], v[160:163], v[184:187], v[120:123]
	v_mfma_f32_16x16x32_bf16 v[108:111], v[144:147], v[192:195], v[108:111]
	v_mfma_f32_16x16x32_bf16 v[104:107], v[160:163], v[192:195], v[104:107]
	v_mfma_f32_16x16x32_bf16 v[92:95], v[144:147], v[200:203], v[92:95]
	v_mfma_f32_16x16x32_bf16 v[88:91], v[160:163], v[200:203], v[88:91]
	v_mfma_f32_16x16x32_bf16 v[76:79], v[144:147], v[208:211], v[76:79]
	v_mfma_f32_16x16x32_bf16 v[72:75], v[160:163], v[208:211], v[72:75]
	v_mfma_f32_16x16x32_bf16 v[124:127], v[156:159], v[188:191], v[124:127]
	v_mfma_f32_16x16x32_bf16 v[120:123], v[164:167], v[188:191], v[120:123]
	v_mfma_f32_16x16x32_bf16 v[108:111], v[156:159], v[196:199], v[108:111]
	v_mfma_f32_16x16x32_bf16 v[104:107], v[164:167], v[196:199], v[104:107]
	v_mfma_f32_16x16x32_bf16 v[92:95], v[156:159], v[204:207], v[92:95]
	v_mfma_f32_16x16x32_bf16 v[88:91], v[164:167], v[204:207], v[88:91]
	v_mfma_f32_16x16x32_bf16 v[76:79], v[156:159], v[212:215], v[76:79]
	v_mfma_f32_16x16x32_bf16 v[72:75], v[164:167], v[212:215], v[72:75]
	s_setprio 0
	s_setprio 1
	v_mfma_f32_16x16x32_bf16 v[116:119], v[168:171], v[184:187], v[116:119]
	v_mfma_f32_16x16x32_bf16 v[112:115], v[176:179], v[184:187], v[112:115]
	v_mfma_f32_16x16x32_bf16 v[100:103], v[168:171], v[192:195], v[100:103]
	v_mfma_f32_16x16x32_bf16 v[96:99], v[176:179], v[192:195], v[96:99]
	v_mfma_f32_16x16x32_bf16 v[84:87], v[168:171], v[200:203], v[84:87]
	v_mfma_f32_16x16x32_bf16 v[80:83], v[176:179], v[200:203], v[80:83]
	v_mfma_f32_16x16x32_bf16 v[68:71], v[168:171], v[208:211], v[68:71]
	v_mfma_f32_16x16x32_bf16 v[64:67], v[176:179], v[208:211], v[64:67]
	v_mfma_f32_16x16x32_bf16 v[116:119], v[172:175], v[188:191], v[116:119]
	v_mfma_f32_16x16x32_bf16 v[112:115], v[180:183], v[188:191], v[112:115]
	v_mfma_f32_16x16x32_bf16 v[100:103], v[172:175], v[196:199], v[100:103]
	v_mfma_f32_16x16x32_bf16 v[96:99], v[180:183], v[196:199], v[96:99]
	v_mfma_f32_16x16x32_bf16 v[84:87], v[172:175], v[204:207], v[84:87]
	v_mfma_f32_16x16x32_bf16 v[80:83], v[180:183], v[204:207], v[80:83]
	v_mfma_f32_16x16x32_bf16 v[68:71], v[172:175], v[212:215], v[68:71]
	v_mfma_f32_16x16x32_bf16 v[64:67], v[180:183], v[212:215], v[64:67]
	s_setprio 0
	s_barrier
	s_add_i32 s62, s48, s11
	v_lshl_add_u64 v[216:217], s[66:67], 0, v[130:131]
	s_mov_b32 m0, s62
	ds_read_b128 v[184:187], v153 offset:16384
	ds_read_b128 v[188:191], v153 offset:17408
	ds_read_b128 v[192:195], v153 offset:18432
	ds_read_b128 v[196:199], v153 offset:19456
	ds_read_b128 v[200:203], v153 offset:20480
	ds_read_b128 v[204:207], v153 offset:21504
	ds_read_b128 v[208:211], v153 offset:22528
	ds_read_b128 v[212:215], v153 offset:23552
	global_load_lds_dwordx4 v[216:217], off
	s_add_i32 m0, s62, 0x2000
	s_add_u32 s62, s66, 0x160000
	v_lshl_add_u64 v[218:219], s[66:67], 0, v[134:135]
	s_addc_u32 s63, s67, 0
	s_add_i32 s73, s49, s11
	global_load_lds_dwordx4 v[218:219], off
	v_lshl_add_u64 v[220:221], s[62:63], 0, v[130:131]
	s_mov_b32 m0, s73
	v_lshl_add_u64 v[222:223], s[68:69], 0, v[132:133]
	global_load_lds_dwordx4 v[220:221], off
	v_lshl_add_u64 v[220:221], s[62:63], 0, v[134:135]
	s_add_i32 m0, s73, 0x2000
	s_nop 0
	global_load_lds_dwordx4 v[220:221], off
	v_lshl_add_u64 v[220:221], s[68:69], 0, v[128:129]
	s_mov_b32 m0, s33
	s_nop 0
	global_load_lds_dwordx4 v[220:221], off
	s_mov_b32 m0, s35
	s_nop 0
	global_load_lds_dwordx4 v[222:223], off
	s_waitcnt vmcnt(8)
	s_waitcnt lgkmcnt(0)
	s_barrier
; #define PG8_STAGE(bufoff, gbase, voff) do { _Pragma("unroll") for (int _i = 0; _i < 2; ++_i) \
;         __builtin_amdgcn_global_load_lds((const unsigned*)((const char*)(gbase) + (voff)[_i]), (PG8_LAS unsigned*)(lds + (bufoff) + ldsw + _i * 8192), 16, 0, 0); } while (0)
; #define PG8_LDA(dst, b, h) do { _Pragma("unroll") for (int m = 0; m < 4; ++m) _Pragma("unroll") for (int k = 0; k < 2; ++k) dst[m][k] = *(const PG8_LAS bf16x8*)(lds + PG8_SA(b, h) + aoff + m * 2048 + k * 1024); } while (0)
; #define PG8_LDB(dst, b, h) do { _Pragma("unroll") for (int n = 0; n < 2; ++n) _Pragma("unroll") for (int k = 0; k < 2; ++k) dst[n][k] = *(const PG8_LAS bf16x8*)(lds + PG8_SB(b, h) + boff + n * 2048 + k * 1024); } while (0)
; #define PG8_MMA(ai, bj, At, Bt) do { __builtin_amdgcn_s_setprio(1); _Pragma("unroll") for (int m = 0; m < 4; ++m) _Pragma("unroll") for (int n = 0; n < 2; ++n) _Pragma("unroll") for (int k = 0; k < 2; ++k) \
;         acc[ai][bj][m][n] = __builtin_amdgcn_mfma_f32_16x16x32_bf16(Bt[n][k], At[m][k], acc[ai][bj][m][n], 0, 0, 0); __builtin_amdgcn_s_setprio(0); } while (0)
; #define PG8_WAIT_V(n) asm volatile("s_waitcnt vmcnt(" #n ")" ::: "memory")
; #define PG8_WAIT_L(n) asm volatile("s_waitcnt lgkmcnt(" #n ")" ::: "memory")
; #define PG8_BAR __builtin_amdgcn_s_barrier()
; #define PG8_SCHED __builtin_amdgcn_sched_barrier(0)
; template <class Epi, class Sched, bool ALIGN_EPI = false, bool SP2 = false>
; __device__ __forceinline__ void gemm_phase(PG8_LAS unsigned char* lds, const Gemm g, const Sched& S, const Epi& E, const int wave_in) {
;     ...
;             PG8_WAIT_V(8); PG8_WAIT_L(0); PG8_BAR; PG8_MMA(1, 0, At, B0); PG8_MMA(1, 1, At, B1); PG8_BAR; PG8_SCHED;
;             PG8_LDB(B0, 1, 0); PG8_LDB(B1, 1, 1); PG8_SCHED; PG8_LDA(At, 1, 0); PG8_STAGE(PG8_SA(0, 1), a2 + hstepA, voffA);
;             PG8_WAIT_V(8); PG8_WAIT_L(0); PG8_BAR; PG8_MMA(0, 0, At, B0); PG8_MMA(0, 1, At, B1); PG8_BAR; PG8_SCHED;
	s_setprio 1
	s_waitcnt lgkmcnt(0)
	v_mfma_f32_16x16x32_bf16 v[60:63], v[144:147], v[184:187], v[60:63]
	v_mfma_f32_16x16x32_bf16 v[56:59], v[160:163], v[184:187], v[56:59]
	v_mfma_f32_16x16x32_bf16 v[44:47], v[144:147], v[192:195], v[44:47]
	v_mfma_f32_16x16x32_bf16 v[40:43], v[160:163], v[192:195], v[40:43]
	v_mfma_f32_16x16x32_bf16 v[28:31], v[144:147], v[200:203], v[28:31]
	v_mfma_f32_16x16x32_bf16 v[24:27], v[160:163], v[200:203], v[24:27]
	v_mfma_f32_16x16x32_bf16 v[12:15], v[144:147], v[208:211], v[12:15]
	v_mfma_f32_16x16x32_bf16 v[8:11], v[160:163], v[208:211], v[8:11]
	v_mfma_f32_16x16x32_bf16 v[60:63], v[156:159], v[188:191], v[60:63]
	v_mfma_f32_16x16x32_bf16 v[56:59], v[164:167], v[188:191], v[56:59]
	v_mfma_f32_16x16x32_bf16 v[44:47], v[156:159], v[196:199], v[44:47]
	v_mfma_f32_16x16x32_bf16 v[40:43], v[164:167], v[196:199], v[40:43]
	v_mfma_f32_16x16x32_bf16 v[28:31], v[156:159], v[204:207], v[28:31]
	v_mfma_f32_16x16x32_bf16 v[24:27], v[164:167], v[204:207], v[24:27]
	v_mfma_f32_16x16x32_bf16 v[12:15], v[156:159], v[212:215], v[12:15]
	v_mfma_f32_16x16x32_bf16 v[8:11], v[164:167], v[212:215], v[8:11]
	s_setprio 0
	s_setprio 1
	v_mfma_f32_16x16x32_bf16 v[52:55], v[168:171], v[184:187], v[52:55]
	v_mfma_f32_16x16x32_bf16 v[48:51], v[176:179], v[184:187], v[48:51]
	v_mfma_f32_16x16x32_bf16 v[36:39], v[168:171], v[192:195], v[36:39]
	v_mfma_f32_16x16x32_bf16 v[32:35], v[176:179], v[192:195], v[32:35]
	v_mfma_f32_16x16x32_bf16 v[20:23], v[168:171], v[200:203], v[20:23]
	v_mfma_f32_16x16x32_bf16 v[16:19], v[176:179], v[200:203], v[16:19]
	v_mfma_f32_16x16x32_bf16 v[4:7], v[168:171], v[208:211], v[4:7]
	v_mfma_f32_16x16x32_bf16 v[0:3], v[176:179], v[208:211], v[0:3]
	v_mfma_f32_16x16x32_bf16 v[52:55], v[172:175], v[188:191], v[52:55]
	v_mfma_f32_16x16x32_bf16 v[48:51], v[180:183], v[188:191], v[48:51]
	v_mfma_f32_16x16x32_bf16 v[36:39], v[172:175], v[196:199], v[36:39]
	v_mfma_f32_16x16x32_bf16 v[32:35], v[180:183], v[196:199], v[32:35]
	v_mfma_f32_16x16x32_bf16 v[20:23], v[172:175], v[204:207], v[20:23]
	v_mfma_f32_16x16x32_bf16 v[16:19], v[180:183], v[204:207], v[16:19]
	v_mfma_f32_16x16x32_bf16 v[4:7], v[172:175], v[212:215], v[4:7]
	v_mfma_f32_16x16x32_bf16 v[0:3], v[180:183], v[212:215], v[0:3]
	s_setprio 0
	s_barrier
	s_add_i32 s73, 0, 0x18000
	v_add_u32_e32 v155, s73, v149
	s_add_i32 s78, 0, 0x1c000
	ds_read_b128 v[144:147], v155
	ds_read_b128 v[156:159], v155 offset:1024
	ds_read_b128 v[160:163], v155 offset:2048
	ds_read_b128 v[164:167], v155 offset:3072
	v_add_u32_e32 v155, s78, v149
	ds_read_b128 v[168:171], v155
	ds_read_b128 v[172:175], v155 offset:1024
	ds_read_b128 v[176:179], v155 offset:2048
	ds_read_b128 v[180:183], v155 offset:3072
	s_add_u32 s62, s68, 0x160000
	s_addc_u32 s63, s69, 0
	s_mov_b32 m0, s38
	v_lshl_add_u64 v[224:225], s[62:63], 0, v[128:129]
	ds_read_b128 v[184:187], v153 offset:32768
	ds_read_b128 v[188:191], v153 offset:33792
	ds_read_b128 v[192:195], v153 offset:34816
	ds_read_b128 v[196:199], v153 offset:35840
	ds_read_b128 v[200:203], v153 offset:36864
	ds_read_b128 v[204:207], v153 offset:37888
	ds_read_b128 v[208:211], v153 offset:38912
	ds_read_b128 v[212:215], v153 offset:39936
	global_load_lds_dwordx4 v[224:225], off
	v_lshl_add_u64 v[224:225], s[62:63], 0, v[132:133]
	s_mov_b32 m0, s39
	s_nop 0
	global_load_lds_dwordx4 v[224:225], off
	s_waitcnt vmcnt(8)
	s_waitcnt lgkmcnt(0)
	s_barrier
	s_setprio 1
	s_waitcnt lgkmcnt(0)
	v_mfma_f32_16x16x32_bf16 v[124:127], v[144:147], v[184:187], v[124:127]
	v_mfma_f32_16x16x32_bf16 v[120:123], v[160:163], v[184:187], v[120:123]
	v_mfma_f32_16x16x32_bf16 v[108:111], v[144:147], v[192:195], v[108:111]
	v_mfma_f32_16x16x32_bf16 v[104:107], v[160:163], v[192:195], v[104:107]
	v_mfma_f32_16x16x32_bf16 v[92:95], v[144:147], v[200:203], v[92:95]
	v_mfma_f32_16x16x32_bf16 v[88:91], v[160:163], v[200:203], v[88:91]
	v_mfma_f32_16x16x32_bf16 v[76:79], v[144:147], v[208:211], v[76:79]
	v_mfma_f32_16x16x32_bf16 v[72:75], v[160:163], v[208:211], v[72:75]
	v_mfma_f32_16x16x32_bf16 v[124:127], v[156:159], v[188:191], v[124:127]
	v_mfma_f32_16x16x32_bf16 v[120:123], v[164:167], v[188:191], v[120:123]
	v_mfma_f32_16x16x32_bf16 v[108:111], v[156:159], v[196:199], v[108:111]
	v_mfma_f32_16x16x32_bf16 v[104:107], v[164:167], v[196:199], v[104:107]
	v_mfma_f32_16x16x32_bf16 v[92:95], v[156:159], v[204:207], v[92:95]
	v_mfma_f32_16x16x32_bf16 v[88:91], v[164:167], v[204:207], v[88:91]
	v_mfma_f32_16x16x32_bf16 v[76:79], v[156:159], v[212:215], v[76:79]
	v_mfma_f32_16x16x32_bf16 v[72:75], v[164:167], v[212:215], v[72:75]
	s_setprio 0
	s_setprio 1
	v_mfma_f32_16x16x32_bf16 v[116:119], v[168:171], v[184:187], v[116:119]
	v_mfma_f32_16x16x32_bf16 v[112:115], v[176:179], v[184:187], v[112:115]
	v_mfma_f32_16x16x32_bf16 v[100:103], v[168:171], v[192:195], v[100:103]
	v_mfma_f32_16x16x32_bf16 v[96:99], v[176:179], v[192:195], v[96:99]
	v_mfma_f32_16x16x32_bf16 v[84:87], v[168:171], v[200:203], v[84:87]
	v_mfma_f32_16x16x32_bf16 v[80:83], v[176:179], v[200:203], v[80:83]
	v_mfma_f32_16x16x32_bf16 v[68:71], v[168:171], v[208:211], v[68:71]
	v_mfma_f32_16x16x32_bf16 v[64:67], v[176:179], v[208:211], v[64:67]
	v_mfma_f32_16x16x32_bf16 v[116:119], v[172:175], v[188:191], v[116:119]
	v_mfma_f32_16x16x32_bf16 v[112:115], v[180:183], v[188:191], v[112:115]
	v_mfma_f32_16x16x32_bf16 v[100:103], v[172:175], v[196:199], v[100:103]
	v_mfma_f32_16x16x32_bf16 v[96:99], v[180:183], v[196:199], v[96:99]
	v_mfma_f32_16x16x32_bf16 v[84:87], v[172:175], v[204:207], v[84:87]
	v_mfma_f32_16x16x32_bf16 v[80:83], v[180:183], v[204:207], v[80:83]
	v_mfma_f32_16x16x32_bf16 v[68:71], v[172:175], v[212:215], v[68:71]
	v_mfma_f32_16x16x32_bf16 v[64:67], v[180:183], v[212:215], v[64:67]
	s_setprio 0
	s_barrier
; #define PG8_STAGE(bufoff, gbase, voff) do { _Pragma("unroll") for (int _i = 0; _i < 2; ++_i) \
;         __builtin_amdgcn_global_load_lds((const unsigned*)((const char*)(gbase) + (voff)[_i]), (PG8_LAS unsigned*)(lds + (bufoff) + ldsw + _i * 8192), 16, 0, 0); } while (0)
; #define PG8_LDA(dst, b, h) do { _Pragma("unroll") for (int m = 0; m < 4; ++m) _Pragma("unroll") for (int k = 0; k < 2; ++k) dst[m][k] = *(const PG8_LAS bf16x8*)(lds + PG8_SA(b, h) + aoff + m * 2048 + k * 1024); } while (0)
; #define PG8_MMA(ai, bj, At, Bt) do { __builtin_amdgcn_s_setprio(1); _Pragma("unroll") for (int m = 0; m < 4; ++m) _Pragma("unroll") for (int n = 0; n < 2; ++n) _Pragma("unroll") for (int k = 0; k < 2; ++k) \
;         acc[ai][bj][m][n] = __builtin_amdgcn_mfma_f32_16x16x32_bf16(Bt[n][k], At[m][k], acc[ai][bj][m][n], 0, 0, 0); __builtin_amdgcn_s_setprio(0); } while (0)
; #define PG8_WAIT_V(n) asm volatile("s_waitcnt vmcnt(" #n ")" ::: "memory")
; #define PG8_WAIT_L(n) asm volatile("s_waitcnt lgkmcnt(" #n ")" ::: "memory")
; #define PG8_BAR __builtin_amdgcn_s_barrier()
; #define PG8_SCHED __builtin_amdgcn_sched_barrier(0)
; template <class Epi, class Sched, bool ALIGN_EPI = false, bool SP2 = false>
; __device__ __forceinline__ void gemm_phase(PG8_LAS unsigned char* lds, const Gemm g, const Sched& S, const Epi& E, const int wave_in) {
;     ...
;         for (int t = 0; t < nt; t += 2) {
;             const bool last = (t == nt - 2);
;             const char* a1 = cA + (size_t)(t + 1) * kstep;
;             const char* a2 = last ? nA : cA + (size_t)(t + 2) * kstep; const char* b2 = last ? nB : cB + (size_t)(t + 2) * kstep;
;             const char* a3 = a2 + kstep; const char* b3 = b2 + kstep;
;     ...
;             PG8_LDA(At, 1, 1); PG8_STAGE(PG8_SB(1, 0), b3, voffB); PG8_STAGE(PG8_SB(1, 1), b3 + hstep, voffB); PG8_STAGE(PG8_SA(1, 0), a3, voffA);
;             PG8_WAIT_V(8); PG8_WAIT_L(0); PG8_BAR; PG8_MMA(1, 0, At, B0); PG8_MMA(1, 1, At, B1); PG8_BAR; PG8_SCHED;
	s_add_i32 s62, s73, s11
	v_lshl_add_u64 v[216:217], v[216:217], 0, s[56:57]
	s_mov_b32 m0, s62
	ds_read_b128 v[184:187], v153 offset:49152
	ds_read_b128 v[188:191], v153 offset:50176
	ds_read_b128 v[192:195], v153 offset:51200
	ds_read_b128 v[196:199], v153 offset:52224
	ds_read_b128 v[200:203], v153 offset:53248
	ds_read_b128 v[204:207], v153 offset:54272
	ds_read_b128 v[208:211], v153 offset:55296
	ds_read_b128 v[212:215], v153 offset:56320
	global_load_lds_dwordx4 v[216:217], off
	s_add_i32 m0, s62, 0x2000
	s_add_u32 s62, s66, 0x160080
	v_lshl_add_u64 v[216:217], v[218:219], 0, s[56:57]
	s_addc_u32 s63, s67, 0
	s_add_i32 s66, s78, s11
	global_load_lds_dwordx4 v[216:217], off
	v_lshl_add_u64 v[216:217], s[62:63], 0, v[130:131]
	s_mov_b32 m0, s66
	s_nop 0
	global_load_lds_dwordx4 v[216:217], off
	v_lshl_add_u64 v[216:217], s[62:63], 0, v[134:135]
	s_add_i32 m0, s66, 0x2000
	s_nop 0
	global_load_lds_dwordx4 v[216:217], off
	v_lshl_add_u64 v[216:217], v[220:221], 0, s[56:57]
	s_mov_b32 m0, s41
	s_nop 0
	global_load_lds_dwordx4 v[216:217], off
	v_lshl_add_u64 v[216:217], v[222:223], 0, s[56:57]
	s_mov_b32 m0, s42
	s_nop 0
	global_load_lds_dwordx4 v[216:217], off
	s_waitcnt vmcnt(8)
	s_waitcnt lgkmcnt(0)
	s_barrier
	s_setprio 1
	s_waitcnt lgkmcnt(0)
	v_mfma_f32_16x16x32_bf16 v[60:63], v[144:147], v[184:187], v[60:63]
	v_mfma_f32_16x16x32_bf16 v[56:59], v[160:163], v[184:187], v[56:59]
	v_mfma_f32_16x16x32_bf16 v[44:47], v[144:147], v[192:195], v[44:47]
	v_mfma_f32_16x16x32_bf16 v[40:43], v[160:163], v[192:195], v[40:43]
	v_mfma_f32_16x16x32_bf16 v[28:31], v[144:147], v[200:203], v[28:31]
	v_mfma_f32_16x16x32_bf16 v[24:27], v[160:163], v[200:203], v[24:27]
	v_mfma_f32_16x16x32_bf16 v[12:15], v[144:147], v[208:211], v[12:15]
	v_mfma_f32_16x16x32_bf16 v[8:11], v[160:163], v[208:211], v[8:11]
	v_mfma_f32_16x16x32_bf16 v[60:63], v[156:159], v[188:191], v[60:63]
	v_mfma_f32_16x16x32_bf16 v[56:59], v[164:167], v[188:191], v[56:59]
	v_mfma_f32_16x16x32_bf16 v[44:47], v[156:159], v[196:199], v[44:47]
	v_mfma_f32_16x16x32_bf16 v[40:43], v[164:167], v[196:199], v[40:43]
	v_mfma_f32_16x16x32_bf16 v[28:31], v[156:159], v[204:207], v[28:31]
	v_mfma_f32_16x16x32_bf16 v[24:27], v[164:167], v[204:207], v[24:27]
	v_mfma_f32_16x16x32_bf16 v[12:15], v[156:159], v[212:215], v[12:15]
	v_mfma_f32_16x16x32_bf16 v[8:11], v[164:167], v[212:215], v[8:11]
	s_setprio 0
	s_setprio 1
	v_mfma_f32_16x16x32_bf16 v[52:55], v[168:171], v[184:187], v[52:55]
	v_mfma_f32_16x16x32_bf16 v[48:51], v[176:179], v[184:187], v[48:51]
	v_mfma_f32_16x16x32_bf16 v[36:39], v[168:171], v[192:195], v[36:39]
	v_mfma_f32_16x16x32_bf16 v[32:35], v[176:179], v[192:195], v[32:35]
	v_mfma_f32_16x16x32_bf16 v[20:23], v[168:171], v[200:203], v[20:23]
	v_mfma_f32_16x16x32_bf16 v[16:19], v[176:179], v[200:203], v[16:19]
	v_mfma_f32_16x16x32_bf16 v[4:7], v[168:171], v[208:211], v[4:7]
	v_mfma_f32_16x16x32_bf16 v[0:3], v[176:179], v[208:211], v[0:3]
	v_mfma_f32_16x16x32_bf16 v[52:55], v[172:175], v[188:191], v[52:55]
	v_mfma_f32_16x16x32_bf16 v[48:51], v[180:183], v[188:191], v[48:51]
	v_mfma_f32_16x16x32_bf16 v[36:39], v[172:175], v[196:199], v[36:39]
	v_mfma_f32_16x16x32_bf16 v[32:35], v[180:183], v[196:199], v[32:35]
	v_mfma_f32_16x16x32_bf16 v[20:23], v[172:175], v[204:207], v[20:23]
	v_mfma_f32_16x16x32_bf16 v[16:19], v[180:183], v[204:207], v[16:19]
	v_mfma_f32_16x16x32_bf16 v[4:7], v[172:175], v[212:215], v[4:7]
	v_mfma_f32_16x16x32_bf16 v[0:3], v[180:183], v[212:215], v[0:3]
	s_setprio 0
	s_add_i32 s72, s72, 2
	s_add_u32 s70, s70, 0x100
	s_addc_u32 s71, s71, 0
	s_cmpk_gt_u32 s72, 0x55
	s_mov_b64 s[62:63], s[64:65]
	s_barrier
	s_cbranch_scc0 .LBB0_583
	s_and_b64 vcc, exec, s[58:59]
	s_cbranch_vccz .LBB0_586
	s_barrier

; #define PG8_STAGE(bufoff, gbase, voff) do { _Pragma("unroll") for (int _i = 0; _i < 2; ++_i) \
;         __builtin_amdgcn_global_load_lds((const unsigned*)((const char*)(gbase) + (voff)[_i]), (PG8_LAS unsigned*)(lds + (bufoff) + ldsw + _i * 8192), 16, 0, 0); } while (0)
; #define PG8_LDA(dst, b, h) do { _Pragma("unroll") for (int m = 0; m < 4; ++m) _Pragma("unroll") for (int k = 0; k < 2; ++k) dst[m][k] = *(const PG8_LAS bf16x8*)(lds + PG8_SA(b, h) + aoff + m * 2048 + k * 1024); } while (0)
; #define PG8_LDB(dst, b, h) do { _Pragma("unroll") for (int n = 0; n < 2; ++n) _Pragma("unroll") for (int k = 0; k < 2; ++k) dst[n][k] = *(const PG8_LAS bf16x8*)(lds + PG8_SB(b, h) + boff + n * 2048 + k * 1024); } while (0)
; #define PG8_MMA(ai, bj, At, Bt) do { __builtin_amdgcn_s_setprio(1); _Pragma("unroll") for (int m = 0; m < 4; ++m) _Pragma("unroll") for (int n = 0; n < 2; ++n) _Pragma("unroll") for (int k = 0; k < 2; ++k) \
;         acc[ai][bj][m][n] = __builtin_amdgcn_mfma_f32_16x16x32_bf16(Bt[n][k], At[m][k], acc[ai][bj][m][n], 0, 0, 0); __builtin_amdgcn_s_setprio(0); } while (0)
; #define PG8_WAIT_V(n) asm volatile("s_waitcnt vmcnt(" #n ")" ::: "memory")
; #define PG8_WAIT_L(n) asm volatile("s_waitcnt lgkmcnt(" #n ")" ::: "memory")
; #define PG8_BAR __builtin_amdgcn_s_barrier()
; template <class Epi, class Sched, bool ALIGN_EPI = false, bool SP2 = false>
; __device__ __forceinline__ void gemm_phase(PG8_LAS unsigned char* lds, const Gemm g, const Sched& S, const Epi& E, const int wave_in) {
;     ...
;         for (int t = 0; t < nt; t += 2) {
;             const bool last = (t == nt - 2);
;             const char* a1 = cA + (size_t)(t + 1) * kstep;
;             const char* a2 = last ? nA : cA + (size_t)(t + 2) * kstep; const char* b2 = last ? nB : cB + (size_t)(t + 2) * kstep;
;             const char* a3 = a2 + kstep; const char* b3 = b2 + kstep;
;             if (last && has_next) S.a_ready(nxt);
;             if constexpr (SP2) {
;             PG8_LDB(B0, 0, 0); PG8_LDB(B1, 0, 1); PG8_SCHED; PG8_LDA(At, 0, 0); PG8_STAGE(PG8_SA(1, 1), a1 + hstepA, voffA);
;             PG8_WAIT_V(8); PG8_WAIT_L(0); PG8_BAR; PG8_MMA(0, 0, At, B0); PG8_MMA(0, 1, At, B1); PG8_BAR; PG8_SCHED;
;             PG8_LDA(At, 0, 1); PG8_STAGE(PG8_SB(0, 0), b2, voffB); PG8_STAGE(PG8_SB(0, 1), b2 + hstep, voffB); PG8_STAGE(PG8_SA(0, 0), a2, voffA);
.LBB0_672:
	ds_read_b128 v[128:131], v169
	ds_read_b128 v[132:135], v169 offset:1024
	ds_read_b128 v[160:163], v169 offset:2048
	ds_read_b128 v[174:177], v169 offset:3072
	ds_read_b128 v[178:181], v170
	ds_read_b128 v[182:185], v170 offset:1024
	ds_read_b128 v[186:189], v170 offset:2048
	ds_read_b128 v[190:193], v170 offset:3072
	s_add_u32 s73, s18, 0xfff80080
	s_addc_u32 s78, s19, -1
	s_cmp_eq_u32 s71, 28
	s_cselect_b32 s85, s1, s78
	s_cselect_b32 s84, s7, s73
	s_cselect_b32 s79, s36, s57
	s_cselect_b32 s78, s37, s56
	v_lshl_add_u64 v[164:165], s[18:19], 0, v[152:153]
	s_add_i32 m0, s33, 0xc000
	ds_read_b128 v[194:197], v171
	ds_read_b128 v[198:201], v171 offset:1024
	ds_read_b128 v[202:205], v171 offset:2048
	ds_read_b128 v[206:209], v171 offset:3072
	ds_read_b128 v[210:213], v171 offset:4096
	ds_read_b128 v[214:217], v171 offset:5120
	ds_read_b128 v[218:221], v171 offset:6144
	ds_read_b128 v[222:225], v171 offset:7168
	global_load_lds_dwordx4 v[164:165], off
	v_lshl_add_u64 v[164:165], s[18:19], 0, v[154:155]
	s_add_i32 m0, s33, 0xe000
	s_nop 0
	global_load_lds_dwordx4 v[164:165], off
	s_waitcnt vmcnt(8)
	s_waitcnt lgkmcnt(0)
	s_barrier
	s_setprio 1
	s_waitcnt lgkmcnt(0)
	v_mfma_f32_16x16x32_bf16 v[124:127], v[128:131], v[194:197], v[124:127]
	v_mfma_f32_16x16x32_bf16 v[120:123], v[160:163], v[194:197], v[120:123]
	v_mfma_f32_16x16x32_bf16 v[108:111], v[128:131], v[202:205], v[108:111]
	v_mfma_f32_16x16x32_bf16 v[104:107], v[160:163], v[202:205], v[104:107]
	v_mfma_f32_16x16x32_bf16 v[92:95], v[128:131], v[210:213], v[92:95]
	v_mfma_f32_16x16x32_bf16 v[88:91], v[160:163], v[210:213], v[88:91]
	v_mfma_f32_16x16x32_bf16 v[76:79], v[128:131], v[218:221], v[76:79]
	v_mfma_f32_16x16x32_bf16 v[72:75], v[160:163], v[218:221], v[72:75]
	v_mfma_f32_16x16x32_bf16 v[124:127], v[132:135], v[198:201], v[124:127]
	v_mfma_f32_16x16x32_bf16 v[120:123], v[174:177], v[198:201], v[120:123]
	v_mfma_f32_16x16x32_bf16 v[108:111], v[132:135], v[206:209], v[108:111]
	v_mfma_f32_16x16x32_bf16 v[104:107], v[174:177], v[206:209], v[104:107]
	v_mfma_f32_16x16x32_bf16 v[92:95], v[132:135], v[214:217], v[92:95]
	v_mfma_f32_16x16x32_bf16 v[88:91], v[174:177], v[214:217], v[88:91]
	v_mfma_f32_16x16x32_bf16 v[76:79], v[132:135], v[222:225], v[76:79]
	v_mfma_f32_16x16x32_bf16 v[72:75], v[174:177], v[222:225], v[72:75]
	s_setprio 0
	s_setprio 1
	v_mfma_f32_16x16x32_bf16 v[116:119], v[178:181], v[194:197], v[116:119]
	v_mfma_f32_16x16x32_bf16 v[112:115], v[186:189], v[194:197], v[112:115]
	v_mfma_f32_16x16x32_bf16 v[100:103], v[178:181], v[202:205], v[100:103]
	v_mfma_f32_16x16x32_bf16 v[96:99], v[186:189], v[202:205], v[96:99]
	v_mfma_f32_16x16x32_bf16 v[84:87], v[178:181], v[210:213], v[84:87]
	v_mfma_f32_16x16x32_bf16 v[80:83], v[186:189], v[210:213], v[80:83]
	v_mfma_f32_16x16x32_bf16 v[68:71], v[178:181], v[218:221], v[68:71]
	v_mfma_f32_16x16x32_bf16 v[64:67], v[186:189], v[218:221], v[64:67]
	v_mfma_f32_16x16x32_bf16 v[116:119], v[182:185], v[198:201], v[116:119]
	v_mfma_f32_16x16x32_bf16 v[112:115], v[190:193], v[198:201], v[112:115]
	v_mfma_f32_16x16x32_bf16 v[100:103], v[182:185], v[206:209], v[100:103]
	v_mfma_f32_16x16x32_bf16 v[96:99], v[190:193], v[206:209], v[96:99]
	v_mfma_f32_16x16x32_bf16 v[84:87], v[182:185], v[214:217], v[84:87]
	v_mfma_f32_16x16x32_bf16 v[80:83], v[190:193], v[214:217], v[80:83]
	v_mfma_f32_16x16x32_bf16 v[68:71], v[182:185], v[222:225], v[68:71]
	v_mfma_f32_16x16x32_bf16 v[64:67], v[190:193], v[222:225], v[64:67]
	s_setprio 0
	s_barrier
	s_add_i32 s73, s92, s11
	v_lshl_add_u64 v[164:165], s[78:79], 0, v[138:139]
	s_mov_b32 m0, s73
	ds_read_b128 v[194:197], v171 offset:16384
	ds_read_b128 v[198:201], v171 offset:17408
	ds_read_b128 v[202:205], v171 offset:18432
	ds_read_b128 v[206:209], v171 offset:19456
	ds_read_b128 v[210:213], v171 offset:20480
	ds_read_b128 v[214:217], v171 offset:21504
	ds_read_b128 v[218:221], v171 offset:22528
	ds_read_b128 v[222:225], v171 offset:23552
	global_load_lds_dwordx4 v[164:165], off
	s_add_i32 m0, s73, 0x2000
	s_add_u32 vcc_lo, s78, 0x80000
	v_lshl_add_u64 v[226:227], s[78:79], 0, v[142:143]
	s_addc_u32 vcc_hi, s79, 0
	s_add_i32 s73, s93, s11
	global_load_lds_dwordx4 v[226:227], off
	v_lshl_add_u64 v[228:229], vcc, 0, v[138:139]
	s_mov_b32 m0, s73
	v_lshl_add_u64 v[230:231], s[84:85], 0, v[140:141]
	global_load_lds_dwordx4 v[228:229], off
	v_lshl_add_u64 v[228:229], vcc, 0, v[142:143]
	s_add_i32 m0, s73, 0x2000
	s_nop 0
	global_load_lds_dwordx4 v[228:229], off
	v_lshl_add_u64 v[228:229], s[84:85], 0, v[136:137]
	s_mov_b32 m0, s33
	s_nop 0
	global_load_lds_dwordx4 v[228:229], off
	s_mov_b32 m0, s35
	s_nop 0
	global_load_lds_dwordx4 v[230:231], off
	s_waitcnt vmcnt(8)
	s_waitcnt lgkmcnt(0)
	s_barrier
; #define PG8_STAGE(bufoff, gbase, voff) do { _Pragma("unroll") for (int _i = 0; _i < 2; ++_i) \
;         __builtin_amdgcn_global_load_lds((const unsigned*)((const char*)(gbase) + (voff)[_i]), (PG8_LAS unsigned*)(lds + (bufoff) + ldsw + _i * 8192), 16, 0, 0); } while (0)
; #define PG8_LDA(dst, b, h) do { _Pragma("unroll") for (int m = 0; m < 4; ++m) _Pragma("unroll") for (int k = 0; k < 2; ++k) dst[m][k] = *(const PG8_LAS bf16x8*)(lds + PG8_SA(b, h) + aoff + m * 2048 + k * 1024); } while (0)
; #define PG8_LDB(dst, b, h) do { _Pragma("unroll") for (int n = 0; n < 2; ++n) _Pragma("unroll") for (int k = 0; k < 2; ++k) dst[n][k] = *(const PG8_LAS bf16x8*)(lds + PG8_SB(b, h) + boff + n * 2048 + k * 1024); } while (0)
; #define PG8_MMA(ai, bj, At, Bt) do { __builtin_amdgcn_s_setprio(1); _Pragma("unroll") for (int m = 0; m < 4; ++m) _Pragma("unroll") for (int n = 0; n < 2; ++n) _Pragma("unroll") for (int k = 0; k < 2; ++k) \
;         acc[ai][bj][m][n] = __builtin_amdgcn_mfma_f32_16x16x32_bf16(Bt[n][k], At[m][k], acc[ai][bj][m][n], 0, 0, 0); __builtin_amdgcn_s_setprio(0); } while (0)
; #define PG8_WAIT_V(n) asm volatile("s_waitcnt vmcnt(" #n ")" ::: "memory")
; #define PG8_WAIT_L(n) asm volatile("s_waitcnt lgkmcnt(" #n ")" ::: "memory")
; #define PG8_BAR __builtin_amdgcn_s_barrier()
; #define PG8_SCHED __builtin_amdgcn_sched_barrier(0)
; template <class Epi, class Sched, bool ALIGN_EPI = false, bool SP2 = false>
; __device__ __forceinline__ void gemm_phase(PG8_LAS unsigned char* lds, const Gemm g, const Sched& S, const Epi& E, const int wave_in) {
;     ...
;             PG8_WAIT_V(8); PG8_WAIT_L(0); PG8_BAR; PG8_MMA(1, 0, At, B0); PG8_MMA(1, 1, At, B1); PG8_BAR; PG8_SCHED;
;             PG8_LDB(B0, 1, 0); PG8_LDB(B1, 1, 1); PG8_SCHED; PG8_LDA(At, 1, 0); PG8_STAGE(PG8_SA(0, 1), a2 + hstepA, voffA);
;             PG8_WAIT_V(8); PG8_WAIT_L(0); PG8_BAR; PG8_MMA(0, 0, At, B0); PG8_MMA(0, 1, At, B1); PG8_BAR; PG8_SCHED;
	s_setprio 1
	s_waitcnt lgkmcnt(0)
	v_mfma_f32_16x16x32_bf16 v[60:63], v[128:131], v[194:197], v[60:63]
	v_mfma_f32_16x16x32_bf16 v[56:59], v[160:163], v[194:197], v[56:59]
	v_mfma_f32_16x16x32_bf16 v[44:47], v[128:131], v[202:205], v[44:47]
	v_mfma_f32_16x16x32_bf16 v[40:43], v[160:163], v[202:205], v[40:43]
	v_mfma_f32_16x16x32_bf16 v[28:31], v[128:131], v[210:213], v[28:31]
	v_mfma_f32_16x16x32_bf16 v[24:27], v[160:163], v[210:213], v[24:27]
	v_mfma_f32_16x16x32_bf16 v[12:15], v[128:131], v[218:221], v[12:15]
	v_mfma_f32_16x16x32_bf16 v[8:11], v[160:163], v[218:221], v[8:11]
	v_mfma_f32_16x16x32_bf16 v[60:63], v[132:135], v[198:201], v[60:63]
	v_mfma_f32_16x16x32_bf16 v[56:59], v[174:177], v[198:201], v[56:59]
	v_mfma_f32_16x16x32_bf16 v[44:47], v[132:135], v[206:209], v[44:47]
	v_mfma_f32_16x16x32_bf16 v[40:43], v[174:177], v[206:209], v[40:43]
	v_mfma_f32_16x16x32_bf16 v[28:31], v[132:135], v[214:217], v[28:31]
	v_mfma_f32_16x16x32_bf16 v[24:27], v[174:177], v[214:217], v[24:27]
	v_mfma_f32_16x16x32_bf16 v[12:15], v[132:135], v[222:225], v[12:15]
	v_mfma_f32_16x16x32_bf16 v[8:11], v[174:177], v[222:225], v[8:11]
	s_setprio 0
	s_setprio 1
	v_mfma_f32_16x16x32_bf16 v[52:55], v[178:181], v[194:197], v[52:55]
	v_mfma_f32_16x16x32_bf16 v[48:51], v[186:189], v[194:197], v[48:51]
	v_mfma_f32_16x16x32_bf16 v[36:39], v[178:181], v[202:205], v[36:39]
	v_mfma_f32_16x16x32_bf16 v[32:35], v[186:189], v[202:205], v[32:35]
	v_mfma_f32_16x16x32_bf16 v[20:23], v[178:181], v[210:213], v[20:23]
	v_mfma_f32_16x16x32_bf16 v[16:19], v[186:189], v[210:213], v[16:19]
	v_mfma_f32_16x16x32_bf16 v[4:7], v[178:181], v[218:221], v[4:7]
	v_mfma_f32_16x16x32_bf16 v[0:3], v[186:189], v[218:221], v[0:3]
	v_mfma_f32_16x16x32_bf16 v[52:55], v[182:185], v[198:201], v[52:55]
	v_mfma_f32_16x16x32_bf16 v[48:51], v[190:193], v[198:201], v[48:51]
	v_mfma_f32_16x16x32_bf16 v[36:39], v[182:185], v[206:209], v[36:39]
	v_mfma_f32_16x16x32_bf16 v[32:35], v[190:193], v[206:209], v[32:35]
	v_mfma_f32_16x16x32_bf16 v[20:23], v[182:185], v[214:217], v[20:23]
	v_mfma_f32_16x16x32_bf16 v[16:19], v[190:193], v[214:217], v[16:19]
	v_mfma_f32_16x16x32_bf16 v[4:7], v[182:185], v[222:225], v[4:7]
	v_mfma_f32_16x16x32_bf16 v[0:3], v[190:193], v[222:225], v[0:3]
	s_setprio 0
	s_barrier
	s_add_i32 s73, 0, 0x18000
	s_add_i32 vcc_lo, 0, 0x1c000
	v_add_u32_e32 v174, s73, v167
	v_add_u32_e32 v190, vcc_lo, v167
	ds_read_b128 v[128:131], v174
	ds_read_b128 v[132:135], v174 offset:1024
	ds_read_b128 v[160:163], v174 offset:2048
	ds_read_b128 v[174:177], v174 offset:3072
	ds_read_b128 v[178:181], v190
	ds_read_b128 v[182:185], v190 offset:1024
	ds_read_b128 v[186:189], v190 offset:2048
	ds_read_b128 v[190:193], v190 offset:3072
	s_add_u32 s84, s84, 0x80000
	s_addc_u32 s85, s85, 0
	s_mov_b32 m0, s38
	v_lshl_add_u64 v[232:233], s[84:85], 0, v[136:137]
	ds_read_b128 v[194:197], v171 offset:32768
	ds_read_b128 v[198:201], v171 offset:33792
	ds_read_b128 v[202:205], v171 offset:34816
	ds_read_b128 v[206:209], v171 offset:35840
	ds_read_b128 v[210:213], v171 offset:36864
	ds_read_b128 v[214:217], v171 offset:37888
	ds_read_b128 v[218:221], v171 offset:38912
	ds_read_b128 v[222:225], v171 offset:39936
	global_load_lds_dwordx4 v[232:233], off
	v_lshl_add_u64 v[232:233], s[84:85], 0, v[140:141]
	s_mov_b32 m0, s39
	s_nop 0
	global_load_lds_dwordx4 v[232:233], off
	s_waitcnt vmcnt(8)
	s_waitcnt lgkmcnt(0)
	s_barrier
	s_setprio 1
	s_waitcnt lgkmcnt(0)
	v_mfma_f32_16x16x32_bf16 v[124:127], v[128:131], v[194:197], v[124:127]
	v_mfma_f32_16x16x32_bf16 v[120:123], v[160:163], v[194:197], v[120:123]
	v_mfma_f32_16x16x32_bf16 v[108:111], v[128:131], v[202:205], v[108:111]
	v_mfma_f32_16x16x32_bf16 v[104:107], v[160:163], v[202:205], v[104:107]
	v_mfma_f32_16x16x32_bf16 v[92:95], v[128:131], v[210:213], v[92:95]
	v_mfma_f32_16x16x32_bf16 v[88:91], v[160:163], v[210:213], v[88:91]
	v_mfma_f32_16x16x32_bf16 v[76:79], v[128:131], v[218:221], v[76:79]
	v_mfma_f32_16x16x32_bf16 v[72:75], v[160:163], v[218:221], v[72:75]
	v_mfma_f32_16x16x32_bf16 v[124:127], v[132:135], v[198:201], v[124:127]
	v_mfma_f32_16x16x32_bf16 v[120:123], v[174:177], v[198:201], v[120:123]
	v_mfma_f32_16x16x32_bf16 v[108:111], v[132:135], v[206:209], v[108:111]
	v_mfma_f32_16x16x32_bf16 v[104:107], v[174:177], v[206:209], v[104:107]
	v_mfma_f32_16x16x32_bf16 v[92:95], v[132:135], v[214:217], v[92:95]
	v_mfma_f32_16x16x32_bf16 v[88:91], v[174:177], v[214:217], v[88:91]
	v_mfma_f32_16x16x32_bf16 v[76:79], v[132:135], v[222:225], v[76:79]
	v_mfma_f32_16x16x32_bf16 v[72:75], v[174:177], v[222:225], v[72:75]
	s_setprio 0
	s_setprio 1
	v_mfma_f32_16x16x32_bf16 v[116:119], v[178:181], v[194:197], v[116:119]
	v_mfma_f32_16x16x32_bf16 v[112:115], v[186:189], v[194:197], v[112:115]
	v_mfma_f32_16x16x32_bf16 v[100:103], v[178:181], v[202:205], v[100:103]
	v_mfma_f32_16x16x32_bf16 v[96:99], v[186:189], v[202:205], v[96:99]
	v_mfma_f32_16x16x32_bf16 v[84:87], v[178:181], v[210:213], v[84:87]
	v_mfma_f32_16x16x32_bf16 v[80:83], v[186:189], v[210:213], v[80:83]
	v_mfma_f32_16x16x32_bf16 v[68:71], v[178:181], v[218:221], v[68:71]
	v_mfma_f32_16x16x32_bf16 v[64:67], v[186:189], v[218:221], v[64:67]
	v_mfma_f32_16x16x32_bf16 v[116:119], v[182:185], v[198:201], v[116:119]
	v_mfma_f32_16x16x32_bf16 v[112:115], v[190:193], v[198:201], v[112:115]
	v_mfma_f32_16x16x32_bf16 v[100:103], v[182:185], v[206:209], v[100:103]
	v_mfma_f32_16x16x32_bf16 v[96:99], v[190:193], v[206:209], v[96:99]
	v_mfma_f32_16x16x32_bf16 v[84:87], v[182:185], v[214:217], v[84:87]
	v_mfma_f32_16x16x32_bf16 v[80:83], v[190:193], v[214:217], v[80:83]
	v_mfma_f32_16x16x32_bf16 v[68:71], v[182:185], v[222:225], v[68:71]
	v_mfma_f32_16x16x32_bf16 v[64:67], v[190:193], v[222:225], v[64:67]
	s_setprio 0
	s_barrier
; #define PG8_STAGE(bufoff, gbase, voff) do { _Pragma("unroll") for (int _i = 0; _i < 2; ++_i) \
;         __builtin_amdgcn_global_load_lds((const unsigned*)((const char*)(gbase) + (voff)[_i]), (PG8_LAS unsigned*)(lds + (bufoff) + ldsw + _i * 8192), 16, 0, 0); } while (0)
; #define PG8_LDA(dst, b, h) do { _Pragma("unroll") for (int m = 0; m < 4; ++m) _Pragma("unroll") for (int k = 0; k < 2; ++k) dst[m][k] = *(const PG8_LAS bf16x8*)(lds + PG8_SA(b, h) + aoff + m * 2048 + k * 1024); } while (0)
; #define PG8_MMA(ai, bj, At, Bt) do { __builtin_amdgcn_s_setprio(1); _Pragma("unroll") for (int m = 0; m < 4; ++m) _Pragma("unroll") for (int n = 0; n < 2; ++n) _Pragma("unroll") for (int k = 0; k < 2; ++k) \
;         acc[ai][bj][m][n] = __builtin_amdgcn_mfma_f32_16x16x32_bf16(Bt[n][k], At[m][k], acc[ai][bj][m][n], 0, 0, 0); __builtin_amdgcn_s_setprio(0); } while (0)
; #define PG8_WAIT_V(n) asm volatile("s_waitcnt vmcnt(" #n ")" ::: "memory")
; #define PG8_WAIT_L(n) asm volatile("s_waitcnt lgkmcnt(" #n ")" ::: "memory")
; #define PG8_BAR __builtin_amdgcn_s_barrier()
; #define PG8_SCHED __builtin_amdgcn_sched_barrier(0)
;     __device__ __forceinline__ void operator()(const f32x4 (&acc)[2][2][4][2], const Unit& u, int wr, int wc, int fr, int fq) const {
;     ...
;         if (u.pn < 16) {
; template <class Epi, class Sched, bool ALIGN_EPI = false, bool SP2 = false>
; __device__ __forceinline__ void gemm_phase(PG8_LAS unsigned char* lds, const Gemm g, const Sched& S, const Epi& E, const int wave_in) {
;     ...
;         for (int t = 0; t < nt; t += 2) {
;             const bool last = (t == nt - 2);
;             const char* a1 = cA + (size_t)(t + 1) * kstep;
;             const char* a2 = last ? nA : cA + (size_t)(t + 2) * kstep; const char* b2 = last ? nB : cB + (size_t)(t + 2) * kstep;
;             const char* a3 = a2 + kstep; const char* b3 = b2 + kstep;
;     ...
;             PG8_LDA(At, 1, 1); PG8_STAGE(PG8_SB(1, 0), b3, voffB); PG8_STAGE(PG8_SB(1, 1), b3 + hstep, voffB); PG8_STAGE(PG8_SA(1, 0), a3, voffA);
;             PG8_WAIT_V(8); PG8_WAIT_L(0); PG8_BAR; PG8_MMA(1, 0, At, B0); PG8_MMA(1, 1, At, B1); PG8_BAR; PG8_SCHED;
	s_add_i32 s73, s73, s11
	v_lshl_add_u64 v[164:165], v[164:165], 0, s[62:63]
	s_mov_b32 m0, s73
	ds_read_b128 v[194:197], v171 offset:49152
	ds_read_b128 v[198:201], v171 offset:50176
	ds_read_b128 v[202:205], v171 offset:51200
	ds_read_b128 v[206:209], v171 offset:52224
	ds_read_b128 v[210:213], v171 offset:53248
	ds_read_b128 v[214:217], v171 offset:54272
	ds_read_b128 v[218:221], v171 offset:55296
	ds_read_b128 v[222:225], v171 offset:56320
	global_load_lds_dwordx4 v[164:165], off
	s_add_i32 m0, s73, 0x2000
	s_add_u32 s78, s78, 0x80080
	v_lshl_add_u64 v[164:165], v[226:227], 0, s[62:63]
	s_addc_u32 s79, s79, 0
	s_add_i32 s73, vcc_lo, s11
	global_load_lds_dwordx4 v[164:165], off
	v_lshl_add_u64 v[164:165], s[78:79], 0, v[138:139]
	s_mov_b32 m0, s73
	s_nop 0
	global_load_lds_dwordx4 v[164:165], off
	v_lshl_add_u64 v[164:165], s[78:79], 0, v[142:143]
	s_add_i32 m0, s73, 0x2000
	s_nop 0
	global_load_lds_dwordx4 v[164:165], off
	v_lshl_add_u64 v[164:165], v[228:229], 0, s[62:63]
	s_mov_b32 m0, s49
	s_nop 0
	global_load_lds_dwordx4 v[164:165], off
	v_lshl_add_u64 v[164:165], v[230:231], 0, s[62:63]
	s_mov_b32 m0, s50
	s_nop 0
	global_load_lds_dwordx4 v[164:165], off
	s_waitcnt vmcnt(8)
	s_waitcnt lgkmcnt(0)
	s_barrier
	s_setprio 1
	s_waitcnt lgkmcnt(0)
	v_mfma_f32_16x16x32_bf16 v[60:63], v[128:131], v[194:197], v[60:63]
	v_mfma_f32_16x16x32_bf16 v[56:59], v[160:163], v[194:197], v[56:59]
	v_mfma_f32_16x16x32_bf16 v[44:47], v[128:131], v[202:205], v[44:47]
	v_mfma_f32_16x16x32_bf16 v[40:43], v[160:163], v[202:205], v[40:43]
	v_mfma_f32_16x16x32_bf16 v[28:31], v[128:131], v[210:213], v[28:31]
	v_mfma_f32_16x16x32_bf16 v[24:27], v[160:163], v[210:213], v[24:27]
	v_mfma_f32_16x16x32_bf16 v[12:15], v[128:131], v[218:221], v[12:15]
	v_mfma_f32_16x16x32_bf16 v[8:11], v[160:163], v[218:221], v[8:11]
	v_mfma_f32_16x16x32_bf16 v[60:63], v[132:135], v[198:201], v[60:63]
	v_mfma_f32_16x16x32_bf16 v[56:59], v[174:177], v[198:201], v[56:59]
	v_mfma_f32_16x16x32_bf16 v[44:47], v[132:135], v[206:209], v[44:47]
	v_mfma_f32_16x16x32_bf16 v[40:43], v[174:177], v[206:209], v[40:43]
	v_mfma_f32_16x16x32_bf16 v[28:31], v[132:135], v[214:217], v[28:31]
	v_mfma_f32_16x16x32_bf16 v[24:27], v[174:177], v[214:217], v[24:27]
	v_mfma_f32_16x16x32_bf16 v[12:15], v[132:135], v[222:225], v[12:15]
	v_mfma_f32_16x16x32_bf16 v[8:11], v[174:177], v[222:225], v[8:11]
	s_setprio 0
	s_setprio 1
	v_mfma_f32_16x16x32_bf16 v[52:55], v[178:181], v[194:197], v[52:55]
	v_mfma_f32_16x16x32_bf16 v[48:51], v[186:189], v[194:197], v[48:51]
	v_mfma_f32_16x16x32_bf16 v[36:39], v[178:181], v[202:205], v[36:39]
	v_mfma_f32_16x16x32_bf16 v[32:35], v[186:189], v[202:205], v[32:35]
	v_mfma_f32_16x16x32_bf16 v[20:23], v[178:181], v[210:213], v[20:23]
	v_mfma_f32_16x16x32_bf16 v[16:19], v[186:189], v[210:213], v[16:19]
	v_mfma_f32_16x16x32_bf16 v[4:7], v[178:181], v[218:221], v[4:7]
	v_mfma_f32_16x16x32_bf16 v[0:3], v[186:189], v[218:221], v[0:3]
	v_mfma_f32_16x16x32_bf16 v[52:55], v[182:185], v[198:201], v[52:55]
	v_mfma_f32_16x16x32_bf16 v[48:51], v[190:193], v[198:201], v[48:51]
	v_mfma_f32_16x16x32_bf16 v[36:39], v[182:185], v[206:209], v[36:39]
	v_mfma_f32_16x16x32_bf16 v[32:35], v[190:193], v[206:209], v[32:35]
	v_mfma_f32_16x16x32_bf16 v[20:23], v[182:185], v[214:217], v[20:23]
	v_mfma_f32_16x16x32_bf16 v[16:19], v[190:193], v[214:217], v[16:19]
	v_mfma_f32_16x16x32_bf16 v[4:7], v[182:185], v[222:225], v[4:7]
	v_mfma_f32_16x16x32_bf16 v[0:3], v[190:193], v[222:225], v[0:3]
	s_setprio 0
	s_add_i32 s71, s71, 2
	s_add_u32 s18, s18, 0x100
	s_addc_u32 s19, s19, 0
	s_add_u32 s56, s56, 0x100
	s_addc_u32 s57, s57, 0
	s_cmp_gt_u32 s71, 29
	s_barrier
	s_cbranch_scc0 .LBB0_672
	s_and_b64 vcc, exec, s[64:65]
	s_cbranch_vccnz .LBB0_676
	v_lshl_add_u32 v160, s0, 8, v166
	s_cmp_gt_i32 s6, 15
	s_mov_b64 s[0:1], -1
	s_cbranch_scc1 .LBB0_677

; #define PG8_STAGE(bufoff, gbase, voff) do { _Pragma("unroll") for (int _i = 0; _i < 2; ++_i) \
;         __builtin_amdgcn_global_load_lds((const unsigned*)((const char*)(gbase) + (voff)[_i]), (PG8_LAS unsigned*)(lds + (bufoff) + ldsw + _i * 8192), 16, 0, 0); } while (0)
; #define PG8_LDA(dst, b, h) do { _Pragma("unroll") for (int m = 0; m < 4; ++m) _Pragma("unroll") for (int k = 0; k < 2; ++k) dst[m][k] = *(const PG8_LAS bf16x8*)(lds + PG8_SA(b, h) + aoff + m * 2048 + k * 1024); } while (0)
; #define PG8_LDB(dst, b, h) do { _Pragma("unroll") for (int n = 0; n < 2; ++n) _Pragma("unroll") for (int k = 0; k < 2; ++k) dst[n][k] = *(const PG8_LAS bf16x8*)(lds + PG8_SB(b, h) + boff + n * 2048 + k * 1024); } while (0)
; #define PG8_MMA(ai, bj, At, Bt) do { __builtin_amdgcn_s_setprio(1); _Pragma("unroll") for (int m = 0; m < 4; ++m) _Pragma("unroll") for (int n = 0; n < 2; ++n) _Pragma("unroll") for (int k = 0; k < 2; ++k) \
;         acc[ai][bj][m][n] = __builtin_amdgcn_mfma_f32_16x16x32_bf16(Bt[n][k], At[m][k], acc[ai][bj][m][n], 0, 0, 0); __builtin_amdgcn_s_setprio(0); } while (0)
; #define PG8_WAIT_V(n) asm volatile("s_waitcnt vmcnt(" #n ")" ::: "memory")
; #define PG8_WAIT_L(n) asm volatile("s_waitcnt lgkmcnt(" #n ")" ::: "memory")
; #define PG8_BAR __builtin_amdgcn_s_barrier()
; template <class Epi, class Sched, bool ALIGN_EPI = false, bool SP2 = false>
; __device__ __forceinline__ void gemm_phase(PG8_LAS unsigned char* lds, const Gemm g, const Sched& S, const Epi& E, const int wave_in) {
;     ...
;         for (int t = 0; t < nt; t += 2) {
;             const bool last = (t == nt - 2);
;             const char* a1 = cA + (size_t)(t + 1) * kstep;
;             const char* a2 = last ? nA : cA + (size_t)(t + 2) * kstep; const char* b2 = last ? nB : cB + (size_t)(t + 2) * kstep;
;             const char* a3 = a2 + kstep; const char* b3 = b2 + kstep;
;             if (last && has_next) S.a_ready(nxt);
;             if constexpr (SP2) {
;             PG8_LDB(B0, 0, 0); PG8_LDB(B1, 0, 1); PG8_SCHED; PG8_LDA(At, 0, 0); PG8_STAGE(PG8_SA(1, 1), a1 + hstepA, voffA);
;             PG8_WAIT_V(8); PG8_WAIT_L(0); PG8_BAR; PG8_MMA(0, 0, At, B0); PG8_MMA(0, 1, At, B1); PG8_BAR; PG8_SCHED;
;             PG8_LDA(At, 0, 1); PG8_STAGE(PG8_SB(0, 0), b2, voffB); PG8_STAGE(PG8_SB(0, 1), b2 + hstep, voffB); PG8_STAGE(PG8_SA(0, 0), a2, voffA);
.LBB0_786:
	ds_read_b128 v[128:131], v160
	ds_read_b128 v[152:155], v160 offset:1024
	ds_read_b128 v[164:167], v160 offset:2048
	ds_read_b128 v[168:171], v160 offset:3072
	ds_read_b128 v[172:175], v161
	ds_read_b128 v[176:179], v161 offset:1024
	ds_read_b128 v[180:183], v161 offset:2048
	ds_read_b128 v[184:187], v161 offset:3072
	s_add_u32 s60, s18, 0xfff00080
	s_addc_u32 s61, s19, -1
	s_cmp_eq_u32 s75, 4
	s_cselect_b32 s85, s1, s61
	s_cselect_b32 s84, s5, s60
	s_cselect_b32 s61, s36, s73
	s_cselect_b32 s60, s37, s62
	v_lshl_add_u64 v[156:157], s[18:19], 0, v[144:145]
	s_add_i32 m0, s42, 0xc000
	ds_read_b128 v[188:191], v162
	ds_read_b128 v[192:195], v162 offset:1024
	ds_read_b128 v[196:199], v162 offset:2048
	ds_read_b128 v[200:203], v162 offset:3072
	ds_read_b128 v[204:207], v162 offset:4096
	ds_read_b128 v[208:211], v162 offset:5120
	ds_read_b128 v[212:215], v162 offset:6144
	ds_read_b128 v[216:219], v162 offset:7168
	global_load_lds_dwordx4 v[156:157], off
	v_lshl_add_u64 v[156:157], s[18:19], 0, v[146:147]
	s_add_i32 m0, s42, 0xe000
	s_nop 0
	global_load_lds_dwordx4 v[156:157], off
	s_waitcnt vmcnt(8)
	s_waitcnt lgkmcnt(0)
	s_barrier
	s_setprio 1
	s_waitcnt lgkmcnt(0)
	v_mfma_f32_16x16x32_bf16 v[124:127], v[128:131], v[188:191], v[124:127]
	v_mfma_f32_16x16x32_bf16 v[120:123], v[164:167], v[188:191], v[120:123]
	v_mfma_f32_16x16x32_bf16 v[108:111], v[128:131], v[196:199], v[108:111]
	v_mfma_f32_16x16x32_bf16 v[104:107], v[164:167], v[196:199], v[104:107]
	v_mfma_f32_16x16x32_bf16 v[92:95], v[128:131], v[204:207], v[92:95]
	v_mfma_f32_16x16x32_bf16 v[88:91], v[164:167], v[204:207], v[88:91]
	v_mfma_f32_16x16x32_bf16 v[76:79], v[128:131], v[212:215], v[76:79]
	v_mfma_f32_16x16x32_bf16 v[72:75], v[164:167], v[212:215], v[72:75]
	v_mfma_f32_16x16x32_bf16 v[124:127], v[152:155], v[192:195], v[124:127]
	v_mfma_f32_16x16x32_bf16 v[120:123], v[168:171], v[192:195], v[120:123]
	v_mfma_f32_16x16x32_bf16 v[108:111], v[152:155], v[200:203], v[108:111]
	v_mfma_f32_16x16x32_bf16 v[104:107], v[168:171], v[200:203], v[104:107]
	v_mfma_f32_16x16x32_bf16 v[92:95], v[152:155], v[208:211], v[92:95]
	v_mfma_f32_16x16x32_bf16 v[88:91], v[168:171], v[208:211], v[88:91]
	v_mfma_f32_16x16x32_bf16 v[76:79], v[152:155], v[216:219], v[76:79]
	v_mfma_f32_16x16x32_bf16 v[72:75], v[168:171], v[216:219], v[72:75]
	s_setprio 0
	s_setprio 1
	v_mfma_f32_16x16x32_bf16 v[116:119], v[172:175], v[188:191], v[116:119]
	v_mfma_f32_16x16x32_bf16 v[112:115], v[180:183], v[188:191], v[112:115]
	v_mfma_f32_16x16x32_bf16 v[100:103], v[172:175], v[196:199], v[100:103]
	v_mfma_f32_16x16x32_bf16 v[96:99], v[180:183], v[196:199], v[96:99]
	v_mfma_f32_16x16x32_bf16 v[84:87], v[172:175], v[204:207], v[84:87]
	v_mfma_f32_16x16x32_bf16 v[80:83], v[180:183], v[204:207], v[80:83]
	v_mfma_f32_16x16x32_bf16 v[68:71], v[172:175], v[212:215], v[68:71]
	v_mfma_f32_16x16x32_bf16 v[64:67], v[180:183], v[212:215], v[64:67]
	v_mfma_f32_16x16x32_bf16 v[116:119], v[176:179], v[192:195], v[116:119]
	v_mfma_f32_16x16x32_bf16 v[112:115], v[184:187], v[192:195], v[112:115]
	v_mfma_f32_16x16x32_bf16 v[100:103], v[176:179], v[200:203], v[100:103]
	v_mfma_f32_16x16x32_bf16 v[96:99], v[184:187], v[200:203], v[96:99]
	v_mfma_f32_16x16x32_bf16 v[84:87], v[176:179], v[208:211], v[84:87]
	v_mfma_f32_16x16x32_bf16 v[80:83], v[184:187], v[208:211], v[80:83]
	v_mfma_f32_16x16x32_bf16 v[68:71], v[176:179], v[216:219], v[68:71]
	v_mfma_f32_16x16x32_bf16 v[64:67], v[184:187], v[216:219], v[64:67]
	s_setprio 0
	s_barrier
	s_add_i32 vcc_lo, s93, s41
	v_lshl_add_u64 v[156:157], s[60:61], 0, v[134:135]
	s_mov_b32 m0, vcc_lo
	ds_read_b128 v[188:191], v162 offset:16384
	ds_read_b128 v[192:195], v162 offset:17408
	ds_read_b128 v[196:199], v162 offset:18432
	ds_read_b128 v[200:203], v162 offset:19456
	ds_read_b128 v[204:207], v162 offset:20480
	ds_read_b128 v[208:211], v162 offset:21504
	ds_read_b128 v[212:215], v162 offset:22528
	ds_read_b128 v[216:219], v162 offset:23552
	global_load_lds_dwordx4 v[156:157], off
	s_add_i32 m0, vcc_lo, 0x2000
	s_add_u32 vcc_lo, s60, 0x20000
	v_lshl_add_u64 v[220:221], s[60:61], 0, v[138:139]
	s_addc_u32 vcc_hi, s61, 0
	s_add_i32 s11, s40, s41
	global_load_lds_dwordx4 v[220:221], off
	v_lshl_add_u64 v[222:223], vcc, 0, v[134:135]
	s_mov_b32 m0, s11
	v_lshl_add_u64 v[224:225], s[84:85], 0, v[136:137]
	global_load_lds_dwordx4 v[222:223], off
	v_lshl_add_u64 v[222:223], vcc, 0, v[138:139]
	s_add_i32 m0, s11, 0x2000
	s_nop 0
	global_load_lds_dwordx4 v[222:223], off
	v_lshl_add_u64 v[222:223], s[84:85], 0, v[132:133]
	s_mov_b32 m0, s42
	s_nop 0
	global_load_lds_dwordx4 v[222:223], off
	s_mov_b32 m0, s43
	s_nop 0
	global_load_lds_dwordx4 v[224:225], off
	s_waitcnt vmcnt(8)
	s_waitcnt lgkmcnt(0)
	s_barrier
; #define PG8_STAGE(bufoff, gbase, voff) do { _Pragma("unroll") for (int _i = 0; _i < 2; ++_i) \
;         __builtin_amdgcn_global_load_lds((const unsigned*)((const char*)(gbase) + (voff)[_i]), (PG8_LAS unsigned*)(lds + (bufoff) + ldsw + _i * 8192), 16, 0, 0); } while (0)
; #define PG8_LDA(dst, b, h) do { _Pragma("unroll") for (int m = 0; m < 4; ++m) _Pragma("unroll") for (int k = 0; k < 2; ++k) dst[m][k] = *(const PG8_LAS bf16x8*)(lds + PG8_SA(b, h) + aoff + m * 2048 + k * 1024); } while (0)
; #define PG8_LDB(dst, b, h) do { _Pragma("unroll") for (int n = 0; n < 2; ++n) _Pragma("unroll") for (int k = 0; k < 2; ++k) dst[n][k] = *(const PG8_LAS bf16x8*)(lds + PG8_SB(b, h) + boff + n * 2048 + k * 1024); } while (0)
; #define PG8_MMA(ai, bj, At, Bt) do { __builtin_amdgcn_s_setprio(1); _Pragma("unroll") for (int m = 0; m < 4; ++m) _Pragma("unroll") for (int n = 0; n < 2; ++n) _Pragma("unroll") for (int k = 0; k < 2; ++k) \
;         acc[ai][bj][m][n] = __builtin_amdgcn_mfma_f32_16x16x32_bf16(Bt[n][k], At[m][k], acc[ai][bj][m][n], 0, 0, 0); __builtin_amdgcn_s_setprio(0); } while (0)
; #define PG8_WAIT_V(n) asm volatile("s_waitcnt vmcnt(" #n ")" ::: "memory")
; #define PG8_WAIT_L(n) asm volatile("s_waitcnt lgkmcnt(" #n ")" ::: "memory")
; #define PG8_BAR __builtin_amdgcn_s_barrier()
; #define PG8_SCHED __builtin_amdgcn_sched_barrier(0)
; template <class Epi, class Sched, bool ALIGN_EPI = false, bool SP2 = false>
; __device__ __forceinline__ void gemm_phase(PG8_LAS unsigned char* lds, const Gemm g, const Sched& S, const Epi& E, const int wave_in) {
;     ...
;             PG8_WAIT_V(8); PG8_WAIT_L(0); PG8_BAR; PG8_MMA(1, 0, At, B0); PG8_MMA(1, 1, At, B1); PG8_BAR; PG8_SCHED;
;             PG8_LDB(B0, 1, 0); PG8_LDB(B1, 1, 1); PG8_SCHED; PG8_LDA(At, 1, 0); PG8_STAGE(PG8_SA(0, 1), a2 + hstepA, voffA);
;             PG8_WAIT_V(8); PG8_WAIT_L(0); PG8_BAR; PG8_MMA(0, 0, At, B0); PG8_MMA(0, 1, At, B1); PG8_BAR; PG8_SCHED;
	s_setprio 1
	s_waitcnt lgkmcnt(0)
	v_mfma_f32_16x16x32_bf16 v[60:63], v[128:131], v[188:191], v[60:63]
	v_mfma_f32_16x16x32_bf16 v[56:59], v[164:167], v[188:191], v[56:59]
	v_mfma_f32_16x16x32_bf16 v[44:47], v[128:131], v[196:199], v[44:47]
	v_mfma_f32_16x16x32_bf16 v[40:43], v[164:167], v[196:199], v[40:43]
	v_mfma_f32_16x16x32_bf16 v[28:31], v[128:131], v[204:207], v[28:31]
	v_mfma_f32_16x16x32_bf16 v[24:27], v[164:167], v[204:207], v[24:27]
	v_mfma_f32_16x16x32_bf16 v[12:15], v[128:131], v[212:215], v[12:15]
	v_mfma_f32_16x16x32_bf16 v[8:11], v[164:167], v[212:215], v[8:11]
	v_mfma_f32_16x16x32_bf16 v[60:63], v[152:155], v[192:195], v[60:63]
	v_mfma_f32_16x16x32_bf16 v[56:59], v[168:171], v[192:195], v[56:59]
	v_mfma_f32_16x16x32_bf16 v[44:47], v[152:155], v[200:203], v[44:47]
	v_mfma_f32_16x16x32_bf16 v[40:43], v[168:171], v[200:203], v[40:43]
	v_mfma_f32_16x16x32_bf16 v[28:31], v[152:155], v[208:211], v[28:31]
	v_mfma_f32_16x16x32_bf16 v[24:27], v[168:171], v[208:211], v[24:27]
	v_mfma_f32_16x16x32_bf16 v[12:15], v[152:155], v[216:219], v[12:15]
	v_mfma_f32_16x16x32_bf16 v[8:11], v[168:171], v[216:219], v[8:11]
	s_setprio 0
	s_setprio 1
	v_mfma_f32_16x16x32_bf16 v[52:55], v[172:175], v[188:191], v[52:55]
	v_mfma_f32_16x16x32_bf16 v[48:51], v[180:183], v[188:191], v[48:51]
	v_mfma_f32_16x16x32_bf16 v[36:39], v[172:175], v[196:199], v[36:39]
	v_mfma_f32_16x16x32_bf16 v[32:35], v[180:183], v[196:199], v[32:35]
	v_mfma_f32_16x16x32_bf16 v[20:23], v[172:175], v[204:207], v[20:23]
	v_mfma_f32_16x16x32_bf16 v[16:19], v[180:183], v[204:207], v[16:19]
	v_mfma_f32_16x16x32_bf16 v[4:7], v[172:175], v[212:215], v[4:7]
	v_mfma_f32_16x16x32_bf16 v[0:3], v[180:183], v[212:215], v[0:3]
	v_mfma_f32_16x16x32_bf16 v[52:55], v[176:179], v[192:195], v[52:55]
	v_mfma_f32_16x16x32_bf16 v[48:51], v[184:187], v[192:195], v[48:51]
	v_mfma_f32_16x16x32_bf16 v[36:39], v[176:179], v[200:203], v[36:39]
	v_mfma_f32_16x16x32_bf16 v[32:35], v[184:187], v[200:203], v[32:35]
	v_mfma_f32_16x16x32_bf16 v[20:23], v[176:179], v[208:211], v[20:23]
	v_mfma_f32_16x16x32_bf16 v[16:19], v[184:187], v[208:211], v[16:19]
	v_mfma_f32_16x16x32_bf16 v[4:7], v[176:179], v[216:219], v[4:7]
	v_mfma_f32_16x16x32_bf16 v[0:3], v[184:187], v[216:219], v[0:3]
	s_setprio 0
	s_barrier
	s_add_i32 s11, 0, 0x18000
	s_add_i32 vcc_lo, 0, 0x1c000
	v_add_u32_e32 v168, s11, v159
	v_add_u32_e32 v184, vcc_lo, v159
	ds_read_b128 v[128:131], v168
	ds_read_b128 v[152:155], v168 offset:1024
	ds_read_b128 v[164:167], v168 offset:2048
	ds_read_b128 v[168:171], v168 offset:3072
	ds_read_b128 v[172:175], v184
	ds_read_b128 v[176:179], v184 offset:1024
	ds_read_b128 v[180:183], v184 offset:2048
	ds_read_b128 v[184:187], v184 offset:3072
	s_add_u32 s84, s84, 0x100000
	s_addc_u32 s85, s85, 0
	s_mov_b32 m0, s48
	v_lshl_add_u64 v[226:227], s[84:85], 0, v[132:133]
	ds_read_b128 v[188:191], v162 offset:32768
	ds_read_b128 v[192:195], v162 offset:33792
	ds_read_b128 v[196:199], v162 offset:34816
	ds_read_b128 v[200:203], v162 offset:35840
	ds_read_b128 v[204:207], v162 offset:36864
	ds_read_b128 v[208:211], v162 offset:37888
	ds_read_b128 v[212:215], v162 offset:38912
	ds_read_b128 v[216:219], v162 offset:39936
	global_load_lds_dwordx4 v[226:227], off
	v_lshl_add_u64 v[226:227], s[84:85], 0, v[136:137]
	s_mov_b32 m0, s49
	s_nop 0
	global_load_lds_dwordx4 v[226:227], off
	s_waitcnt vmcnt(8)
	s_waitcnt lgkmcnt(0)
	s_barrier
	s_setprio 1
	s_waitcnt lgkmcnt(0)
	v_mfma_f32_16x16x32_bf16 v[124:127], v[128:131], v[188:191], v[124:127]
	v_mfma_f32_16x16x32_bf16 v[120:123], v[164:167], v[188:191], v[120:123]
	v_mfma_f32_16x16x32_bf16 v[108:111], v[128:131], v[196:199], v[108:111]
	v_mfma_f32_16x16x32_bf16 v[104:107], v[164:167], v[196:199], v[104:107]
	v_mfma_f32_16x16x32_bf16 v[92:95], v[128:131], v[204:207], v[92:95]
	v_mfma_f32_16x16x32_bf16 v[88:91], v[164:167], v[204:207], v[88:91]
	v_mfma_f32_16x16x32_bf16 v[76:79], v[128:131], v[212:215], v[76:79]
	v_mfma_f32_16x16x32_bf16 v[72:75], v[164:167], v[212:215], v[72:75]
	v_mfma_f32_16x16x32_bf16 v[124:127], v[152:155], v[192:195], v[124:127]
	v_mfma_f32_16x16x32_bf16 v[120:123], v[168:171], v[192:195], v[120:123]
	v_mfma_f32_16x16x32_bf16 v[108:111], v[152:155], v[200:203], v[108:111]
	v_mfma_f32_16x16x32_bf16 v[104:107], v[168:171], v[200:203], v[104:107]
	v_mfma_f32_16x16x32_bf16 v[92:95], v[152:155], v[208:211], v[92:95]
	v_mfma_f32_16x16x32_bf16 v[88:91], v[168:171], v[208:211], v[88:91]
	v_mfma_f32_16x16x32_bf16 v[76:79], v[152:155], v[216:219], v[76:79]
	v_mfma_f32_16x16x32_bf16 v[72:75], v[168:171], v[216:219], v[72:75]
	s_setprio 0
	s_setprio 1
	v_mfma_f32_16x16x32_bf16 v[116:119], v[172:175], v[188:191], v[116:119]
	v_mfma_f32_16x16x32_bf16 v[112:115], v[180:183], v[188:191], v[112:115]
	v_mfma_f32_16x16x32_bf16 v[100:103], v[172:175], v[196:199], v[100:103]
	v_mfma_f32_16x16x32_bf16 v[96:99], v[180:183], v[196:199], v[96:99]
	v_mfma_f32_16x16x32_bf16 v[84:87], v[172:175], v[204:207], v[84:87]
	v_mfma_f32_16x16x32_bf16 v[80:83], v[180:183], v[204:207], v[80:83]
	v_mfma_f32_16x16x32_bf16 v[68:71], v[172:175], v[212:215], v[68:71]
	v_mfma_f32_16x16x32_bf16 v[64:67], v[180:183], v[212:215], v[64:67]
	v_mfma_f32_16x16x32_bf16 v[116:119], v[176:179], v[192:195], v[116:119]
	v_mfma_f32_16x16x32_bf16 v[112:115], v[184:187], v[192:195], v[112:115]
	v_mfma_f32_16x16x32_bf16 v[100:103], v[176:179], v[200:203], v[100:103]
	v_mfma_f32_16x16x32_bf16 v[96:99], v[184:187], v[200:203], v[96:99]
	v_mfma_f32_16x16x32_bf16 v[84:87], v[176:179], v[208:211], v[84:87]
	v_mfma_f32_16x16x32_bf16 v[80:83], v[184:187], v[208:211], v[80:83]
	v_mfma_f32_16x16x32_bf16 v[68:71], v[176:179], v[216:219], v[68:71]
	v_mfma_f32_16x16x32_bf16 v[64:67], v[184:187], v[216:219], v[64:67]
	s_setprio 0
	s_barrier
; #define PG8_STAGE(bufoff, gbase, voff) do { _Pragma("unroll") for (int _i = 0; _i < 2; ++_i) \
;         __builtin_amdgcn_global_load_lds((const unsigned*)((const char*)(gbase) + (voff)[_i]), (PG8_LAS unsigned*)(lds + (bufoff) + ldsw + _i * 8192), 16, 0, 0); } while (0)
; #define PG8_LDA(dst, b, h) do { _Pragma("unroll") for (int m = 0; m < 4; ++m) _Pragma("unroll") for (int k = 0; k < 2; ++k) dst[m][k] = *(const PG8_LAS bf16x8*)(lds + PG8_SA(b, h) + aoff + m * 2048 + k * 1024); } while (0)
; #define PG8_MMA(ai, bj, At, Bt) do { __builtin_amdgcn_s_setprio(1); _Pragma("unroll") for (int m = 0; m < 4; ++m) _Pragma("unroll") for (int n = 0; n < 2; ++n) _Pragma("unroll") for (int k = 0; k < 2; ++k) \
;         acc[ai][bj][m][n] = __builtin_amdgcn_mfma_f32_16x16x32_bf16(Bt[n][k], At[m][k], acc[ai][bj][m][n], 0, 0, 0); __builtin_amdgcn_s_setprio(0); } while (0)
; #define PG8_WAIT_V(n) asm volatile("s_waitcnt vmcnt(" #n ")" ::: "memory")
; #define PG8_WAIT_L(n) asm volatile("s_waitcnt lgkmcnt(" #n ")" ::: "memory")
; #define PG8_BAR __builtin_amdgcn_s_barrier()
; #define PG8_SCHED __builtin_amdgcn_sched_barrier(0)
; template <class Epi, class Sched, bool ALIGN_EPI = false, bool SP2 = false>
; __device__ __forceinline__ void gemm_phase(PG8_LAS unsigned char* lds, const Gemm g, const Sched& S, const Epi& E, const int wave_in) {
;     ...
;         for (int t = 0; t < nt; t += 2) {
;             const bool last = (t == nt - 2);
;             const char* a1 = cA + (size_t)(t + 1) * kstep;
;             const char* a2 = last ? nA : cA + (size_t)(t + 2) * kstep; const char* b2 = last ? nB : cB + (size_t)(t + 2) * kstep;
;             const char* a3 = a2 + kstep; const char* b3 = b2 + kstep;
;     ...
;             PG8_LDA(At, 1, 1); PG8_STAGE(PG8_SB(1, 0), b3, voffB); PG8_STAGE(PG8_SB(1, 1), b3 + hstep, voffB); PG8_STAGE(PG8_SA(1, 0), a3, voffA);
;             PG8_WAIT_V(8); PG8_WAIT_L(0); PG8_BAR; PG8_MMA(1, 0, At, B0); PG8_MMA(1, 1, At, B1); PG8_BAR; PG8_SCHED;
	s_add_i32 s11, s11, s41
	v_lshl_add_u64 v[156:157], v[156:157], 0, s[68:69]
	s_mov_b32 m0, s11
	ds_read_b128 v[188:191], v162 offset:49152
	ds_read_b128 v[192:195], v162 offset:50176
	ds_read_b128 v[196:199], v162 offset:51200
	ds_read_b128 v[200:203], v162 offset:52224
	ds_read_b128 v[204:207], v162 offset:53248
	ds_read_b128 v[208:211], v162 offset:54272
	ds_read_b128 v[212:215], v162 offset:55296
	ds_read_b128 v[216:219], v162 offset:56320
	global_load_lds_dwordx4 v[156:157], off
	s_add_i32 m0, s11, 0x2000
	s_add_u32 s60, s60, 0x20080
	v_lshl_add_u64 v[156:157], v[220:221], 0, s[68:69]
	s_addc_u32 s61, s61, 0
	s_add_i32 s11, vcc_lo, s41
	global_load_lds_dwordx4 v[156:157], off
	v_lshl_add_u64 v[156:157], s[60:61], 0, v[134:135]
	s_mov_b32 m0, s11
	s_nop 0
	global_load_lds_dwordx4 v[156:157], off
	v_lshl_add_u64 v[156:157], s[60:61], 0, v[138:139]
	s_add_i32 m0, s11, 0x2000
	s_nop 0
	global_load_lds_dwordx4 v[156:157], off
	v_lshl_add_u64 v[156:157], v[222:223], 0, s[68:69]
	s_mov_b32 m0, s51
	s_nop 0
	global_load_lds_dwordx4 v[156:157], off
	v_lshl_add_u64 v[156:157], v[224:225], 0, s[68:69]
	s_mov_b32 m0, s39
	s_nop 0
	global_load_lds_dwordx4 v[156:157], off
	s_waitcnt vmcnt(8)
	s_waitcnt lgkmcnt(0)
	s_barrier
	s_setprio 1
	s_waitcnt lgkmcnt(0)
	v_mfma_f32_16x16x32_bf16 v[60:63], v[128:131], v[188:191], v[60:63]
	v_mfma_f32_16x16x32_bf16 v[56:59], v[164:167], v[188:191], v[56:59]
	v_mfma_f32_16x16x32_bf16 v[44:47], v[128:131], v[196:199], v[44:47]
	v_mfma_f32_16x16x32_bf16 v[40:43], v[164:167], v[196:199], v[40:43]
	v_mfma_f32_16x16x32_bf16 v[28:31], v[128:131], v[204:207], v[28:31]
	v_mfma_f32_16x16x32_bf16 v[24:27], v[164:167], v[204:207], v[24:27]
	v_mfma_f32_16x16x32_bf16 v[12:15], v[128:131], v[212:215], v[12:15]
	v_mfma_f32_16x16x32_bf16 v[8:11], v[164:167], v[212:215], v[8:11]
	v_mfma_f32_16x16x32_bf16 v[60:63], v[152:155], v[192:195], v[60:63]
	v_mfma_f32_16x16x32_bf16 v[56:59], v[168:171], v[192:195], v[56:59]
	v_mfma_f32_16x16x32_bf16 v[44:47], v[152:155], v[200:203], v[44:47]
	v_mfma_f32_16x16x32_bf16 v[40:43], v[168:171], v[200:203], v[40:43]
	v_mfma_f32_16x16x32_bf16 v[28:31], v[152:155], v[208:211], v[28:31]
	v_mfma_f32_16x16x32_bf16 v[24:27], v[168:171], v[208:211], v[24:27]
	v_mfma_f32_16x16x32_bf16 v[12:15], v[152:155], v[216:219], v[12:15]
	v_mfma_f32_16x16x32_bf16 v[8:11], v[168:171], v[216:219], v[8:11]
	s_setprio 0
	s_setprio 1
	v_mfma_f32_16x16x32_bf16 v[52:55], v[172:175], v[188:191], v[52:55]
	v_mfma_f32_16x16x32_bf16 v[48:51], v[180:183], v[188:191], v[48:51]
	v_mfma_f32_16x16x32_bf16 v[36:39], v[172:175], v[196:199], v[36:39]
	v_mfma_f32_16x16x32_bf16 v[32:35], v[180:183], v[196:199], v[32:35]
	v_mfma_f32_16x16x32_bf16 v[20:23], v[172:175], v[204:207], v[20:23]
	v_mfma_f32_16x16x32_bf16 v[16:19], v[180:183], v[204:207], v[16:19]
	v_mfma_f32_16x16x32_bf16 v[4:7], v[172:175], v[212:215], v[4:7]
	v_mfma_f32_16x16x32_bf16 v[0:3], v[180:183], v[212:215], v[0:3]
	v_mfma_f32_16x16x32_bf16 v[52:55], v[176:179], v[192:195], v[52:55]
	v_mfma_f32_16x16x32_bf16 v[48:51], v[184:187], v[192:195], v[48:51]
	v_mfma_f32_16x16x32_bf16 v[36:39], v[176:179], v[200:203], v[36:39]
	v_mfma_f32_16x16x32_bf16 v[32:35], v[184:187], v[200:203], v[32:35]
	v_mfma_f32_16x16x32_bf16 v[20:23], v[176:179], v[208:211], v[20:23]
	v_mfma_f32_16x16x32_bf16 v[16:19], v[184:187], v[208:211], v[16:19]
	v_mfma_f32_16x16x32_bf16 v[4:7], v[176:179], v[216:219], v[4:7]
	v_mfma_f32_16x16x32_bf16 v[0:3], v[184:187], v[216:219], v[0:3]
	s_setprio 0
	s_add_i32 s75, s75, 2
	s_add_u32 s18, s18, 0x100
	s_addc_u32 s19, s19, 0
	s_add_u32 s62, s62, 0x100
	s_addc_u32 s73, s73, 0
	s_cmp_gt_u32 s75, 5
	s_barrier
	s_cbranch_scc0 .LBB0_786
	s_and_b64 vcc, exec, s[70:71]
	s_cbranch_vccz .LBB0_789
	s_barrier

; #define PG8_STAGE(bufoff, gbase, voff) do { _Pragma("unroll") for (int _i = 0; _i < 2; ++_i) \
;         __builtin_amdgcn_global_load_lds((const unsigned*)((const char*)(gbase) + (voff)[_i]), (PG8_LAS unsigned*)(lds + (bufoff) + ldsw + _i * 8192), 16, 0, 0); } while (0)
; #define PG8_LDA(dst, b, h) do { _Pragma("unroll") for (int m = 0; m < 4; ++m) _Pragma("unroll") for (int k = 0; k < 2; ++k) dst[m][k] = *(const PG8_LAS bf16x8*)(lds + PG8_SA(b, h) + aoff + m * 2048 + k * 1024); } while (0)
; #define PG8_LDB(dst, b, h) do { _Pragma("unroll") for (int n = 0; n < 2; ++n) _Pragma("unroll") for (int k = 0; k < 2; ++k) dst[n][k] = *(const PG8_LAS bf16x8*)(lds + PG8_SB(b, h) + boff + n * 2048 + k * 1024); } while (0)
; #define PG8_MMA(ai, bj, At, Bt) do { __builtin_amdgcn_s_setprio(1); _Pragma("unroll") for (int m = 0; m < 4; ++m) _Pragma("unroll") for (int n = 0; n < 2; ++n) _Pragma("unroll") for (int k = 0; k < 2; ++k) \
;         acc[ai][bj][m][n] = __builtin_amdgcn_mfma_f32_16x16x32_bf16(Bt[n][k], At[m][k], acc[ai][bj][m][n], 0, 0, 0); __builtin_amdgcn_s_setprio(0); } while (0)
; #define PG8_WAIT_V(n) asm volatile("s_waitcnt vmcnt(" #n ")" ::: "memory")
; #define PG8_WAIT_L(n) asm volatile("s_waitcnt lgkmcnt(" #n ")" ::: "memory")
; #define PG8_BAR __builtin_amdgcn_s_barrier()
; template <class Epi, class Sched, bool ALIGN_EPI = false, bool SP2 = false>
; __device__ __forceinline__ void gemm_phase(PG8_LAS unsigned char* lds, const Gemm g, const Sched& S, const Epi& E, const int wave_in) {
;     ...
;         for (int t = 0; t < nt; t += 2) {
;             const bool last = (t == nt - 2);
;             const char* a1 = cA + (size_t)(t + 1) * kstep;
;             const char* a2 = last ? nA : cA + (size_t)(t + 2) * kstep; const char* b2 = last ? nB : cB + (size_t)(t + 2) * kstep;
;             const char* a3 = a2 + kstep; const char* b3 = b2 + kstep;
;             if (last && has_next) S.a_ready(nxt);
;             if constexpr (SP2) {
;             PG8_LDB(B0, 0, 0); PG8_LDB(B1, 0, 1); PG8_SCHED; PG8_LDA(At, 0, 0); PG8_STAGE(PG8_SA(1, 1), a1 + hstepA, voffA);
;             PG8_WAIT_V(8); PG8_WAIT_L(0); PG8_BAR; PG8_MMA(0, 0, At, B0); PG8_MMA(0, 1, At, B1); PG8_BAR; PG8_SCHED;
;             PG8_LDA(At, 0, 1); PG8_STAGE(PG8_SB(0, 0), b2, voffB); PG8_STAGE(PG8_SB(0, 1), b2 + hstep, voffB); PG8_STAGE(PG8_SA(0, 0), a2, voffA);
.LBB0_838:
	ds_read_b128 v[146:149], v152
	ds_read_b128 v[156:159], v152 offset:1024
	ds_read_b128 v[160:163], v152 offset:2048
	ds_read_b128 v[164:167], v152 offset:3072
	ds_read_b128 v[168:171], v153
	ds_read_b128 v[172:175], v153 offset:1024
	ds_read_b128 v[176:179], v153 offset:2048
	ds_read_b128 v[180:183], v153 offset:3072
	s_add_u32 s11, s18, 0xfff00080
	s_addc_u32 s78, s19, -1
	s_cmp_eq_u32 s94, 4
	s_cselect_b32 s85, s1, s78
	s_cselect_b32 s84, s36, s11
	s_cselect_b32 s79, s37, s93
	s_cselect_b32 s78, s69, s71
	v_lshl_add_u64 v[216:217], s[18:19], 0, v[136:137]
	s_add_i32 m0, s42, 0xc000
	ds_read_b128 v[184:187], v154
	ds_read_b128 v[188:191], v154 offset:1024
	ds_read_b128 v[192:195], v154 offset:2048
	ds_read_b128 v[196:199], v154 offset:3072
	ds_read_b128 v[200:203], v154 offset:4096
	ds_read_b128 v[204:207], v154 offset:5120
	ds_read_b128 v[208:211], v154 offset:6144
	ds_read_b128 v[212:215], v154 offset:7168
	global_load_lds_dwordx4 v[216:217], off
	v_lshl_add_u64 v[216:217], s[18:19], 0, v[138:139]
	s_add_i32 m0, s42, 0xe000
	s_nop 0
	global_load_lds_dwordx4 v[216:217], off
	s_waitcnt vmcnt(8)
	s_waitcnt lgkmcnt(0)
	s_barrier
	s_setprio 1
	s_waitcnt lgkmcnt(0)
	v_mfma_f32_16x16x32_bf16 v[124:127], v[146:149], v[184:187], v[124:127]
	v_mfma_f32_16x16x32_bf16 v[120:123], v[160:163], v[184:187], v[120:123]
	v_mfma_f32_16x16x32_bf16 v[108:111], v[146:149], v[192:195], v[108:111]
	v_mfma_f32_16x16x32_bf16 v[104:107], v[160:163], v[192:195], v[104:107]
	v_mfma_f32_16x16x32_bf16 v[92:95], v[146:149], v[200:203], v[92:95]
	v_mfma_f32_16x16x32_bf16 v[88:91], v[160:163], v[200:203], v[88:91]
	v_mfma_f32_16x16x32_bf16 v[76:79], v[146:149], v[208:211], v[76:79]
	v_mfma_f32_16x16x32_bf16 v[72:75], v[160:163], v[208:211], v[72:75]
	v_mfma_f32_16x16x32_bf16 v[124:127], v[156:159], v[188:191], v[124:127]
	v_mfma_f32_16x16x32_bf16 v[120:123], v[164:167], v[188:191], v[120:123]
	v_mfma_f32_16x16x32_bf16 v[108:111], v[156:159], v[196:199], v[108:111]
	v_mfma_f32_16x16x32_bf16 v[104:107], v[164:167], v[196:199], v[104:107]
	v_mfma_f32_16x16x32_bf16 v[92:95], v[156:159], v[204:207], v[92:95]
	v_mfma_f32_16x16x32_bf16 v[88:91], v[164:167], v[204:207], v[88:91]
	v_mfma_f32_16x16x32_bf16 v[76:79], v[156:159], v[212:215], v[76:79]
	v_mfma_f32_16x16x32_bf16 v[72:75], v[164:167], v[212:215], v[72:75]
	s_setprio 0
	s_setprio 1
	v_mfma_f32_16x16x32_bf16 v[116:119], v[168:171], v[184:187], v[116:119]
	v_mfma_f32_16x16x32_bf16 v[112:115], v[176:179], v[184:187], v[112:115]
	v_mfma_f32_16x16x32_bf16 v[100:103], v[168:171], v[192:195], v[100:103]
	v_mfma_f32_16x16x32_bf16 v[96:99], v[176:179], v[192:195], v[96:99]
	v_mfma_f32_16x16x32_bf16 v[84:87], v[168:171], v[200:203], v[84:87]
	v_mfma_f32_16x16x32_bf16 v[80:83], v[176:179], v[200:203], v[80:83]
	v_mfma_f32_16x16x32_bf16 v[68:71], v[168:171], v[208:211], v[68:71]
	v_mfma_f32_16x16x32_bf16 v[64:67], v[176:179], v[208:211], v[64:67]
	v_mfma_f32_16x16x32_bf16 v[116:119], v[172:175], v[188:191], v[116:119]
	v_mfma_f32_16x16x32_bf16 v[112:115], v[180:183], v[188:191], v[112:115]
	v_mfma_f32_16x16x32_bf16 v[100:103], v[172:175], v[196:199], v[100:103]
	v_mfma_f32_16x16x32_bf16 v[96:99], v[180:183], v[196:199], v[96:99]
	v_mfma_f32_16x16x32_bf16 v[84:87], v[172:175], v[204:207], v[84:87]
	v_mfma_f32_16x16x32_bf16 v[80:83], v[180:183], v[204:207], v[80:83]
	v_mfma_f32_16x16x32_bf16 v[68:71], v[172:175], v[212:215], v[68:71]
	v_mfma_f32_16x16x32_bf16 v[64:67], v[180:183], v[212:215], v[64:67]
	s_setprio 0
	s_barrier
	s_add_i32 s11, s56, s39
	v_lshl_add_u64 v[216:217], s[78:79], 0, v[132:133]
	s_mov_b32 m0, s11
	ds_read_b128 v[184:187], v154 offset:16384
	ds_read_b128 v[188:191], v154 offset:17408
	ds_read_b128 v[192:195], v154 offset:18432
	ds_read_b128 v[196:199], v154 offset:19456
	ds_read_b128 v[200:203], v154 offset:20480
	ds_read_b128 v[204:207], v154 offset:21504
	ds_read_b128 v[208:211], v154 offset:22528
	ds_read_b128 v[212:215], v154 offset:23552
	global_load_lds_dwordx4 v[216:217], off
	s_add_i32 m0, s11, 0x2000
	s_add_u32 vcc_lo, s78, 0x20000
	v_lshl_add_u64 v[218:219], s[78:79], 0, v[128:129]
	s_addc_u32 vcc_hi, s79, 0
	s_add_i32 s11, s57, s39
	global_load_lds_dwordx4 v[218:219], off
	v_lshl_add_u64 v[220:221], vcc, 0, v[132:133]
	s_mov_b32 m0, s11
	v_lshl_add_u64 v[222:223], s[84:85], 0, v[130:131]
	global_load_lds_dwordx4 v[220:221], off
	v_lshl_add_u64 v[220:221], vcc, 0, v[128:129]
	s_add_i32 m0, s11, 0x2000
	s_nop 0
	global_load_lds_dwordx4 v[220:221], off
	v_lshl_add_u64 v[220:221], s[84:85], 0, v[134:135]
	s_mov_b32 m0, s42
	s_nop 0
	global_load_lds_dwordx4 v[220:221], off
	s_mov_b32 m0, s43
	s_nop 0
	global_load_lds_dwordx4 v[222:223], off
	s_waitcnt vmcnt(8)
	s_waitcnt lgkmcnt(0)
	s_barrier
; #define PG8_STAGE(bufoff, gbase, voff) do { _Pragma("unroll") for (int _i = 0; _i < 2; ++_i) \
;         __builtin_amdgcn_global_load_lds((const unsigned*)((const char*)(gbase) + (voff)[_i]), (PG8_LAS unsigned*)(lds + (bufoff) + ldsw + _i * 8192), 16, 0, 0); } while (0)
; #define PG8_LDA(dst, b, h) do { _Pragma("unroll") for (int m = 0; m < 4; ++m) _Pragma("unroll") for (int k = 0; k < 2; ++k) dst[m][k] = *(const PG8_LAS bf16x8*)(lds + PG8_SA(b, h) + aoff + m * 2048 + k * 1024); } while (0)
; #define PG8_LDB(dst, b, h) do { _Pragma("unroll") for (int n = 0; n < 2; ++n) _Pragma("unroll") for (int k = 0; k < 2; ++k) dst[n][k] = *(const PG8_LAS bf16x8*)(lds + PG8_SB(b, h) + boff + n * 2048 + k * 1024); } while (0)
; #define PG8_MMA(ai, bj, At, Bt) do { __builtin_amdgcn_s_setprio(1); _Pragma("unroll") for (int m = 0; m < 4; ++m) _Pragma("unroll") for (int n = 0; n < 2; ++n) _Pragma("unroll") for (int k = 0; k < 2; ++k) \
;         acc[ai][bj][m][n] = __builtin_amdgcn_mfma_f32_16x16x32_bf16(Bt[n][k], At[m][k], acc[ai][bj][m][n], 0, 0, 0); __builtin_amdgcn_s_setprio(0); } while (0)
; #define PG8_WAIT_V(n) asm volatile("s_waitcnt vmcnt(" #n ")" ::: "memory")
; #define PG8_WAIT_L(n) asm volatile("s_waitcnt lgkmcnt(" #n ")" ::: "memory")
; #define PG8_BAR __builtin_amdgcn_s_barrier()
; #define PG8_SCHED __builtin_amdgcn_sched_barrier(0)
; template <class Epi, class Sched, bool ALIGN_EPI = false, bool SP2 = false>
; __device__ __forceinline__ void gemm_phase(PG8_LAS unsigned char* lds, const Gemm g, const Sched& S, const Epi& E, const int wave_in) {
;     ...
;             PG8_WAIT_V(8); PG8_WAIT_L(0); PG8_BAR; PG8_MMA(1, 0, At, B0); PG8_MMA(1, 1, At, B1); PG8_BAR; PG8_SCHED;
;             PG8_LDB(B0, 1, 0); PG8_LDB(B1, 1, 1); PG8_SCHED; PG8_LDA(At, 1, 0); PG8_STAGE(PG8_SA(0, 1), a2 + hstepA, voffA);
;             PG8_WAIT_V(8); PG8_WAIT_L(0); PG8_BAR; PG8_MMA(0, 0, At, B0); PG8_MMA(0, 1, At, B1); PG8_BAR; PG8_SCHED;
	s_setprio 1
	s_waitcnt lgkmcnt(0)
	v_mfma_f32_16x16x32_bf16 v[60:63], v[146:149], v[184:187], v[60:63]
	v_mfma_f32_16x16x32_bf16 v[56:59], v[160:163], v[184:187], v[56:59]
	v_mfma_f32_16x16x32_bf16 v[44:47], v[146:149], v[192:195], v[44:47]
	v_mfma_f32_16x16x32_bf16 v[40:43], v[160:163], v[192:195], v[40:43]
	v_mfma_f32_16x16x32_bf16 v[28:31], v[146:149], v[200:203], v[28:31]
	v_mfma_f32_16x16x32_bf16 v[24:27], v[160:163], v[200:203], v[24:27]
	v_mfma_f32_16x16x32_bf16 v[12:15], v[146:149], v[208:211], v[12:15]
	v_mfma_f32_16x16x32_bf16 v[8:11], v[160:163], v[208:211], v[8:11]
	v_mfma_f32_16x16x32_bf16 v[60:63], v[156:159], v[188:191], v[60:63]
	v_mfma_f32_16x16x32_bf16 v[56:59], v[164:167], v[188:191], v[56:59]
	v_mfma_f32_16x16x32_bf16 v[44:47], v[156:159], v[196:199], v[44:47]
	v_mfma_f32_16x16x32_bf16 v[40:43], v[164:167], v[196:199], v[40:43]
	v_mfma_f32_16x16x32_bf16 v[28:31], v[156:159], v[204:207], v[28:31]
	v_mfma_f32_16x16x32_bf16 v[24:27], v[164:167], v[204:207], v[24:27]
	v_mfma_f32_16x16x32_bf16 v[12:15], v[156:159], v[212:215], v[12:15]
	v_mfma_f32_16x16x32_bf16 v[8:11], v[164:167], v[212:215], v[8:11]
	s_setprio 0
	s_setprio 1
	v_mfma_f32_16x16x32_bf16 v[52:55], v[168:171], v[184:187], v[52:55]
	v_mfma_f32_16x16x32_bf16 v[48:51], v[176:179], v[184:187], v[48:51]
	v_mfma_f32_16x16x32_bf16 v[36:39], v[168:171], v[192:195], v[36:39]
	v_mfma_f32_16x16x32_bf16 v[32:35], v[176:179], v[192:195], v[32:35]
	v_mfma_f32_16x16x32_bf16 v[20:23], v[168:171], v[200:203], v[20:23]
	v_mfma_f32_16x16x32_bf16 v[16:19], v[176:179], v[200:203], v[16:19]
	v_mfma_f32_16x16x32_bf16 v[4:7], v[168:171], v[208:211], v[4:7]
	v_mfma_f32_16x16x32_bf16 v[0:3], v[176:179], v[208:211], v[0:3]
	v_mfma_f32_16x16x32_bf16 v[52:55], v[172:175], v[188:191], v[52:55]
	v_mfma_f32_16x16x32_bf16 v[48:51], v[180:183], v[188:191], v[48:51]
	v_mfma_f32_16x16x32_bf16 v[36:39], v[172:175], v[196:199], v[36:39]
	v_mfma_f32_16x16x32_bf16 v[32:35], v[180:183], v[196:199], v[32:35]
	v_mfma_f32_16x16x32_bf16 v[20:23], v[172:175], v[204:207], v[20:23]
	v_mfma_f32_16x16x32_bf16 v[16:19], v[180:183], v[204:207], v[16:19]
	v_mfma_f32_16x16x32_bf16 v[4:7], v[172:175], v[212:215], v[4:7]
	v_mfma_f32_16x16x32_bf16 v[0:3], v[180:183], v[212:215], v[0:3]
	s_setprio 0
	s_barrier
	s_add_i32 s11, 0, 0x18000
	s_add_i32 s95, 0, 0x1c000
	v_add_u32_e32 v164, s11, v151
	v_add_u32_e32 v180, s95, v151
	ds_read_b128 v[146:149], v164
	ds_read_b128 v[156:159], v164 offset:1024
	ds_read_b128 v[160:163], v164 offset:2048
	ds_read_b128 v[164:167], v164 offset:3072
	ds_read_b128 v[168:171], v180
	ds_read_b128 v[172:175], v180 offset:1024
	ds_read_b128 v[176:179], v180 offset:2048
	ds_read_b128 v[180:183], v180 offset:3072
	s_add_u32 s84, s84, 0x100000
	s_addc_u32 s85, s85, 0
	s_mov_b32 m0, s48
	v_lshl_add_u64 v[224:225], s[84:85], 0, v[134:135]
	ds_read_b128 v[184:187], v154 offset:32768
	ds_read_b128 v[188:191], v154 offset:33792
	ds_read_b128 v[192:195], v154 offset:34816
	ds_read_b128 v[196:199], v154 offset:35840
	ds_read_b128 v[200:203], v154 offset:36864
	ds_read_b128 v[204:207], v154 offset:37888
	ds_read_b128 v[208:211], v154 offset:38912
	ds_read_b128 v[212:215], v154 offset:39936
	global_load_lds_dwordx4 v[224:225], off
	v_lshl_add_u64 v[224:225], s[84:85], 0, v[130:131]
	s_mov_b32 m0, s49
	s_nop 0
	global_load_lds_dwordx4 v[224:225], off
	s_waitcnt vmcnt(8)
	s_waitcnt lgkmcnt(0)
	s_barrier
	s_setprio 1
	s_waitcnt lgkmcnt(0)
	v_mfma_f32_16x16x32_bf16 v[124:127], v[146:149], v[184:187], v[124:127]
	v_mfma_f32_16x16x32_bf16 v[120:123], v[160:163], v[184:187], v[120:123]
	v_mfma_f32_16x16x32_bf16 v[108:111], v[146:149], v[192:195], v[108:111]
	v_mfma_f32_16x16x32_bf16 v[104:107], v[160:163], v[192:195], v[104:107]
	v_mfma_f32_16x16x32_bf16 v[92:95], v[146:149], v[200:203], v[92:95]
	v_mfma_f32_16x16x32_bf16 v[88:91], v[160:163], v[200:203], v[88:91]
	v_mfma_f32_16x16x32_bf16 v[76:79], v[146:149], v[208:211], v[76:79]
	v_mfma_f32_16x16x32_bf16 v[72:75], v[160:163], v[208:211], v[72:75]
	v_mfma_f32_16x16x32_bf16 v[124:127], v[156:159], v[188:191], v[124:127]
	v_mfma_f32_16x16x32_bf16 v[120:123], v[164:167], v[188:191], v[120:123]
	v_mfma_f32_16x16x32_bf16 v[108:111], v[156:159], v[196:199], v[108:111]
	v_mfma_f32_16x16x32_bf16 v[104:107], v[164:167], v[196:199], v[104:107]
	v_mfma_f32_16x16x32_bf16 v[92:95], v[156:159], v[204:207], v[92:95]
	v_mfma_f32_16x16x32_bf16 v[88:91], v[164:167], v[204:207], v[88:91]
	v_mfma_f32_16x16x32_bf16 v[76:79], v[156:159], v[212:215], v[76:79]
	v_mfma_f32_16x16x32_bf16 v[72:75], v[164:167], v[212:215], v[72:75]
	s_setprio 0
	s_setprio 1
	v_mfma_f32_16x16x32_bf16 v[116:119], v[168:171], v[184:187], v[116:119]
	v_mfma_f32_16x16x32_bf16 v[112:115], v[176:179], v[184:187], v[112:115]
	v_mfma_f32_16x16x32_bf16 v[100:103], v[168:171], v[192:195], v[100:103]
	v_mfma_f32_16x16x32_bf16 v[96:99], v[176:179], v[192:195], v[96:99]
	v_mfma_f32_16x16x32_bf16 v[84:87], v[168:171], v[200:203], v[84:87]
	v_mfma_f32_16x16x32_bf16 v[80:83], v[176:179], v[200:203], v[80:83]
	v_mfma_f32_16x16x32_bf16 v[68:71], v[168:171], v[208:211], v[68:71]
	v_mfma_f32_16x16x32_bf16 v[64:67], v[176:179], v[208:211], v[64:67]
	v_mfma_f32_16x16x32_bf16 v[116:119], v[172:175], v[188:191], v[116:119]
	v_mfma_f32_16x16x32_bf16 v[112:115], v[180:183], v[188:191], v[112:115]
	v_mfma_f32_16x16x32_bf16 v[100:103], v[172:175], v[196:199], v[100:103]
	v_mfma_f32_16x16x32_bf16 v[96:99], v[180:183], v[196:199], v[96:99]
	v_mfma_f32_16x16x32_bf16 v[84:87], v[172:175], v[204:207], v[84:87]
	v_mfma_f32_16x16x32_bf16 v[80:83], v[180:183], v[204:207], v[80:83]
	v_mfma_f32_16x16x32_bf16 v[68:71], v[172:175], v[212:215], v[68:71]
	v_mfma_f32_16x16x32_bf16 v[64:67], v[180:183], v[212:215], v[64:67]
	s_setprio 0
	s_barrier
; #define PG8_STAGE(bufoff, gbase, voff) do { _Pragma("unroll") for (int _i = 0; _i < 2; ++_i) \
;         __builtin_amdgcn_global_load_lds((const unsigned*)((const char*)(gbase) + (voff)[_i]), (PG8_LAS unsigned*)(lds + (bufoff) + ldsw + _i * 8192), 16, 0, 0); } while (0)
; #define PG8_LDA(dst, b, h) do { _Pragma("unroll") for (int m = 0; m < 4; ++m) _Pragma("unroll") for (int k = 0; k < 2; ++k) dst[m][k] = *(const PG8_LAS bf16x8*)(lds + PG8_SA(b, h) + aoff + m * 2048 + k * 1024); } while (0)
; #define PG8_MMA(ai, bj, At, Bt) do { __builtin_amdgcn_s_setprio(1); _Pragma("unroll") for (int m = 0; m < 4; ++m) _Pragma("unroll") for (int n = 0; n < 2; ++n) _Pragma("unroll") for (int k = 0; k < 2; ++k) \
;         acc[ai][bj][m][n] = __builtin_amdgcn_mfma_f32_16x16x32_bf16(Bt[n][k], At[m][k], acc[ai][bj][m][n], 0, 0, 0); __builtin_amdgcn_s_setprio(0); } while (0)
; #define PG8_WAIT_V(n) asm volatile("s_waitcnt vmcnt(" #n ")" ::: "memory")
; #define PG8_WAIT_L(n) asm volatile("s_waitcnt lgkmcnt(" #n ")" ::: "memory")
; #define PG8_BAR __builtin_amdgcn_s_barrier()
; #define PG8_SCHED __builtin_amdgcn_sched_barrier(0)
; template <class Epi, class Sched, bool ALIGN_EPI = false, bool SP2 = false>
; __device__ __forceinline__ void gemm_phase(PG8_LAS unsigned char* lds, const Gemm g, const Sched& S, const Epi& E, const int wave_in) {
;     ...
;         for (int t = 0; t < nt; t += 2) {
;             const bool last = (t == nt - 2);
;             const char* a1 = cA + (size_t)(t + 1) * kstep;
;             const char* a2 = last ? nA : cA + (size_t)(t + 2) * kstep; const char* b2 = last ? nB : cB + (size_t)(t + 2) * kstep;
;             const char* a3 = a2 + kstep; const char* b3 = b2 + kstep;
;     ...
;             PG8_LDA(At, 1, 1); PG8_STAGE(PG8_SB(1, 0), b3, voffB); PG8_STAGE(PG8_SB(1, 1), b3 + hstep, voffB); PG8_STAGE(PG8_SA(1, 0), a3, voffA);
;             PG8_WAIT_V(8); PG8_WAIT_L(0); PG8_BAR; PG8_MMA(1, 0, At, B0); PG8_MMA(1, 1, At, B1); PG8_BAR; PG8_SCHED;
	s_add_i32 s11, s11, s39
	v_lshl_add_u64 v[216:217], v[216:217], 0, s[64:65]
	s_mov_b32 m0, s11
	ds_read_b128 v[184:187], v154 offset:49152
	ds_read_b128 v[188:191], v154 offset:50176
	ds_read_b128 v[192:195], v154 offset:51200
	ds_read_b128 v[196:199], v154 offset:52224
	ds_read_b128 v[200:203], v154 offset:53248
	ds_read_b128 v[204:207], v154 offset:54272
	ds_read_b128 v[208:211], v154 offset:55296
	ds_read_b128 v[212:215], v154 offset:56320
	global_load_lds_dwordx4 v[216:217], off
	s_add_i32 m0, s11, 0x2000
	s_add_u32 s78, s78, 0x20080
	v_lshl_add_u64 v[216:217], v[218:219], 0, s[64:65]
	s_addc_u32 s79, s79, 0
	s_add_i32 s11, s95, s39
	global_load_lds_dwordx4 v[216:217], off
	v_lshl_add_u64 v[216:217], s[78:79], 0, v[132:133]
	s_mov_b32 m0, s11
	s_nop 0
	global_load_lds_dwordx4 v[216:217], off
	v_lshl_add_u64 v[216:217], s[78:79], 0, v[128:129]
	s_add_i32 m0, s11, 0x2000
	s_nop 0
	global_load_lds_dwordx4 v[216:217], off
	v_lshl_add_u64 v[216:217], v[220:221], 0, s[64:65]
	s_mov_b32 m0, s50
	s_nop 0
	global_load_lds_dwordx4 v[216:217], off
	v_lshl_add_u64 v[216:217], v[222:223], 0, s[64:65]
	s_mov_b32 m0, s51
	s_nop 0
	global_load_lds_dwordx4 v[216:217], off
	s_waitcnt vmcnt(8)
	s_waitcnt lgkmcnt(0)
	s_barrier
	s_setprio 1
	s_waitcnt lgkmcnt(0)
	v_mfma_f32_16x16x32_bf16 v[60:63], v[146:149], v[184:187], v[60:63]
	v_mfma_f32_16x16x32_bf16 v[56:59], v[160:163], v[184:187], v[56:59]
	v_mfma_f32_16x16x32_bf16 v[44:47], v[146:149], v[192:195], v[44:47]
	v_mfma_f32_16x16x32_bf16 v[40:43], v[160:163], v[192:195], v[40:43]
	v_mfma_f32_16x16x32_bf16 v[28:31], v[146:149], v[200:203], v[28:31]
	v_mfma_f32_16x16x32_bf16 v[24:27], v[160:163], v[200:203], v[24:27]
	v_mfma_f32_16x16x32_bf16 v[12:15], v[146:149], v[208:211], v[12:15]
	v_mfma_f32_16x16x32_bf16 v[8:11], v[160:163], v[208:211], v[8:11]
	v_mfma_f32_16x16x32_bf16 v[60:63], v[156:159], v[188:191], v[60:63]
	v_mfma_f32_16x16x32_bf16 v[56:59], v[164:167], v[188:191], v[56:59]
	v_mfma_f32_16x16x32_bf16 v[44:47], v[156:159], v[196:199], v[44:47]
	v_mfma_f32_16x16x32_bf16 v[40:43], v[164:167], v[196:199], v[40:43]
	v_mfma_f32_16x16x32_bf16 v[28:31], v[156:159], v[204:207], v[28:31]
	v_mfma_f32_16x16x32_bf16 v[24:27], v[164:167], v[204:207], v[24:27]
	v_mfma_f32_16x16x32_bf16 v[12:15], v[156:159], v[212:215], v[12:15]
	v_mfma_f32_16x16x32_bf16 v[8:11], v[164:167], v[212:215], v[8:11]
	s_setprio 0
	s_setprio 1
	v_mfma_f32_16x16x32_bf16 v[52:55], v[168:171], v[184:187], v[52:55]
	v_mfma_f32_16x16x32_bf16 v[48:51], v[176:179], v[184:187], v[48:51]
	v_mfma_f32_16x16x32_bf16 v[36:39], v[168:171], v[192:195], v[36:39]
	v_mfma_f32_16x16x32_bf16 v[32:35], v[176:179], v[192:195], v[32:35]
	v_mfma_f32_16x16x32_bf16 v[20:23], v[168:171], v[200:203], v[20:23]
	v_mfma_f32_16x16x32_bf16 v[16:19], v[176:179], v[200:203], v[16:19]
	v_mfma_f32_16x16x32_bf16 v[4:7], v[168:171], v[208:211], v[4:7]
	v_mfma_f32_16x16x32_bf16 v[0:3], v[176:179], v[208:211], v[0:3]
	v_mfma_f32_16x16x32_bf16 v[52:55], v[172:175], v[188:191], v[52:55]
	v_mfma_f32_16x16x32_bf16 v[48:51], v[180:183], v[188:191], v[48:51]
	v_mfma_f32_16x16x32_bf16 v[36:39], v[172:175], v[196:199], v[36:39]
	v_mfma_f32_16x16x32_bf16 v[32:35], v[180:183], v[196:199], v[32:35]
	v_mfma_f32_16x16x32_bf16 v[20:23], v[172:175], v[204:207], v[20:23]
	v_mfma_f32_16x16x32_bf16 v[16:19], v[180:183], v[204:207], v[16:19]
	v_mfma_f32_16x16x32_bf16 v[4:7], v[172:175], v[212:215], v[4:7]
	v_mfma_f32_16x16x32_bf16 v[0:3], v[180:183], v[212:215], v[0:3]
	s_setprio 0
	s_add_i32 s94, s94, 2
	s_add_u32 s18, s18, 0x100
	s_addc_u32 s19, s19, 0
	s_add_u32 s71, s71, 0x100
	s_addc_u32 s93, s93, 0
	s_cmp_gt_u32 s94, 5
	s_barrier
	s_cbranch_scc0 .LBB0_838
	s_and_b64 vcc, exec, s[66:67]
	s_cbranch_vccz .LBB0_841
	s_barrier

; #define PG8_STAGE(bufoff, gbase, voff) do { _Pragma("unroll") for (int _i = 0; _i < 2; ++_i) \
;         __builtin_amdgcn_global_load_lds((const unsigned*)((const char*)(gbase) + (voff)[_i]), (PG8_LAS unsigned*)(lds + (bufoff) + ldsw + _i * 8192), 16, 0, 0); } while (0)
; #define PG8_LDA(dst, b, h) do { _Pragma("unroll") for (int m = 0; m < 4; ++m) _Pragma("unroll") for (int k = 0; k < 2; ++k) dst[m][k] = *(const PG8_LAS bf16x8*)(lds + PG8_SA(b, h) + aoff + m * 2048 + k * 1024); } while (0)
; #define PG8_LDB(dst, b, h) do { _Pragma("unroll") for (int n = 0; n < 2; ++n) _Pragma("unroll") for (int k = 0; k < 2; ++k) dst[n][k] = *(const PG8_LAS bf16x8*)(lds + PG8_SB(b, h) + boff + n * 2048 + k * 1024); } while (0)
; #define PG8_MMA(ai, bj, At, Bt) do { __builtin_amdgcn_s_setprio(1); _Pragma("unroll") for (int m = 0; m < 4; ++m) _Pragma("unroll") for (int n = 0; n < 2; ++n) _Pragma("unroll") for (int k = 0; k < 2; ++k) \
;         acc[ai][bj][m][n] = __builtin_amdgcn_mfma_f32_16x16x32_bf16(Bt[n][k], At[m][k], acc[ai][bj][m][n], 0, 0, 0); __builtin_amdgcn_s_setprio(0); } while (0)
; #define PG8_WAIT_V(n) asm volatile("s_waitcnt vmcnt(" #n ")" ::: "memory")
; #define PG8_WAIT_L(n) asm volatile("s_waitcnt lgkmcnt(" #n ")" ::: "memory")
; #define PG8_BAR __builtin_amdgcn_s_barrier()
; template <class Epi, class Sched, bool ALIGN_EPI = false, bool SP2 = false>
; __device__ __forceinline__ void gemm_phase(PG8_LAS unsigned char* lds, const Gemm g, const Sched& S, const Epi& E, const int wave_in) {
;     ...
;         for (int t = 0; t < nt; t += 2) {
;             const bool last = (t == nt - 2);
;             const char* a1 = cA + (size_t)(t + 1) * kstep;
;             const char* a2 = last ? nA : cA + (size_t)(t + 2) * kstep; const char* b2 = last ? nB : cB + (size_t)(t + 2) * kstep;
;             const char* a3 = a2 + kstep; const char* b3 = b2 + kstep;
;             if (last && has_next) S.a_ready(nxt);
;             if constexpr (SP2) {
;             PG8_LDB(B0, 0, 0); PG8_LDB(B1, 0, 1); PG8_SCHED; PG8_LDA(At, 0, 0); PG8_STAGE(PG8_SA(1, 1), a1 + hstepA, voffA);
;             PG8_WAIT_V(8); PG8_WAIT_L(0); PG8_BAR; PG8_MMA(0, 0, At, B0); PG8_MMA(0, 1, At, B1); PG8_BAR; PG8_SCHED;
;             PG8_LDA(At, 0, 1); PG8_STAGE(PG8_SB(0, 0), b2, voffB); PG8_STAGE(PG8_SB(0, 1), b2 + hstep, voffB); PG8_STAGE(PG8_SA(0, 0), a2, voffA);
.LBB0_1303:
	ds_read_b128 v[144:147], v151
	ds_read_b128 v[156:159], v151 offset:1024
	ds_read_b128 v[160:163], v151 offset:2048
	ds_read_b128 v[164:167], v151 offset:3072
	ds_read_b128 v[168:171], v152
	ds_read_b128 v[172:175], v152 offset:1024
	ds_read_b128 v[176:179], v152 offset:2048
	ds_read_b128 v[180:183], v152 offset:3072
	s_add_u32 s68, s66, 0xfff80080
	s_addc_u32 s69, s67, -1
	s_cmp_eq_u32 s78, 28
	s_cselect_b32 s71, s43, s69
	s_cselect_b32 s70, s48, s68
	s_cselect_b32 s69, s41, s77
	s_cselect_b32 s68, s49, s76
	v_lshl_add_u64 v[216:217], s[66:67], 0, v[136:137]
	s_add_i32 m0, s33, 0xc000
	ds_read_b128 v[184:187], v153
	ds_read_b128 v[188:191], v153 offset:1024
	ds_read_b128 v[192:195], v153 offset:2048
	ds_read_b128 v[196:199], v153 offset:3072
	ds_read_b128 v[200:203], v153 offset:4096
	ds_read_b128 v[204:207], v153 offset:5120
	ds_read_b128 v[208:211], v153 offset:6144
	ds_read_b128 v[212:215], v153 offset:7168
	global_load_lds_dwordx4 v[216:217], off
	v_lshl_add_u64 v[216:217], s[66:67], 0, v[138:139]
	s_add_i32 m0, s33, 0xe000
	s_nop 0
	global_load_lds_dwordx4 v[216:217], off
	s_waitcnt vmcnt(8)
	s_waitcnt lgkmcnt(0)
	s_barrier
	s_setprio 1
	s_waitcnt lgkmcnt(0)
	v_mfma_f32_16x16x32_bf16 v[124:127], v[144:147], v[184:187], v[124:127]
	v_mfma_f32_16x16x32_bf16 v[120:123], v[160:163], v[184:187], v[120:123]
	v_mfma_f32_16x16x32_bf16 v[108:111], v[144:147], v[192:195], v[108:111]
	v_mfma_f32_16x16x32_bf16 v[104:107], v[160:163], v[192:195], v[104:107]
	v_mfma_f32_16x16x32_bf16 v[92:95], v[144:147], v[200:203], v[92:95]
	v_mfma_f32_16x16x32_bf16 v[88:91], v[160:163], v[200:203], v[88:91]
	v_mfma_f32_16x16x32_bf16 v[76:79], v[144:147], v[208:211], v[76:79]
	v_mfma_f32_16x16x32_bf16 v[72:75], v[160:163], v[208:211], v[72:75]
	v_mfma_f32_16x16x32_bf16 v[124:127], v[156:159], v[188:191], v[124:127]
	v_mfma_f32_16x16x32_bf16 v[120:123], v[164:167], v[188:191], v[120:123]
	v_mfma_f32_16x16x32_bf16 v[108:111], v[156:159], v[196:199], v[108:111]
	v_mfma_f32_16x16x32_bf16 v[104:107], v[164:167], v[196:199], v[104:107]
	v_mfma_f32_16x16x32_bf16 v[92:95], v[156:159], v[204:207], v[92:95]
	v_mfma_f32_16x16x32_bf16 v[88:91], v[164:167], v[204:207], v[88:91]
	v_mfma_f32_16x16x32_bf16 v[76:79], v[156:159], v[212:215], v[76:79]
	v_mfma_f32_16x16x32_bf16 v[72:75], v[164:167], v[212:215], v[72:75]
	s_setprio 0
	s_setprio 1
	v_mfma_f32_16x16x32_bf16 v[116:119], v[168:171], v[184:187], v[116:119]
	v_mfma_f32_16x16x32_bf16 v[112:115], v[176:179], v[184:187], v[112:115]
	v_mfma_f32_16x16x32_bf16 v[100:103], v[168:171], v[192:195], v[100:103]
	v_mfma_f32_16x16x32_bf16 v[96:99], v[176:179], v[192:195], v[96:99]
	v_mfma_f32_16x16x32_bf16 v[84:87], v[168:171], v[200:203], v[84:87]
	v_mfma_f32_16x16x32_bf16 v[80:83], v[176:179], v[200:203], v[80:83]
	v_mfma_f32_16x16x32_bf16 v[68:71], v[168:171], v[208:211], v[68:71]
	v_mfma_f32_16x16x32_bf16 v[64:67], v[176:179], v[208:211], v[64:67]
	v_mfma_f32_16x16x32_bf16 v[116:119], v[172:175], v[188:191], v[116:119]
	v_mfma_f32_16x16x32_bf16 v[112:115], v[180:183], v[188:191], v[112:115]
	v_mfma_f32_16x16x32_bf16 v[100:103], v[172:175], v[196:199], v[100:103]
	v_mfma_f32_16x16x32_bf16 v[96:99], v[180:183], v[196:199], v[96:99]
	v_mfma_f32_16x16x32_bf16 v[84:87], v[172:175], v[204:207], v[84:87]
	v_mfma_f32_16x16x32_bf16 v[80:83], v[180:183], v[204:207], v[80:83]
	v_mfma_f32_16x16x32_bf16 v[68:71], v[172:175], v[212:215], v[68:71]
	v_mfma_f32_16x16x32_bf16 v[64:67], v[180:183], v[212:215], v[64:67]
	s_setprio 0
	s_barrier
	s_add_i32 s79, s74, s11
	v_lshl_add_u64 v[216:217], s[68:69], 0, v[130:131]
	s_mov_b32 m0, s79
	ds_read_b128 v[184:187], v153 offset:16384
	ds_read_b128 v[188:191], v153 offset:17408
	ds_read_b128 v[192:195], v153 offset:18432
	ds_read_b128 v[196:199], v153 offset:19456
	ds_read_b128 v[200:203], v153 offset:20480
	ds_read_b128 v[204:207], v153 offset:21504
	ds_read_b128 v[208:211], v153 offset:22528
	ds_read_b128 v[212:215], v153 offset:23552
	global_load_lds_dwordx4 v[216:217], off
	s_add_i32 m0, s79, 0x2000
	s_add_u32 s82, s68, 0x80000
	v_lshl_add_u64 v[218:219], s[68:69], 0, v[134:135]
	s_addc_u32 s83, s69, 0
	s_add_i32 s79, s75, s11
	global_load_lds_dwordx4 v[218:219], off
	v_lshl_add_u64 v[220:221], s[82:83], 0, v[130:131]
	s_mov_b32 m0, s79
	v_lshl_add_u64 v[222:223], s[70:71], 0, v[132:133]
	global_load_lds_dwordx4 v[220:221], off
	v_lshl_add_u64 v[220:221], s[82:83], 0, v[134:135]
	s_add_i32 m0, s79, 0x2000
	s_nop 0
	global_load_lds_dwordx4 v[220:221], off
	v_lshl_add_u64 v[220:221], s[70:71], 0, v[128:129]
	s_mov_b32 m0, s33
	s_nop 0
	global_load_lds_dwordx4 v[220:221], off
	s_mov_b32 m0, s35
	s_nop 0
	global_load_lds_dwordx4 v[222:223], off
	s_waitcnt vmcnt(8)
	s_waitcnt lgkmcnt(0)
	s_barrier
; #define PG8_STAGE(bufoff, gbase, voff) do { _Pragma("unroll") for (int _i = 0; _i < 2; ++_i) \
;         __builtin_amdgcn_global_load_lds((const unsigned*)((const char*)(gbase) + (voff)[_i]), (PG8_LAS unsigned*)(lds + (bufoff) + ldsw + _i * 8192), 16, 0, 0); } while (0)
; #define PG8_LDA(dst, b, h) do { _Pragma("unroll") for (int m = 0; m < 4; ++m) _Pragma("unroll") for (int k = 0; k < 2; ++k) dst[m][k] = *(const PG8_LAS bf16x8*)(lds + PG8_SA(b, h) + aoff + m * 2048 + k * 1024); } while (0)
; #define PG8_LDB(dst, b, h) do { _Pragma("unroll") for (int n = 0; n < 2; ++n) _Pragma("unroll") for (int k = 0; k < 2; ++k) dst[n][k] = *(const PG8_LAS bf16x8*)(lds + PG8_SB(b, h) + boff + n * 2048 + k * 1024); } while (0)
; #define PG8_MMA(ai, bj, At, Bt) do { __builtin_amdgcn_s_setprio(1); _Pragma("unroll") for (int m = 0; m < 4; ++m) _Pragma("unroll") for (int n = 0; n < 2; ++n) _Pragma("unroll") for (int k = 0; k < 2; ++k) \
;         acc[ai][bj][m][n] = __builtin_amdgcn_mfma_f32_16x16x32_bf16(Bt[n][k], At[m][k], acc[ai][bj][m][n], 0, 0, 0); __builtin_amdgcn_s_setprio(0); } while (0)
; #define PG8_WAIT_V(n) asm volatile("s_waitcnt vmcnt(" #n ")" ::: "memory")
; #define PG8_WAIT_L(n) asm volatile("s_waitcnt lgkmcnt(" #n ")" ::: "memory")
; #define PG8_BAR __builtin_amdgcn_s_barrier()
; #define PG8_SCHED __builtin_amdgcn_sched_barrier(0)
; template <class Epi, class Sched, bool ALIGN_EPI = false, bool SP2 = false>
; __device__ __forceinline__ void gemm_phase(PG8_LAS unsigned char* lds, const Gemm g, const Sched& S, const Epi& E, const int wave_in) {
;     ...
;             PG8_WAIT_V(8); PG8_WAIT_L(0); PG8_BAR; PG8_MMA(1, 0, At, B0); PG8_MMA(1, 1, At, B1); PG8_BAR; PG8_SCHED;
;             PG8_LDB(B0, 1, 0); PG8_LDB(B1, 1, 1); PG8_SCHED; PG8_LDA(At, 1, 0); PG8_STAGE(PG8_SA(0, 1), a2 + hstepA, voffA);
;             PG8_WAIT_V(8); PG8_WAIT_L(0); PG8_BAR; PG8_MMA(0, 0, At, B0); PG8_MMA(0, 1, At, B1); PG8_BAR; PG8_SCHED;
	s_setprio 1
	s_waitcnt lgkmcnt(0)
	v_mfma_f32_16x16x32_bf16 v[60:63], v[144:147], v[184:187], v[60:63]
	v_mfma_f32_16x16x32_bf16 v[56:59], v[160:163], v[184:187], v[56:59]
	v_mfma_f32_16x16x32_bf16 v[44:47], v[144:147], v[192:195], v[44:47]
	v_mfma_f32_16x16x32_bf16 v[40:43], v[160:163], v[192:195], v[40:43]
	v_mfma_f32_16x16x32_bf16 v[28:31], v[144:147], v[200:203], v[28:31]
	v_mfma_f32_16x16x32_bf16 v[24:27], v[160:163], v[200:203], v[24:27]
	v_mfma_f32_16x16x32_bf16 v[12:15], v[144:147], v[208:211], v[12:15]
	v_mfma_f32_16x16x32_bf16 v[8:11], v[160:163], v[208:211], v[8:11]
	v_mfma_f32_16x16x32_bf16 v[60:63], v[156:159], v[188:191], v[60:63]
	v_mfma_f32_16x16x32_bf16 v[56:59], v[164:167], v[188:191], v[56:59]
	v_mfma_f32_16x16x32_bf16 v[44:47], v[156:159], v[196:199], v[44:47]
	v_mfma_f32_16x16x32_bf16 v[40:43], v[164:167], v[196:199], v[40:43]
	v_mfma_f32_16x16x32_bf16 v[28:31], v[156:159], v[204:207], v[28:31]
	v_mfma_f32_16x16x32_bf16 v[24:27], v[164:167], v[204:207], v[24:27]
	v_mfma_f32_16x16x32_bf16 v[12:15], v[156:159], v[212:215], v[12:15]
	v_mfma_f32_16x16x32_bf16 v[8:11], v[164:167], v[212:215], v[8:11]
	s_setprio 0
	s_setprio 1
	v_mfma_f32_16x16x32_bf16 v[52:55], v[168:171], v[184:187], v[52:55]
	v_mfma_f32_16x16x32_bf16 v[48:51], v[176:179], v[184:187], v[48:51]
	v_mfma_f32_16x16x32_bf16 v[36:39], v[168:171], v[192:195], v[36:39]
	v_mfma_f32_16x16x32_bf16 v[32:35], v[176:179], v[192:195], v[32:35]
	v_mfma_f32_16x16x32_bf16 v[20:23], v[168:171], v[200:203], v[20:23]
	v_mfma_f32_16x16x32_bf16 v[16:19], v[176:179], v[200:203], v[16:19]
	v_mfma_f32_16x16x32_bf16 v[4:7], v[168:171], v[208:211], v[4:7]
	v_mfma_f32_16x16x32_bf16 v[0:3], v[176:179], v[208:211], v[0:3]
	v_mfma_f32_16x16x32_bf16 v[52:55], v[172:175], v[188:191], v[52:55]
	v_mfma_f32_16x16x32_bf16 v[48:51], v[180:183], v[188:191], v[48:51]
	v_mfma_f32_16x16x32_bf16 v[36:39], v[172:175], v[196:199], v[36:39]
	v_mfma_f32_16x16x32_bf16 v[32:35], v[180:183], v[196:199], v[32:35]
	v_mfma_f32_16x16x32_bf16 v[20:23], v[172:175], v[204:207], v[20:23]
	v_mfma_f32_16x16x32_bf16 v[16:19], v[180:183], v[204:207], v[16:19]
	v_mfma_f32_16x16x32_bf16 v[4:7], v[172:175], v[212:215], v[4:7]
	v_mfma_f32_16x16x32_bf16 v[0:3], v[180:183], v[212:215], v[0:3]
	s_setprio 0
	s_barrier
	s_add_i32 s79, 0, 0x18000
	v_add_u32_e32 v155, s79, v149
	s_add_i32 s82, 0, 0x1c000
	ds_read_b128 v[144:147], v155
	ds_read_b128 v[156:159], v155 offset:1024
	ds_read_b128 v[160:163], v155 offset:2048
	ds_read_b128 v[164:167], v155 offset:3072
	v_add_u32_e32 v155, s82, v149
	ds_read_b128 v[168:171], v155
	ds_read_b128 v[172:175], v155 offset:1024
	ds_read_b128 v[176:179], v155 offset:2048
	ds_read_b128 v[180:183], v155 offset:3072
	s_add_u32 s70, s70, 0x80000
	s_addc_u32 s71, s71, 0
	s_mov_b32 m0, s50
	v_lshl_add_u64 v[224:225], s[70:71], 0, v[128:129]
	ds_read_b128 v[184:187], v153 offset:32768
	ds_read_b128 v[188:191], v153 offset:33792
	ds_read_b128 v[192:195], v153 offset:34816
	ds_read_b128 v[196:199], v153 offset:35840
	ds_read_b128 v[200:203], v153 offset:36864
	ds_read_b128 v[204:207], v153 offset:37888
	ds_read_b128 v[208:211], v153 offset:38912
	ds_read_b128 v[212:215], v153 offset:39936
	global_load_lds_dwordx4 v[224:225], off
	v_lshl_add_u64 v[224:225], s[70:71], 0, v[132:133]
	s_mov_b32 m0, s51
	s_nop 0
	global_load_lds_dwordx4 v[224:225], off
	s_waitcnt vmcnt(8)
	s_waitcnt lgkmcnt(0)
	s_barrier
	s_setprio 1
	s_waitcnt lgkmcnt(0)
	v_mfma_f32_16x16x32_bf16 v[124:127], v[144:147], v[184:187], v[124:127]
	v_mfma_f32_16x16x32_bf16 v[120:123], v[160:163], v[184:187], v[120:123]
	v_mfma_f32_16x16x32_bf16 v[108:111], v[144:147], v[192:195], v[108:111]
	v_mfma_f32_16x16x32_bf16 v[104:107], v[160:163], v[192:195], v[104:107]
	v_mfma_f32_16x16x32_bf16 v[92:95], v[144:147], v[200:203], v[92:95]
	v_mfma_f32_16x16x32_bf16 v[88:91], v[160:163], v[200:203], v[88:91]
	v_mfma_f32_16x16x32_bf16 v[76:79], v[144:147], v[208:211], v[76:79]
	v_mfma_f32_16x16x32_bf16 v[72:75], v[160:163], v[208:211], v[72:75]
	v_mfma_f32_16x16x32_bf16 v[124:127], v[156:159], v[188:191], v[124:127]
	v_mfma_f32_16x16x32_bf16 v[120:123], v[164:167], v[188:191], v[120:123]
	v_mfma_f32_16x16x32_bf16 v[108:111], v[156:159], v[196:199], v[108:111]
	v_mfma_f32_16x16x32_bf16 v[104:107], v[164:167], v[196:199], v[104:107]
	v_mfma_f32_16x16x32_bf16 v[92:95], v[156:159], v[204:207], v[92:95]
	v_mfma_f32_16x16x32_bf16 v[88:91], v[164:167], v[204:207], v[88:91]
	v_mfma_f32_16x16x32_bf16 v[76:79], v[156:159], v[212:215], v[76:79]
	v_mfma_f32_16x16x32_bf16 v[72:75], v[164:167], v[212:215], v[72:75]
	s_setprio 0
	s_setprio 1
	v_mfma_f32_16x16x32_bf16 v[116:119], v[168:171], v[184:187], v[116:119]
	v_mfma_f32_16x16x32_bf16 v[112:115], v[176:179], v[184:187], v[112:115]
	v_mfma_f32_16x16x32_bf16 v[100:103], v[168:171], v[192:195], v[100:103]
	v_mfma_f32_16x16x32_bf16 v[96:99], v[176:179], v[192:195], v[96:99]
	v_mfma_f32_16x16x32_bf16 v[84:87], v[168:171], v[200:203], v[84:87]
	v_mfma_f32_16x16x32_bf16 v[80:83], v[176:179], v[200:203], v[80:83]
	v_mfma_f32_16x16x32_bf16 v[68:71], v[168:171], v[208:211], v[68:71]
	v_mfma_f32_16x16x32_bf16 v[64:67], v[176:179], v[208:211], v[64:67]
	v_mfma_f32_16x16x32_bf16 v[116:119], v[172:175], v[188:191], v[116:119]
	v_mfma_f32_16x16x32_bf16 v[112:115], v[180:183], v[188:191], v[112:115]
	v_mfma_f32_16x16x32_bf16 v[100:103], v[172:175], v[196:199], v[100:103]
	v_mfma_f32_16x16x32_bf16 v[96:99], v[180:183], v[196:199], v[96:99]
	v_mfma_f32_16x16x32_bf16 v[84:87], v[172:175], v[204:207], v[84:87]
	v_mfma_f32_16x16x32_bf16 v[80:83], v[180:183], v[204:207], v[80:83]
	v_mfma_f32_16x16x32_bf16 v[68:71], v[172:175], v[212:215], v[68:71]
	v_mfma_f32_16x16x32_bf16 v[64:67], v[180:183], v[212:215], v[64:67]
	s_setprio 0
	s_barrier
; #define PG8_STAGE(bufoff, gbase, voff) do { _Pragma("unroll") for (int _i = 0; _i < 2; ++_i) \
;         __builtin_amdgcn_global_load_lds((const unsigned*)((const char*)(gbase) + (voff)[_i]), (PG8_LAS unsigned*)(lds + (bufoff) + ldsw + _i * 8192), 16, 0, 0); } while (0)
; #define PG8_LDA(dst, b, h) do { _Pragma("unroll") for (int m = 0; m < 4; ++m) _Pragma("unroll") for (int k = 0; k < 2; ++k) dst[m][k] = *(const PG8_LAS bf16x8*)(lds + PG8_SA(b, h) + aoff + m * 2048 + k * 1024); } while (0)
; #define PG8_MMA(ai, bj, At, Bt) do { __builtin_amdgcn_s_setprio(1); _Pragma("unroll") for (int m = 0; m < 4; ++m) _Pragma("unroll") for (int n = 0; n < 2; ++n) _Pragma("unroll") for (int k = 0; k < 2; ++k) \
;         acc[ai][bj][m][n] = __builtin_amdgcn_mfma_f32_16x16x32_bf16(Bt[n][k], At[m][k], acc[ai][bj][m][n], 0, 0, 0); __builtin_amdgcn_s_setprio(0); } while (0)
; #define PG8_WAIT_V(n) asm volatile("s_waitcnt vmcnt(" #n ")" ::: "memory")
; #define PG8_WAIT_L(n) asm volatile("s_waitcnt lgkmcnt(" #n ")" ::: "memory")
; #define PG8_BAR __builtin_amdgcn_s_barrier()
; #define PG8_SCHED __builtin_amdgcn_sched_barrier(0)
; template <class Epi, class Sched, bool ALIGN_EPI = false, bool SP2 = false>
; __device__ __forceinline__ void gemm_phase(PG8_LAS unsigned char* lds, const Gemm g, const Sched& S, const Epi& E, const int wave_in) {
;     ...
;         for (int t = 0; t < nt; t += 2) {
;             const bool last = (t == nt - 2);
;             const char* a1 = cA + (size_t)(t + 1) * kstep;
;             const char* a2 = last ? nA : cA + (size_t)(t + 2) * kstep; const char* b2 = last ? nB : cB + (size_t)(t + 2) * kstep;
;             const char* a3 = a2 + kstep; const char* b3 = b2 + kstep;
;     ...
;             PG8_LDA(At, 1, 1); PG8_STAGE(PG8_SB(1, 0), b3, voffB); PG8_STAGE(PG8_SB(1, 1), b3 + hstep, voffB); PG8_STAGE(PG8_SA(1, 0), a3, voffA);
;             PG8_WAIT_V(8); PG8_WAIT_L(0); PG8_BAR; PG8_MMA(1, 0, At, B0); PG8_MMA(1, 1, At, B1); PG8_BAR; PG8_SCHED;
	s_add_i32 s70, s79, s11
	v_lshl_add_u64 v[216:217], v[216:217], 0, s[18:19]
	s_mov_b32 m0, s70
	ds_read_b128 v[184:187], v153 offset:49152
	ds_read_b128 v[188:191], v153 offset:50176
	ds_read_b128 v[192:195], v153 offset:51200
	ds_read_b128 v[196:199], v153 offset:52224
	ds_read_b128 v[200:203], v153 offset:53248
	ds_read_b128 v[204:207], v153 offset:54272
	ds_read_b128 v[208:211], v153 offset:55296
	ds_read_b128 v[212:215], v153 offset:56320
	global_load_lds_dwordx4 v[216:217], off
	s_add_i32 m0, s70, 0x2000
	s_add_u32 s68, s68, 0x80080
	v_lshl_add_u64 v[216:217], v[218:219], 0, s[18:19]
	s_addc_u32 s69, s69, 0
	s_add_i32 s70, s82, s11
	global_load_lds_dwordx4 v[216:217], off
	v_lshl_add_u64 v[216:217], s[68:69], 0, v[130:131]
	s_mov_b32 m0, s70
	s_nop 0
	global_load_lds_dwordx4 v[216:217], off
	v_lshl_add_u64 v[216:217], s[68:69], 0, v[134:135]
	s_add_i32 m0, s70, 0x2000
	s_nop 0
	global_load_lds_dwordx4 v[216:217], off
	v_lshl_add_u64 v[216:217], v[220:221], 0, s[18:19]
	s_mov_b32 m0, s65
	s_nop 0
	global_load_lds_dwordx4 v[216:217], off
	v_lshl_add_u64 v[216:217], v[222:223], 0, s[18:19]
	s_mov_b32 m0, s72
	s_nop 0
	global_load_lds_dwordx4 v[216:217], off
	s_waitcnt vmcnt(8)
	s_waitcnt lgkmcnt(0)
	s_barrier
	s_setprio 1
	s_waitcnt lgkmcnt(0)
	v_mfma_f32_16x16x32_bf16 v[60:63], v[144:147], v[184:187], v[60:63]
	v_mfma_f32_16x16x32_bf16 v[56:59], v[160:163], v[184:187], v[56:59]
	v_mfma_f32_16x16x32_bf16 v[44:47], v[144:147], v[192:195], v[44:47]
	v_mfma_f32_16x16x32_bf16 v[40:43], v[160:163], v[192:195], v[40:43]
	v_mfma_f32_16x16x32_bf16 v[28:31], v[144:147], v[200:203], v[28:31]
	v_mfma_f32_16x16x32_bf16 v[24:27], v[160:163], v[200:203], v[24:27]
	v_mfma_f32_16x16x32_bf16 v[12:15], v[144:147], v[208:211], v[12:15]
	v_mfma_f32_16x16x32_bf16 v[8:11], v[160:163], v[208:211], v[8:11]
	v_mfma_f32_16x16x32_bf16 v[60:63], v[156:159], v[188:191], v[60:63]
	v_mfma_f32_16x16x32_bf16 v[56:59], v[164:167], v[188:191], v[56:59]
	v_mfma_f32_16x16x32_bf16 v[44:47], v[156:159], v[196:199], v[44:47]
	v_mfma_f32_16x16x32_bf16 v[40:43], v[164:167], v[196:199], v[40:43]
	v_mfma_f32_16x16x32_bf16 v[28:31], v[156:159], v[204:207], v[28:31]
	v_mfma_f32_16x16x32_bf16 v[24:27], v[164:167], v[204:207], v[24:27]
	v_mfma_f32_16x16x32_bf16 v[12:15], v[156:159], v[212:215], v[12:15]
	v_mfma_f32_16x16x32_bf16 v[8:11], v[164:167], v[212:215], v[8:11]
	s_setprio 0
	s_setprio 1
	v_mfma_f32_16x16x32_bf16 v[52:55], v[168:171], v[184:187], v[52:55]
	v_mfma_f32_16x16x32_bf16 v[48:51], v[176:179], v[184:187], v[48:51]
	v_mfma_f32_16x16x32_bf16 v[36:39], v[168:171], v[192:195], v[36:39]
	v_mfma_f32_16x16x32_bf16 v[32:35], v[176:179], v[192:195], v[32:35]
	v_mfma_f32_16x16x32_bf16 v[20:23], v[168:171], v[200:203], v[20:23]
	v_mfma_f32_16x16x32_bf16 v[16:19], v[176:179], v[200:203], v[16:19]
	v_mfma_f32_16x16x32_bf16 v[4:7], v[168:171], v[208:211], v[4:7]
	v_mfma_f32_16x16x32_bf16 v[0:3], v[176:179], v[208:211], v[0:3]
	v_mfma_f32_16x16x32_bf16 v[52:55], v[172:175], v[188:191], v[52:55]
	v_mfma_f32_16x16x32_bf16 v[48:51], v[180:183], v[188:191], v[48:51]
	v_mfma_f32_16x16x32_bf16 v[36:39], v[172:175], v[196:199], v[36:39]
	v_mfma_f32_16x16x32_bf16 v[32:35], v[180:183], v[196:199], v[32:35]
	v_mfma_f32_16x16x32_bf16 v[20:23], v[172:175], v[204:207], v[20:23]
	v_mfma_f32_16x16x32_bf16 v[16:19], v[180:183], v[204:207], v[16:19]
	v_mfma_f32_16x16x32_bf16 v[4:7], v[172:175], v[212:215], v[4:7]
	v_mfma_f32_16x16x32_bf16 v[0:3], v[180:183], v[212:215], v[0:3]
	s_setprio 0
	s_add_i32 s78, s78, 2
	s_add_u32 s66, s66, 0x100
	s_addc_u32 s67, s67, 0
	s_add_u32 s76, s76, 0x100
	s_addc_u32 s77, s77, 0
	s_cmp_gt_u32 s78, 29
	s_barrier
	s_cbranch_scc0 .LBB0_1303
	s_and_b64 vcc, exec, s[38:39]
	s_cbranch_vccz .LBB0_1306
	s_barrier

; #define PG8_STAGE(bufoff, gbase, voff) do { _Pragma("unroll") for (int _i = 0; _i < 2; ++_i) \
;         __builtin_amdgcn_global_load_lds((const unsigned*)((const char*)(gbase) + (voff)[_i]), (PG8_LAS unsigned*)(lds + (bufoff) + ldsw + _i * 8192), 16, 0, 0); } while (0)
; #define PG8_LDA(dst, b, h) do { _Pragma("unroll") for (int m = 0; m < 4; ++m) _Pragma("unroll") for (int k = 0; k < 2; ++k) dst[m][k] = *(const PG8_LAS bf16x8*)(lds + PG8_SA(b, h) + aoff + m * 2048 + k * 1024); } while (0)
; #define PG8_LDB(dst, b, h) do { _Pragma("unroll") for (int n = 0; n < 2; ++n) _Pragma("unroll") for (int k = 0; k < 2; ++k) dst[n][k] = *(const PG8_LAS bf16x8*)(lds + PG8_SB(b, h) + boff + n * 2048 + k * 1024); } while (0)
; #define PG8_MMA(ai, bj, At, Bt) do { __builtin_amdgcn_s_setprio(1); _Pragma("unroll") for (int m = 0; m < 4; ++m) _Pragma("unroll") for (int n = 0; n < 2; ++n) _Pragma("unroll") for (int k = 0; k < 2; ++k) \
;         acc[ai][bj][m][n] = __builtin_amdgcn_mfma_f32_16x16x32_bf16(Bt[n][k], At[m][k], acc[ai][bj][m][n], 0, 0, 0); __builtin_amdgcn_s_setprio(0); } while (0)
; #define PG8_WAIT_V(n) asm volatile("s_waitcnt vmcnt(" #n ")" ::: "memory")
; #define PG8_WAIT_L(n) asm volatile("s_waitcnt lgkmcnt(" #n ")" ::: "memory")
; #define PG8_BAR __builtin_amdgcn_s_barrier()
; template <class Epi, class Sched, bool ALIGN_EPI = false, bool SP2 = false>
; __device__ __forceinline__ void gemm_phase(PG8_LAS unsigned char* lds, const Gemm g, const Sched& S, const Epi& E, const int wave_in) {
;     ...
;         for (int t = 0; t < nt; t += 2) {
;             const bool last = (t == nt - 2);
;             const char* a1 = cA + (size_t)(t + 1) * kstep;
;             const char* a2 = last ? nA : cA + (size_t)(t + 2) * kstep; const char* b2 = last ? nB : cB + (size_t)(t + 2) * kstep;
;             const char* a3 = a2 + kstep; const char* b3 = b2 + kstep;
;             if (last && has_next) S.a_ready(nxt);
;             if constexpr (SP2) {
;             PG8_LDB(B0, 0, 0); PG8_LDB(B1, 0, 1); PG8_SCHED; PG8_LDA(At, 0, 0); PG8_STAGE(PG8_SA(1, 1), a1 + hstepA, voffA);
;             PG8_WAIT_V(8); PG8_WAIT_L(0); PG8_BAR; PG8_MMA(0, 0, At, B0); PG8_MMA(0, 1, At, B1); PG8_BAR; PG8_SCHED;
;             PG8_LDA(At, 0, 1); PG8_STAGE(PG8_SB(0, 0), b2, voffB); PG8_STAGE(PG8_SB(0, 1), b2 + hstep, voffB); PG8_STAGE(PG8_SA(0, 0), a2, voffA);
.LBB0_1390:
	ds_read_b128 v[144:147], v151
	ds_read_b128 v[156:159], v151 offset:1024
	ds_read_b128 v[160:163], v151 offset:2048
	ds_read_b128 v[164:167], v151 offset:3072
	ds_read_b128 v[168:171], v152
	ds_read_b128 v[172:175], v152 offset:1024
	ds_read_b128 v[176:179], v152 offset:2048
	ds_read_b128 v[180:183], v152 offset:3072
	s_add_u32 s64, s62, 0xfff80080
	s_addc_u32 s65, s63, -1
	s_cmp_eq_u32 s78, 28
	s_cselect_b32 s67, s41, s65
	s_cselect_b32 s66, s74, s64
	s_cselect_b32 s65, s39, s77
	s_cselect_b32 s64, s75, s76
	v_lshl_add_u64 v[216:217], s[62:63], 0, v[136:137]
	s_add_i32 m0, s48, 0xc000
	ds_read_b128 v[184:187], v153
	ds_read_b128 v[188:191], v153 offset:1024
	ds_read_b128 v[192:195], v153 offset:2048
	ds_read_b128 v[196:199], v153 offset:3072
	ds_read_b128 v[200:203], v153 offset:4096
	ds_read_b128 v[204:207], v153 offset:5120
	ds_read_b128 v[208:211], v153 offset:6144
	ds_read_b128 v[212:215], v153 offset:7168
	global_load_lds_dwordx4 v[216:217], off
	v_lshl_add_u64 v[216:217], s[62:63], 0, v[138:139]
	s_add_i32 m0, s48, 0xe000
	s_nop 0
	global_load_lds_dwordx4 v[216:217], off
	s_waitcnt vmcnt(8)
	s_waitcnt lgkmcnt(0)
	s_barrier
	s_setprio 1
	s_waitcnt lgkmcnt(0)
	v_mfma_f32_16x16x32_bf16 v[116:119], v[144:147], v[184:187], v[116:119]
	v_mfma_f32_16x16x32_bf16 v[112:115], v[160:163], v[184:187], v[112:115]
	v_mfma_f32_16x16x32_bf16 v[100:103], v[144:147], v[192:195], v[100:103]
	v_mfma_f32_16x16x32_bf16 v[96:99], v[160:163], v[192:195], v[96:99]
	v_mfma_f32_16x16x32_bf16 v[84:87], v[144:147], v[200:203], v[84:87]
	v_mfma_f32_16x16x32_bf16 v[80:83], v[160:163], v[200:203], v[80:83]
	v_mfma_f32_16x16x32_bf16 v[68:71], v[144:147], v[208:211], v[68:71]
	v_mfma_f32_16x16x32_bf16 v[64:67], v[160:163], v[208:211], v[64:67]
	v_mfma_f32_16x16x32_bf16 v[116:119], v[156:159], v[188:191], v[116:119]
	v_mfma_f32_16x16x32_bf16 v[112:115], v[164:167], v[188:191], v[112:115]
	v_mfma_f32_16x16x32_bf16 v[100:103], v[156:159], v[196:199], v[100:103]
	v_mfma_f32_16x16x32_bf16 v[96:99], v[164:167], v[196:199], v[96:99]
	v_mfma_f32_16x16x32_bf16 v[84:87], v[156:159], v[204:207], v[84:87]
	v_mfma_f32_16x16x32_bf16 v[80:83], v[164:167], v[204:207], v[80:83]
	v_mfma_f32_16x16x32_bf16 v[68:71], v[156:159], v[212:215], v[68:71]
	v_mfma_f32_16x16x32_bf16 v[64:67], v[164:167], v[212:215], v[64:67]
	s_setprio 0
	s_setprio 1
	v_mfma_f32_16x16x32_bf16 v[124:127], v[168:171], v[184:187], v[124:127]
	v_mfma_f32_16x16x32_bf16 v[120:123], v[176:179], v[184:187], v[120:123]
	v_mfma_f32_16x16x32_bf16 v[108:111], v[168:171], v[192:195], v[108:111]
	v_mfma_f32_16x16x32_bf16 v[104:107], v[176:179], v[192:195], v[104:107]
	v_mfma_f32_16x16x32_bf16 v[92:95], v[168:171], v[200:203], v[92:95]
	v_mfma_f32_16x16x32_bf16 v[88:91], v[176:179], v[200:203], v[88:91]
	v_mfma_f32_16x16x32_bf16 v[76:79], v[168:171], v[208:211], v[76:79]
	v_mfma_f32_16x16x32_bf16 v[72:75], v[176:179], v[208:211], v[72:75]
	v_mfma_f32_16x16x32_bf16 v[124:127], v[172:175], v[188:191], v[124:127]
	v_mfma_f32_16x16x32_bf16 v[120:123], v[180:183], v[188:191], v[120:123]
	v_mfma_f32_16x16x32_bf16 v[108:111], v[172:175], v[196:199], v[108:111]
	v_mfma_f32_16x16x32_bf16 v[104:107], v[180:183], v[196:199], v[104:107]
	v_mfma_f32_16x16x32_bf16 v[92:95], v[172:175], v[204:207], v[92:95]
	v_mfma_f32_16x16x32_bf16 v[88:91], v[180:183], v[204:207], v[88:91]
	v_mfma_f32_16x16x32_bf16 v[76:79], v[172:175], v[212:215], v[76:79]
	v_mfma_f32_16x16x32_bf16 v[72:75], v[180:183], v[212:215], v[72:75]
	s_setprio 0
	s_barrier
	s_add_i32 s79, s70, s11
	v_lshl_add_u64 v[216:217], s[64:65], 0, v[132:133]
	s_mov_b32 m0, s79
	ds_read_b128 v[184:187], v153 offset:16384
	ds_read_b128 v[188:191], v153 offset:17408
	ds_read_b128 v[192:195], v153 offset:18432
	ds_read_b128 v[196:199], v153 offset:19456
	ds_read_b128 v[200:203], v153 offset:20480
	ds_read_b128 v[204:207], v153 offset:21504
	ds_read_b128 v[208:211], v153 offset:22528
	ds_read_b128 v[212:215], v153 offset:23552
	global_load_lds_dwordx4 v[216:217], off
	s_add_i32 m0, s79, 0x2000
	s_add_u32 s80, s64, 0x80000
	v_lshl_add_u64 v[218:219], s[64:65], 0, v[128:129]
	s_addc_u32 s81, s65, 0
	s_add_i32 s79, s71, s11
	global_load_lds_dwordx4 v[218:219], off
	v_lshl_add_u64 v[220:221], s[80:81], 0, v[132:133]
	s_mov_b32 m0, s79
	v_lshl_add_u64 v[222:223], s[66:67], 0, v[130:131]
	global_load_lds_dwordx4 v[220:221], off
	v_lshl_add_u64 v[220:221], s[80:81], 0, v[128:129]
	s_add_i32 m0, s79, 0x2000
	s_nop 0
	global_load_lds_dwordx4 v[220:221], off
	v_lshl_add_u64 v[220:221], s[66:67], 0, v[134:135]
	s_mov_b32 m0, s48
	s_nop 0
	global_load_lds_dwordx4 v[220:221], off
	s_mov_b32 m0, s49
	s_nop 0
	global_load_lds_dwordx4 v[222:223], off
	s_waitcnt vmcnt(8)
	s_waitcnt lgkmcnt(0)
	s_barrier
; #define PG8_STAGE(bufoff, gbase, voff) do { _Pragma("unroll") for (int _i = 0; _i < 2; ++_i) \
;         __builtin_amdgcn_global_load_lds((const unsigned*)((const char*)(gbase) + (voff)[_i]), (PG8_LAS unsigned*)(lds + (bufoff) + ldsw + _i * 8192), 16, 0, 0); } while (0)
; #define PG8_LDA(dst, b, h) do { _Pragma("unroll") for (int m = 0; m < 4; ++m) _Pragma("unroll") for (int k = 0; k < 2; ++k) dst[m][k] = *(const PG8_LAS bf16x8*)(lds + PG8_SA(b, h) + aoff + m * 2048 + k * 1024); } while (0)
; #define PG8_LDB(dst, b, h) do { _Pragma("unroll") for (int n = 0; n < 2; ++n) _Pragma("unroll") for (int k = 0; k < 2; ++k) dst[n][k] = *(const PG8_LAS bf16x8*)(lds + PG8_SB(b, h) + boff + n * 2048 + k * 1024); } while (0)
; #define PG8_MMA(ai, bj, At, Bt) do { __builtin_amdgcn_s_setprio(1); _Pragma("unroll") for (int m = 0; m < 4; ++m) _Pragma("unroll") for (int n = 0; n < 2; ++n) _Pragma("unroll") for (int k = 0; k < 2; ++k) \
;         acc[ai][bj][m][n] = __builtin_amdgcn_mfma_f32_16x16x32_bf16(Bt[n][k], At[m][k], acc[ai][bj][m][n], 0, 0, 0); __builtin_amdgcn_s_setprio(0); } while (0)
; #define PG8_WAIT_V(n) asm volatile("s_waitcnt vmcnt(" #n ")" ::: "memory")
; #define PG8_WAIT_L(n) asm volatile("s_waitcnt lgkmcnt(" #n ")" ::: "memory")
; #define PG8_BAR __builtin_amdgcn_s_barrier()
; #define PG8_SCHED __builtin_amdgcn_sched_barrier(0)
; template <class Epi, class Sched, bool ALIGN_EPI = false, bool SP2 = false>
; __device__ __forceinline__ void gemm_phase(PG8_LAS unsigned char* lds, const Gemm g, const Sched& S, const Epi& E, const int wave_in) {
;     ...
;             PG8_WAIT_V(8); PG8_WAIT_L(0); PG8_BAR; PG8_MMA(1, 0, At, B0); PG8_MMA(1, 1, At, B1); PG8_BAR; PG8_SCHED;
;             PG8_LDB(B0, 1, 0); PG8_LDB(B1, 1, 1); PG8_SCHED; PG8_LDA(At, 1, 0); PG8_STAGE(PG8_SA(0, 1), a2 + hstepA, voffA);
;             PG8_WAIT_V(8); PG8_WAIT_L(0); PG8_BAR; PG8_MMA(0, 0, At, B0); PG8_MMA(0, 1, At, B1); PG8_BAR; PG8_SCHED;
	s_setprio 1
	s_waitcnt lgkmcnt(0)
	v_mfma_f32_16x16x32_bf16 v[52:55], v[144:147], v[184:187], v[52:55]
	v_mfma_f32_16x16x32_bf16 v[48:51], v[160:163], v[184:187], v[48:51]
	v_mfma_f32_16x16x32_bf16 v[36:39], v[144:147], v[192:195], v[36:39]
	v_mfma_f32_16x16x32_bf16 v[32:35], v[160:163], v[192:195], v[32:35]
	v_mfma_f32_16x16x32_bf16 v[20:23], v[144:147], v[200:203], v[20:23]
	v_mfma_f32_16x16x32_bf16 v[16:19], v[160:163], v[200:203], v[16:19]
	v_mfma_f32_16x16x32_bf16 v[4:7], v[144:147], v[208:211], v[4:7]
	v_mfma_f32_16x16x32_bf16 v[0:3], v[160:163], v[208:211], v[0:3]
	v_mfma_f32_16x16x32_bf16 v[52:55], v[156:159], v[188:191], v[52:55]
	v_mfma_f32_16x16x32_bf16 v[48:51], v[164:167], v[188:191], v[48:51]
	v_mfma_f32_16x16x32_bf16 v[36:39], v[156:159], v[196:199], v[36:39]
	v_mfma_f32_16x16x32_bf16 v[32:35], v[164:167], v[196:199], v[32:35]
	v_mfma_f32_16x16x32_bf16 v[20:23], v[156:159], v[204:207], v[20:23]
	v_mfma_f32_16x16x32_bf16 v[16:19], v[164:167], v[204:207], v[16:19]
	v_mfma_f32_16x16x32_bf16 v[4:7], v[156:159], v[212:215], v[4:7]
	v_mfma_f32_16x16x32_bf16 v[0:3], v[164:167], v[212:215], v[0:3]
	s_setprio 0
	s_setprio 1
	v_mfma_f32_16x16x32_bf16 v[60:63], v[168:171], v[184:187], v[60:63]
	v_mfma_f32_16x16x32_bf16 v[56:59], v[176:179], v[184:187], v[56:59]
	v_mfma_f32_16x16x32_bf16 v[44:47], v[168:171], v[192:195], v[44:47]
	v_mfma_f32_16x16x32_bf16 v[40:43], v[176:179], v[192:195], v[40:43]
	v_mfma_f32_16x16x32_bf16 v[28:31], v[168:171], v[200:203], v[28:31]
	v_mfma_f32_16x16x32_bf16 v[24:27], v[176:179], v[200:203], v[24:27]
	v_mfma_f32_16x16x32_bf16 v[12:15], v[168:171], v[208:211], v[12:15]
	v_mfma_f32_16x16x32_bf16 v[8:11], v[176:179], v[208:211], v[8:11]
	v_mfma_f32_16x16x32_bf16 v[60:63], v[172:175], v[188:191], v[60:63]
	v_mfma_f32_16x16x32_bf16 v[56:59], v[180:183], v[188:191], v[56:59]
	v_mfma_f32_16x16x32_bf16 v[44:47], v[172:175], v[196:199], v[44:47]
	v_mfma_f32_16x16x32_bf16 v[40:43], v[180:183], v[196:199], v[40:43]
	v_mfma_f32_16x16x32_bf16 v[28:31], v[172:175], v[204:207], v[28:31]
	v_mfma_f32_16x16x32_bf16 v[24:27], v[180:183], v[204:207], v[24:27]
	v_mfma_f32_16x16x32_bf16 v[12:15], v[172:175], v[212:215], v[12:15]
	v_mfma_f32_16x16x32_bf16 v[8:11], v[180:183], v[212:215], v[8:11]
	s_setprio 0
	s_barrier
	s_add_i32 s79, 0, 0x18000
	v_add_u32_e32 v155, s79, v149
	s_add_i32 s80, 0, 0x1c000
	ds_read_b128 v[144:147], v155
	ds_read_b128 v[156:159], v155 offset:1024
	ds_read_b128 v[160:163], v155 offset:2048
	ds_read_b128 v[164:167], v155 offset:3072
	v_add_u32_e32 v155, s80, v149
	ds_read_b128 v[168:171], v155
	ds_read_b128 v[172:175], v155 offset:1024
	ds_read_b128 v[176:179], v155 offset:2048
	ds_read_b128 v[180:183], v155 offset:3072
	s_add_u32 s66, s66, 0x80000
	s_addc_u32 s67, s67, 0
	s_mov_b32 m0, s50
	v_lshl_add_u64 v[224:225], s[66:67], 0, v[134:135]
	ds_read_b128 v[184:187], v153 offset:32768
	ds_read_b128 v[188:191], v153 offset:33792
	ds_read_b128 v[192:195], v153 offset:34816
	ds_read_b128 v[196:199], v153 offset:35840
	ds_read_b128 v[200:203], v153 offset:36864
	ds_read_b128 v[204:207], v153 offset:37888
	ds_read_b128 v[208:211], v153 offset:38912
	ds_read_b128 v[212:215], v153 offset:39936
	global_load_lds_dwordx4 v[224:225], off
	v_lshl_add_u64 v[224:225], s[66:67], 0, v[130:131]
	s_mov_b32 m0, s51
	s_nop 0
	global_load_lds_dwordx4 v[224:225], off
	s_waitcnt vmcnt(8)
	s_waitcnt lgkmcnt(0)
	s_barrier
	s_setprio 1
	s_waitcnt lgkmcnt(0)
	v_mfma_f32_16x16x32_bf16 v[116:119], v[144:147], v[184:187], v[116:119]
	v_mfma_f32_16x16x32_bf16 v[112:115], v[160:163], v[184:187], v[112:115]
	v_mfma_f32_16x16x32_bf16 v[100:103], v[144:147], v[192:195], v[100:103]
	v_mfma_f32_16x16x32_bf16 v[96:99], v[160:163], v[192:195], v[96:99]
	v_mfma_f32_16x16x32_bf16 v[84:87], v[144:147], v[200:203], v[84:87]
	v_mfma_f32_16x16x32_bf16 v[80:83], v[160:163], v[200:203], v[80:83]
	v_mfma_f32_16x16x32_bf16 v[68:71], v[144:147], v[208:211], v[68:71]
	v_mfma_f32_16x16x32_bf16 v[64:67], v[160:163], v[208:211], v[64:67]
	v_mfma_f32_16x16x32_bf16 v[116:119], v[156:159], v[188:191], v[116:119]
	v_mfma_f32_16x16x32_bf16 v[112:115], v[164:167], v[188:191], v[112:115]
	v_mfma_f32_16x16x32_bf16 v[100:103], v[156:159], v[196:199], v[100:103]
	v_mfma_f32_16x16x32_bf16 v[96:99], v[164:167], v[196:199], v[96:99]
	v_mfma_f32_16x16x32_bf16 v[84:87], v[156:159], v[204:207], v[84:87]
	v_mfma_f32_16x16x32_bf16 v[80:83], v[164:167], v[204:207], v[80:83]
	v_mfma_f32_16x16x32_bf16 v[68:71], v[156:159], v[212:215], v[68:71]
	v_mfma_f32_16x16x32_bf16 v[64:67], v[164:167], v[212:215], v[64:67]
	s_setprio 0
	s_setprio 1
	v_mfma_f32_16x16x32_bf16 v[124:127], v[168:171], v[184:187], v[124:127]
	v_mfma_f32_16x16x32_bf16 v[120:123], v[176:179], v[184:187], v[120:123]
	v_mfma_f32_16x16x32_bf16 v[108:111], v[168:171], v[192:195], v[108:111]
	v_mfma_f32_16x16x32_bf16 v[104:107], v[176:179], v[192:195], v[104:107]
	v_mfma_f32_16x16x32_bf16 v[92:95], v[168:171], v[200:203], v[92:95]
	v_mfma_f32_16x16x32_bf16 v[88:91], v[176:179], v[200:203], v[88:91]
	v_mfma_f32_16x16x32_bf16 v[76:79], v[168:171], v[208:211], v[76:79]
	v_mfma_f32_16x16x32_bf16 v[72:75], v[176:179], v[208:211], v[72:75]
	v_mfma_f32_16x16x32_bf16 v[124:127], v[172:175], v[188:191], v[124:127]
	v_mfma_f32_16x16x32_bf16 v[120:123], v[180:183], v[188:191], v[120:123]
	v_mfma_f32_16x16x32_bf16 v[108:111], v[172:175], v[196:199], v[108:111]
	v_mfma_f32_16x16x32_bf16 v[104:107], v[180:183], v[196:199], v[104:107]
	v_mfma_f32_16x16x32_bf16 v[92:95], v[172:175], v[204:207], v[92:95]
	v_mfma_f32_16x16x32_bf16 v[88:91], v[180:183], v[204:207], v[88:91]
	v_mfma_f32_16x16x32_bf16 v[76:79], v[172:175], v[212:215], v[76:79]
	v_mfma_f32_16x16x32_bf16 v[72:75], v[180:183], v[212:215], v[72:75]
	s_setprio 0
	s_barrier
; #define PG8_STAGE(bufoff, gbase, voff) do { _Pragma("unroll") for (int _i = 0; _i < 2; ++_i) \
;         __builtin_amdgcn_global_load_lds((const unsigned*)((const char*)(gbase) + (voff)[_i]), (PG8_LAS unsigned*)(lds + (bufoff) + ldsw + _i * 8192), 16, 0, 0); } while (0)
; #define PG8_LDA(dst, b, h) do { _Pragma("unroll") for (int m = 0; m < 4; ++m) _Pragma("unroll") for (int k = 0; k < 2; ++k) dst[m][k] = *(const PG8_LAS bf16x8*)(lds + PG8_SA(b, h) + aoff + m * 2048 + k * 1024); } while (0)
; #define PG8_MMA(ai, bj, At, Bt) do { __builtin_amdgcn_s_setprio(1); _Pragma("unroll") for (int m = 0; m < 4; ++m) _Pragma("unroll") for (int n = 0; n < 2; ++n) _Pragma("unroll") for (int k = 0; k < 2; ++k) \
;         acc[ai][bj][m][n] = __builtin_amdgcn_mfma_f32_16x16x32_bf16(Bt[n][k], At[m][k], acc[ai][bj][m][n], 0, 0, 0); __builtin_amdgcn_s_setprio(0); } while (0)
; #define PG8_WAIT_V(n) asm volatile("s_waitcnt vmcnt(" #n ")" ::: "memory")
; #define PG8_WAIT_L(n) asm volatile("s_waitcnt lgkmcnt(" #n ")" ::: "memory")
; #define PG8_BAR __builtin_amdgcn_s_barrier()
; #define PG8_SCHED __builtin_amdgcn_sched_barrier(0)
; template <class Epi, class Sched, bool ALIGN_EPI = false, bool SP2 = false>
; __device__ __forceinline__ void gemm_phase(PG8_LAS unsigned char* lds, const Gemm g, const Sched& S, const Epi& E, const int wave_in) {
;     ...
;         for (int t = 0; t < nt; t += 2) {
;             const bool last = (t == nt - 2);
;             const char* a1 = cA + (size_t)(t + 1) * kstep;
;             const char* a2 = last ? nA : cA + (size_t)(t + 2) * kstep; const char* b2 = last ? nB : cB + (size_t)(t + 2) * kstep;
;             const char* a3 = a2 + kstep; const char* b3 = b2 + kstep;
;     ...
;             PG8_LDA(At, 1, 1); PG8_STAGE(PG8_SB(1, 0), b3, voffB); PG8_STAGE(PG8_SB(1, 1), b3 + hstep, voffB); PG8_STAGE(PG8_SA(1, 0), a3, voffA);
;             PG8_WAIT_V(8); PG8_WAIT_L(0); PG8_BAR; PG8_MMA(1, 0, At, B0); PG8_MMA(1, 1, At, B1); PG8_BAR; PG8_SCHED;
	s_add_i32 s66, s79, s11
	v_lshl_add_u64 v[216:217], v[216:217], 0, s[6:7]
	s_mov_b32 m0, s66
	ds_read_b128 v[184:187], v153 offset:49152
	ds_read_b128 v[188:191], v153 offset:50176
	ds_read_b128 v[192:195], v153 offset:51200
	ds_read_b128 v[196:199], v153 offset:52224
	ds_read_b128 v[200:203], v153 offset:53248
	ds_read_b128 v[204:207], v153 offset:54272
	ds_read_b128 v[208:211], v153 offset:55296
	ds_read_b128 v[212:215], v153 offset:56320
	global_load_lds_dwordx4 v[216:217], off
	s_add_i32 m0, s66, 0x2000
	s_add_u32 s64, s64, 0x80080
	v_lshl_add_u64 v[216:217], v[218:219], 0, s[6:7]
	s_addc_u32 s65, s65, 0
	s_add_i32 s66, s80, s11
	global_load_lds_dwordx4 v[216:217], off
	v_lshl_add_u64 v[216:217], s[64:65], 0, v[132:133]
	s_mov_b32 m0, s66
	s_nop 0
	global_load_lds_dwordx4 v[216:217], off
	v_lshl_add_u64 v[216:217], s[64:65], 0, v[128:129]
	s_add_i32 m0, s66, 0x2000
	s_nop 0
	global_load_lds_dwordx4 v[216:217], off
	v_lshl_add_u64 v[216:217], v[220:221], 0, s[6:7]
	s_mov_b32 m0, s68
	s_nop 0
	global_load_lds_dwordx4 v[216:217], off
	v_lshl_add_u64 v[216:217], v[222:223], 0, s[6:7]
	s_mov_b32 m0, s69
	s_nop 0
	global_load_lds_dwordx4 v[216:217], off
	s_waitcnt vmcnt(8)
	s_waitcnt lgkmcnt(0)
	s_barrier
	s_setprio 1
	s_waitcnt lgkmcnt(0)
	v_mfma_f32_16x16x32_bf16 v[52:55], v[144:147], v[184:187], v[52:55]
	v_mfma_f32_16x16x32_bf16 v[48:51], v[160:163], v[184:187], v[48:51]
	v_mfma_f32_16x16x32_bf16 v[36:39], v[144:147], v[192:195], v[36:39]
	v_mfma_f32_16x16x32_bf16 v[32:35], v[160:163], v[192:195], v[32:35]
	v_mfma_f32_16x16x32_bf16 v[20:23], v[144:147], v[200:203], v[20:23]
	v_mfma_f32_16x16x32_bf16 v[16:19], v[160:163], v[200:203], v[16:19]
	v_mfma_f32_16x16x32_bf16 v[4:7], v[144:147], v[208:211], v[4:7]
	v_mfma_f32_16x16x32_bf16 v[0:3], v[160:163], v[208:211], v[0:3]
	v_mfma_f32_16x16x32_bf16 v[52:55], v[156:159], v[188:191], v[52:55]
	v_mfma_f32_16x16x32_bf16 v[48:51], v[164:167], v[188:191], v[48:51]
	v_mfma_f32_16x16x32_bf16 v[36:39], v[156:159], v[196:199], v[36:39]
	v_mfma_f32_16x16x32_bf16 v[32:35], v[164:167], v[196:199], v[32:35]
	v_mfma_f32_16x16x32_bf16 v[20:23], v[156:159], v[204:207], v[20:23]
	v_mfma_f32_16x16x32_bf16 v[16:19], v[164:167], v[204:207], v[16:19]
	v_mfma_f32_16x16x32_bf16 v[4:7], v[156:159], v[212:215], v[4:7]
	v_mfma_f32_16x16x32_bf16 v[0:3], v[164:167], v[212:215], v[0:3]
	s_setprio 0
	s_setprio 1
	v_mfma_f32_16x16x32_bf16 v[60:63], v[168:171], v[184:187], v[60:63]
	v_mfma_f32_16x16x32_bf16 v[56:59], v[176:179], v[184:187], v[56:59]
	v_mfma_f32_16x16x32_bf16 v[44:47], v[168:171], v[192:195], v[44:47]
	v_mfma_f32_16x16x32_bf16 v[40:43], v[176:179], v[192:195], v[40:43]
	v_mfma_f32_16x16x32_bf16 v[28:31], v[168:171], v[200:203], v[28:31]
	v_mfma_f32_16x16x32_bf16 v[24:27], v[176:179], v[200:203], v[24:27]
	v_mfma_f32_16x16x32_bf16 v[12:15], v[168:171], v[208:211], v[12:15]
	v_mfma_f32_16x16x32_bf16 v[8:11], v[176:179], v[208:211], v[8:11]
	v_mfma_f32_16x16x32_bf16 v[60:63], v[172:175], v[188:191], v[60:63]
	v_mfma_f32_16x16x32_bf16 v[56:59], v[180:183], v[188:191], v[56:59]
	v_mfma_f32_16x16x32_bf16 v[44:47], v[172:175], v[196:199], v[44:47]
	v_mfma_f32_16x16x32_bf16 v[40:43], v[180:183], v[196:199], v[40:43]
	v_mfma_f32_16x16x32_bf16 v[28:31], v[172:175], v[204:207], v[28:31]
	v_mfma_f32_16x16x32_bf16 v[24:27], v[180:183], v[204:207], v[24:27]
	v_mfma_f32_16x16x32_bf16 v[12:15], v[172:175], v[212:215], v[12:15]
	v_mfma_f32_16x16x32_bf16 v[8:11], v[180:183], v[212:215], v[8:11]
	s_setprio 0
	s_add_i32 s78, s78, 2
	s_add_u32 s62, s62, 0x100
	s_addc_u32 s63, s63, 0
	s_add_u32 s76, s76, 0x100
	s_addc_u32 s77, s77, 0
	s_cmp_gt_u32 s78, 29
	s_barrier
	s_cbranch_scc0 .LBB0_1390
	s_and_b64 vcc, exec, s[18:19]
	s_cbranch_vccz .LBB0_1393
	s_barrier

; #define PG8_STAGE(bufoff, gbase, voff) do { _Pragma("unroll") for (int _i = 0; _i < 2; ++_i) \
;         __builtin_amdgcn_global_load_lds((const unsigned*)((const char*)(gbase) + (voff)[_i]), (PG8_LAS unsigned*)(lds + (bufoff) + ldsw + _i * 8192), 16, 0, 0); } while (0)
; #define PG8_LDA(dst, b, h) do { _Pragma("unroll") for (int m = 0; m < 4; ++m) _Pragma("unroll") for (int k = 0; k < 2; ++k) dst[m][k] = *(const PG8_LAS bf16x8*)(lds + PG8_SA(b, h) + aoff + m * 2048 + k * 1024); } while (0)
; #define PG8_LDB(dst, b, h) do { _Pragma("unroll") for (int n = 0; n < 2; ++n) _Pragma("unroll") for (int k = 0; k < 2; ++k) dst[n][k] = *(const PG8_LAS bf16x8*)(lds + PG8_SB(b, h) + boff + n * 2048 + k * 1024); } while (0)
; #define PG8_MMA(ai, bj, At, Bt) do { __builtin_amdgcn_s_setprio(1); _Pragma("unroll") for (int m = 0; m < 4; ++m) _Pragma("unroll") for (int n = 0; n < 2; ++n) _Pragma("unroll") for (int k = 0; k < 2; ++k) \
;         acc[ai][bj][m][n] = __builtin_amdgcn_mfma_f32_16x16x32_bf16(Bt[n][k], At[m][k], acc[ai][bj][m][n], 0, 0, 0); __builtin_amdgcn_s_setprio(0); } while (0)
; #define PG8_WAIT_V(n) asm volatile("s_waitcnt vmcnt(" #n ")" ::: "memory")
; #define PG8_WAIT_L(n) asm volatile("s_waitcnt lgkmcnt(" #n ")" ::: "memory")
; #define PG8_BAR __builtin_amdgcn_s_barrier()
; template <class Epi, class Sched, bool ALIGN_EPI = false, bool SP2 = false>
; __device__ __forceinline__ void gemm_phase(PG8_LAS unsigned char* lds, const Gemm g, const Sched& S, const Epi& E, const int wave_in) {
;     ...
;         for (int t = 0; t < nt; t += 2) {
;             const bool last = (t == nt - 2);
;             const char* a1 = cA + (size_t)(t + 1) * kstep;
;             const char* a2 = last ? nA : cA + (size_t)(t + 2) * kstep; const char* b2 = last ? nB : cB + (size_t)(t + 2) * kstep;
;             const char* a3 = a2 + kstep; const char* b3 = b2 + kstep;
;             if (last && has_next) S.a_ready(nxt);
;             if constexpr (SP2) {
;             PG8_LDB(B0, 0, 0); PG8_LDB(B1, 0, 1); PG8_SCHED; PG8_LDA(At, 0, 0); PG8_STAGE(PG8_SA(1, 1), a1 + hstepA, voffA);
;             PG8_WAIT_V(8); PG8_WAIT_L(0); PG8_BAR; PG8_MMA(0, 0, At, B0); PG8_MMA(0, 1, At, B1); PG8_BAR; PG8_SCHED;
;             PG8_LDA(At, 0, 1); PG8_STAGE(PG8_SB(0, 0), b2, voffB); PG8_STAGE(PG8_SB(0, 1), b2 + hstep, voffB); PG8_STAGE(PG8_SA(0, 0), a2, voffA);
.LBB0_1475:
	ds_read_b128 v[144:147], v151
	ds_read_b128 v[156:159], v151 offset:1024
	ds_read_b128 v[160:163], v151 offset:2048
	ds_read_b128 v[164:167], v151 offset:3072
	ds_read_b128 v[168:171], v152
	ds_read_b128 v[172:175], v152 offset:1024
	ds_read_b128 v[176:179], v152 offset:2048
	ds_read_b128 v[180:183], v152 offset:3072
	s_add_u32 s60, s58, 0x100
	s_addc_u32 s61, s59, 0
	s_cmpk_eq_i32 s76, 0x54
	s_cselect_b32 s65, s7, s61
	s_cselect_b32 s64, s6, s60
	s_cselect_b32 s63, s43, s75
	s_cselect_b32 s62, s42, s74
	v_lshl_add_u64 v[216:217], s[58:59], 0, v[136:137]
	s_add_i32 m0, s33, 0xc000
	ds_read_b128 v[184:187], v153
	ds_read_b128 v[188:191], v153 offset:1024
	ds_read_b128 v[192:195], v153 offset:2048
	ds_read_b128 v[196:199], v153 offset:3072
	ds_read_b128 v[200:203], v153 offset:4096
	ds_read_b128 v[204:207], v153 offset:5120
	ds_read_b128 v[208:211], v153 offset:6144
	ds_read_b128 v[212:215], v153 offset:7168
	global_load_lds_dwordx4 v[216:217], off
	v_lshl_add_u64 v[216:217], s[58:59], 0, v[138:139]
	s_add_i32 m0, s33, 0xe000
	s_nop 0
	global_load_lds_dwordx4 v[216:217], off
	s_waitcnt vmcnt(8)
	s_waitcnt lgkmcnt(0)
	s_barrier
	s_setprio 1
	s_waitcnt lgkmcnt(0)
	v_mfma_f32_16x16x32_bf16 v[124:127], v[144:147], v[184:187], v[124:127]
	v_mfma_f32_16x16x32_bf16 v[120:123], v[160:163], v[184:187], v[120:123]
	v_mfma_f32_16x16x32_bf16 v[108:111], v[144:147], v[192:195], v[108:111]
	v_mfma_f32_16x16x32_bf16 v[104:107], v[160:163], v[192:195], v[104:107]
	v_mfma_f32_16x16x32_bf16 v[92:95], v[144:147], v[200:203], v[92:95]
	v_mfma_f32_16x16x32_bf16 v[88:91], v[160:163], v[200:203], v[88:91]
	v_mfma_f32_16x16x32_bf16 v[76:79], v[144:147], v[208:211], v[76:79]
	v_mfma_f32_16x16x32_bf16 v[72:75], v[160:163], v[208:211], v[72:75]
	v_mfma_f32_16x16x32_bf16 v[124:127], v[156:159], v[188:191], v[124:127]
	v_mfma_f32_16x16x32_bf16 v[120:123], v[164:167], v[188:191], v[120:123]
	v_mfma_f32_16x16x32_bf16 v[108:111], v[156:159], v[196:199], v[108:111]
	v_mfma_f32_16x16x32_bf16 v[104:107], v[164:167], v[196:199], v[104:107]
	v_mfma_f32_16x16x32_bf16 v[92:95], v[156:159], v[204:207], v[92:95]
	v_mfma_f32_16x16x32_bf16 v[88:91], v[164:167], v[204:207], v[88:91]
	v_mfma_f32_16x16x32_bf16 v[76:79], v[156:159], v[212:215], v[76:79]
	v_mfma_f32_16x16x32_bf16 v[72:75], v[164:167], v[212:215], v[72:75]
	s_setprio 0
	s_setprio 1
	v_mfma_f32_16x16x32_bf16 v[116:119], v[168:171], v[184:187], v[116:119]
	v_mfma_f32_16x16x32_bf16 v[112:115], v[176:179], v[184:187], v[112:115]
	v_mfma_f32_16x16x32_bf16 v[100:103], v[168:171], v[192:195], v[100:103]
	v_mfma_f32_16x16x32_bf16 v[96:99], v[176:179], v[192:195], v[96:99]
	v_mfma_f32_16x16x32_bf16 v[84:87], v[168:171], v[200:203], v[84:87]
	v_mfma_f32_16x16x32_bf16 v[80:83], v[176:179], v[200:203], v[80:83]
	v_mfma_f32_16x16x32_bf16 v[68:71], v[168:171], v[208:211], v[68:71]
	v_mfma_f32_16x16x32_bf16 v[64:67], v[176:179], v[208:211], v[64:67]
	v_mfma_f32_16x16x32_bf16 v[116:119], v[172:175], v[188:191], v[116:119]
	v_mfma_f32_16x16x32_bf16 v[112:115], v[180:183], v[188:191], v[112:115]
	v_mfma_f32_16x16x32_bf16 v[100:103], v[172:175], v[196:199], v[100:103]
	v_mfma_f32_16x16x32_bf16 v[96:99], v[180:183], v[196:199], v[96:99]
	v_mfma_f32_16x16x32_bf16 v[84:87], v[172:175], v[204:207], v[84:87]
	v_mfma_f32_16x16x32_bf16 v[80:83], v[180:183], v[204:207], v[80:83]
	v_mfma_f32_16x16x32_bf16 v[68:71], v[172:175], v[212:215], v[68:71]
	v_mfma_f32_16x16x32_bf16 v[64:67], v[180:183], v[212:215], v[64:67]
	s_setprio 0
	s_barrier
	s_add_i32 s58, s70, s11
	v_lshl_add_u64 v[216:217], s[62:63], 0, v[130:131]
	s_mov_b32 m0, s58
	ds_read_b128 v[184:187], v153 offset:16384
	ds_read_b128 v[188:191], v153 offset:17408
	ds_read_b128 v[192:195], v153 offset:18432
	ds_read_b128 v[196:199], v153 offset:19456
	ds_read_b128 v[200:203], v153 offset:20480
	ds_read_b128 v[204:207], v153 offset:21504
	ds_read_b128 v[208:211], v153 offset:22528
	ds_read_b128 v[212:215], v153 offset:23552
	global_load_lds_dwordx4 v[216:217], off
	s_add_i32 m0, s58, 0x2000
	s_add_u32 s58, s62, 0x160000
	v_lshl_add_u64 v[218:219], s[62:63], 0, v[134:135]
	s_addc_u32 s59, s63, 0
	s_add_i32 s77, s71, s11
	global_load_lds_dwordx4 v[218:219], off
	v_lshl_add_u64 v[220:221], s[58:59], 0, v[130:131]
	s_mov_b32 m0, s77
	v_lshl_add_u64 v[222:223], s[64:65], 0, v[132:133]
	global_load_lds_dwordx4 v[220:221], off
	v_lshl_add_u64 v[220:221], s[58:59], 0, v[134:135]
	s_add_i32 m0, s77, 0x2000
	s_nop 0
	global_load_lds_dwordx4 v[220:221], off
	v_lshl_add_u64 v[220:221], s[64:65], 0, v[128:129]
	s_mov_b32 m0, s33
	s_nop 0
	global_load_lds_dwordx4 v[220:221], off
	s_mov_b32 m0, s35
	s_nop 0
	global_load_lds_dwordx4 v[222:223], off
	s_waitcnt vmcnt(8)
	s_waitcnt lgkmcnt(0)
	s_barrier
; #define PG8_STAGE(bufoff, gbase, voff) do { _Pragma("unroll") for (int _i = 0; _i < 2; ++_i) \
;         __builtin_amdgcn_global_load_lds((const unsigned*)((const char*)(gbase) + (voff)[_i]), (PG8_LAS unsigned*)(lds + (bufoff) + ldsw + _i * 8192), 16, 0, 0); } while (0)
; #define PG8_LDA(dst, b, h) do { _Pragma("unroll") for (int m = 0; m < 4; ++m) _Pragma("unroll") for (int k = 0; k < 2; ++k) dst[m][k] = *(const PG8_LAS bf16x8*)(lds + PG8_SA(b, h) + aoff + m * 2048 + k * 1024); } while (0)
; #define PG8_LDB(dst, b, h) do { _Pragma("unroll") for (int n = 0; n < 2; ++n) _Pragma("unroll") for (int k = 0; k < 2; ++k) dst[n][k] = *(const PG8_LAS bf16x8*)(lds + PG8_SB(b, h) + boff + n * 2048 + k * 1024); } while (0)
; #define PG8_MMA(ai, bj, At, Bt) do { __builtin_amdgcn_s_setprio(1); _Pragma("unroll") for (int m = 0; m < 4; ++m) _Pragma("unroll") for (int n = 0; n < 2; ++n) _Pragma("unroll") for (int k = 0; k < 2; ++k) \
;         acc[ai][bj][m][n] = __builtin_amdgcn_mfma_f32_16x16x32_bf16(Bt[n][k], At[m][k], acc[ai][bj][m][n], 0, 0, 0); __builtin_amdgcn_s_setprio(0); } while (0)
; #define PG8_WAIT_V(n) asm volatile("s_waitcnt vmcnt(" #n ")" ::: "memory")
; #define PG8_WAIT_L(n) asm volatile("s_waitcnt lgkmcnt(" #n ")" ::: "memory")
; #define PG8_BAR __builtin_amdgcn_s_barrier()
; #define PG8_SCHED __builtin_amdgcn_sched_barrier(0)
; template <class Epi, class Sched, bool ALIGN_EPI = false, bool SP2 = false>
; __device__ __forceinline__ void gemm_phase(PG8_LAS unsigned char* lds, const Gemm g, const Sched& S, const Epi& E, const int wave_in) {
;     ...
;             PG8_WAIT_V(8); PG8_WAIT_L(0); PG8_BAR; PG8_MMA(1, 0, At, B0); PG8_MMA(1, 1, At, B1); PG8_BAR; PG8_SCHED;
;             PG8_LDB(B0, 1, 0); PG8_LDB(B1, 1, 1); PG8_SCHED; PG8_LDA(At, 1, 0); PG8_STAGE(PG8_SA(0, 1), a2 + hstepA, voffA);
;             PG8_WAIT_V(8); PG8_WAIT_L(0); PG8_BAR; PG8_MMA(0, 0, At, B0); PG8_MMA(0, 1, At, B1); PG8_BAR; PG8_SCHED;
	s_setprio 1
	s_waitcnt lgkmcnt(0)
	v_mfma_f32_16x16x32_bf16 v[60:63], v[144:147], v[184:187], v[60:63]
	v_mfma_f32_16x16x32_bf16 v[56:59], v[160:163], v[184:187], v[56:59]
	v_mfma_f32_16x16x32_bf16 v[44:47], v[144:147], v[192:195], v[44:47]
	v_mfma_f32_16x16x32_bf16 v[40:43], v[160:163], v[192:195], v[40:43]
	v_mfma_f32_16x16x32_bf16 v[28:31], v[144:147], v[200:203], v[28:31]
	v_mfma_f32_16x16x32_bf16 v[24:27], v[160:163], v[200:203], v[24:27]
	v_mfma_f32_16x16x32_bf16 v[12:15], v[144:147], v[208:211], v[12:15]
	v_mfma_f32_16x16x32_bf16 v[8:11], v[160:163], v[208:211], v[8:11]
	v_mfma_f32_16x16x32_bf16 v[60:63], v[156:159], v[188:191], v[60:63]
	v_mfma_f32_16x16x32_bf16 v[56:59], v[164:167], v[188:191], v[56:59]
	v_mfma_f32_16x16x32_bf16 v[44:47], v[156:159], v[196:199], v[44:47]
	v_mfma_f32_16x16x32_bf16 v[40:43], v[164:167], v[196:199], v[40:43]
	v_mfma_f32_16x16x32_bf16 v[28:31], v[156:159], v[204:207], v[28:31]
	v_mfma_f32_16x16x32_bf16 v[24:27], v[164:167], v[204:207], v[24:27]
	v_mfma_f32_16x16x32_bf16 v[12:15], v[156:159], v[212:215], v[12:15]
	v_mfma_f32_16x16x32_bf16 v[8:11], v[164:167], v[212:215], v[8:11]
	s_setprio 0
	s_setprio 1
	v_mfma_f32_16x16x32_bf16 v[52:55], v[168:171], v[184:187], v[52:55]
	v_mfma_f32_16x16x32_bf16 v[48:51], v[176:179], v[184:187], v[48:51]
	v_mfma_f32_16x16x32_bf16 v[36:39], v[168:171], v[192:195], v[36:39]
	v_mfma_f32_16x16x32_bf16 v[32:35], v[176:179], v[192:195], v[32:35]
	v_mfma_f32_16x16x32_bf16 v[20:23], v[168:171], v[200:203], v[20:23]
	v_mfma_f32_16x16x32_bf16 v[16:19], v[176:179], v[200:203], v[16:19]
	v_mfma_f32_16x16x32_bf16 v[4:7], v[168:171], v[208:211], v[4:7]
	v_mfma_f32_16x16x32_bf16 v[0:3], v[176:179], v[208:211], v[0:3]
	v_mfma_f32_16x16x32_bf16 v[52:55], v[172:175], v[188:191], v[52:55]
	v_mfma_f32_16x16x32_bf16 v[48:51], v[180:183], v[188:191], v[48:51]
	v_mfma_f32_16x16x32_bf16 v[36:39], v[172:175], v[196:199], v[36:39]
	v_mfma_f32_16x16x32_bf16 v[32:35], v[180:183], v[196:199], v[32:35]
	v_mfma_f32_16x16x32_bf16 v[20:23], v[172:175], v[204:207], v[20:23]
	v_mfma_f32_16x16x32_bf16 v[16:19], v[180:183], v[204:207], v[16:19]
	v_mfma_f32_16x16x32_bf16 v[4:7], v[172:175], v[212:215], v[4:7]
	v_mfma_f32_16x16x32_bf16 v[0:3], v[180:183], v[212:215], v[0:3]
	s_setprio 0
	s_barrier
	s_add_i32 s77, 0, 0x18000
	v_add_u32_e32 v155, s77, v149
	s_add_i32 s78, 0, 0x1c000
	ds_read_b128 v[144:147], v155
	ds_read_b128 v[156:159], v155 offset:1024
	ds_read_b128 v[160:163], v155 offset:2048
	ds_read_b128 v[164:167], v155 offset:3072
	v_add_u32_e32 v155, s78, v149
	ds_read_b128 v[168:171], v155
	ds_read_b128 v[172:175], v155 offset:1024
	ds_read_b128 v[176:179], v155 offset:2048
	ds_read_b128 v[180:183], v155 offset:3072
	s_add_u32 s58, s64, 0x160000
	s_addc_u32 s59, s65, 0
	s_mov_b32 m0, s50
	v_lshl_add_u64 v[224:225], s[58:59], 0, v[128:129]
	ds_read_b128 v[184:187], v153 offset:32768
	ds_read_b128 v[188:191], v153 offset:33792
	ds_read_b128 v[192:195], v153 offset:34816
	ds_read_b128 v[196:199], v153 offset:35840
	ds_read_b128 v[200:203], v153 offset:36864
	ds_read_b128 v[204:207], v153 offset:37888
	ds_read_b128 v[208:211], v153 offset:38912
	ds_read_b128 v[212:215], v153 offset:39936
	global_load_lds_dwordx4 v[224:225], off
	v_lshl_add_u64 v[224:225], s[58:59], 0, v[132:133]
	s_mov_b32 m0, s51
	s_nop 0
	global_load_lds_dwordx4 v[224:225], off
	s_waitcnt vmcnt(8)
	s_waitcnt lgkmcnt(0)
	s_barrier
	s_setprio 1
	s_waitcnt lgkmcnt(0)
	v_mfma_f32_16x16x32_bf16 v[124:127], v[144:147], v[184:187], v[124:127]
	v_mfma_f32_16x16x32_bf16 v[120:123], v[160:163], v[184:187], v[120:123]
	v_mfma_f32_16x16x32_bf16 v[108:111], v[144:147], v[192:195], v[108:111]
	v_mfma_f32_16x16x32_bf16 v[104:107], v[160:163], v[192:195], v[104:107]
	v_mfma_f32_16x16x32_bf16 v[92:95], v[144:147], v[200:203], v[92:95]
	v_mfma_f32_16x16x32_bf16 v[88:91], v[160:163], v[200:203], v[88:91]
	v_mfma_f32_16x16x32_bf16 v[76:79], v[144:147], v[208:211], v[76:79]
	v_mfma_f32_16x16x32_bf16 v[72:75], v[160:163], v[208:211], v[72:75]
	v_mfma_f32_16x16x32_bf16 v[124:127], v[156:159], v[188:191], v[124:127]
	v_mfma_f32_16x16x32_bf16 v[120:123], v[164:167], v[188:191], v[120:123]
	v_mfma_f32_16x16x32_bf16 v[108:111], v[156:159], v[196:199], v[108:111]
	v_mfma_f32_16x16x32_bf16 v[104:107], v[164:167], v[196:199], v[104:107]
	v_mfma_f32_16x16x32_bf16 v[92:95], v[156:159], v[204:207], v[92:95]
	v_mfma_f32_16x16x32_bf16 v[88:91], v[164:167], v[204:207], v[88:91]
	v_mfma_f32_16x16x32_bf16 v[76:79], v[156:159], v[212:215], v[76:79]
	v_mfma_f32_16x16x32_bf16 v[72:75], v[164:167], v[212:215], v[72:75]
	s_setprio 0
	s_setprio 1
	v_mfma_f32_16x16x32_bf16 v[116:119], v[168:171], v[184:187], v[116:119]
	v_mfma_f32_16x16x32_bf16 v[112:115], v[176:179], v[184:187], v[112:115]
	v_mfma_f32_16x16x32_bf16 v[100:103], v[168:171], v[192:195], v[100:103]
	v_mfma_f32_16x16x32_bf16 v[96:99], v[176:179], v[192:195], v[96:99]
	v_mfma_f32_16x16x32_bf16 v[84:87], v[168:171], v[200:203], v[84:87]
	v_mfma_f32_16x16x32_bf16 v[80:83], v[176:179], v[200:203], v[80:83]
	v_mfma_f32_16x16x32_bf16 v[68:71], v[168:171], v[208:211], v[68:71]
	v_mfma_f32_16x16x32_bf16 v[64:67], v[176:179], v[208:211], v[64:67]
	v_mfma_f32_16x16x32_bf16 v[116:119], v[172:175], v[188:191], v[116:119]
	v_mfma_f32_16x16x32_bf16 v[112:115], v[180:183], v[188:191], v[112:115]
	v_mfma_f32_16x16x32_bf16 v[100:103], v[172:175], v[196:199], v[100:103]
	v_mfma_f32_16x16x32_bf16 v[96:99], v[180:183], v[196:199], v[96:99]
	v_mfma_f32_16x16x32_bf16 v[84:87], v[172:175], v[204:207], v[84:87]
	v_mfma_f32_16x16x32_bf16 v[80:83], v[180:183], v[204:207], v[80:83]
	v_mfma_f32_16x16x32_bf16 v[68:71], v[172:175], v[212:215], v[68:71]
	v_mfma_f32_16x16x32_bf16 v[64:67], v[180:183], v[212:215], v[64:67]
	s_setprio 0
	s_barrier
; #define PG8_STAGE(bufoff, gbase, voff) do { _Pragma("unroll") for (int _i = 0; _i < 2; ++_i) \
;         __builtin_amdgcn_global_load_lds((const unsigned*)((const char*)(gbase) + (voff)[_i]), (PG8_LAS unsigned*)(lds + (bufoff) + ldsw + _i * 8192), 16, 0, 0); } while (0)
; #define PG8_LDA(dst, b, h) do { _Pragma("unroll") for (int m = 0; m < 4; ++m) _Pragma("unroll") for (int k = 0; k < 2; ++k) dst[m][k] = *(const PG8_LAS bf16x8*)(lds + PG8_SA(b, h) + aoff + m * 2048 + k * 1024); } while (0)
; #define PG8_MMA(ai, bj, At, Bt) do { __builtin_amdgcn_s_setprio(1); _Pragma("unroll") for (int m = 0; m < 4; ++m) _Pragma("unroll") for (int n = 0; n < 2; ++n) _Pragma("unroll") for (int k = 0; k < 2; ++k) \
;         acc[ai][bj][m][n] = __builtin_amdgcn_mfma_f32_16x16x32_bf16(Bt[n][k], At[m][k], acc[ai][bj][m][n], 0, 0, 0); __builtin_amdgcn_s_setprio(0); } while (0)
; #define PG8_WAIT_V(n) asm volatile("s_waitcnt vmcnt(" #n ")" ::: "memory")
; #define PG8_WAIT_L(n) asm volatile("s_waitcnt lgkmcnt(" #n ")" ::: "memory")
; #define PG8_BAR __builtin_amdgcn_s_barrier()
; #define PG8_SCHED __builtin_amdgcn_sched_barrier(0)
; template <class Epi, class Sched, bool ALIGN_EPI = false, bool SP2 = false>
; __device__ __forceinline__ void gemm_phase(PG8_LAS unsigned char* lds, const Gemm g, const Sched& S, const Epi& E, const int wave_in) {
;     ...
;         for (int t = 0; t < nt; t += 2) {
;             const bool last = (t == nt - 2);
;     ...
;             PG8_LDA(At, 1, 1); PG8_STAGE(PG8_SB(1, 0), b3, voffB); PG8_STAGE(PG8_SB(1, 1), b3 + hstep, voffB); PG8_STAGE(PG8_SA(1, 0), a3, voffA);
;             PG8_WAIT_V(8); PG8_WAIT_L(0); PG8_BAR; PG8_MMA(1, 0, At, B0); PG8_MMA(1, 1, At, B1); PG8_BAR; PG8_SCHED;
	s_add_i32 s58, s77, s11
	v_lshl_add_u64 v[216:217], v[216:217], 0, s[38:39]
	s_mov_b32 m0, s58
	ds_read_b128 v[184:187], v153 offset:49152
	ds_read_b128 v[188:191], v153 offset:50176
	ds_read_b128 v[192:195], v153 offset:51200
	ds_read_b128 v[196:199], v153 offset:52224
	ds_read_b128 v[200:203], v153 offset:53248
	ds_read_b128 v[204:207], v153 offset:54272
	ds_read_b128 v[208:211], v153 offset:55296
	ds_read_b128 v[212:215], v153 offset:56320
	global_load_lds_dwordx4 v[216:217], off
	s_add_i32 m0, s58, 0x2000
	s_add_u32 s58, s62, 0x160080
	v_lshl_add_u64 v[216:217], v[218:219], 0, s[38:39]
	s_addc_u32 s59, s63, 0
	s_add_i32 s62, s78, s11
	global_load_lds_dwordx4 v[216:217], off
	v_lshl_add_u64 v[216:217], s[58:59], 0, v[130:131]
	s_mov_b32 m0, s62
	s_nop 0
	global_load_lds_dwordx4 v[216:217], off
	v_lshl_add_u64 v[216:217], s[58:59], 0, v[134:135]
	s_add_i32 m0, s62, 0x2000
	s_nop 0
	global_load_lds_dwordx4 v[216:217], off
	v_lshl_add_u64 v[216:217], v[220:221], 0, s[38:39]
	s_mov_b32 m0, s67
	s_nop 0
	global_load_lds_dwordx4 v[216:217], off
	v_lshl_add_u64 v[216:217], v[222:223], 0, s[38:39]
	s_mov_b32 m0, s68
	s_nop 0
	global_load_lds_dwordx4 v[216:217], off
	s_waitcnt vmcnt(8)
	s_waitcnt lgkmcnt(0)
	s_barrier
	s_setprio 1
	s_waitcnt lgkmcnt(0)
	v_mfma_f32_16x16x32_bf16 v[60:63], v[144:147], v[184:187], v[60:63]
	v_mfma_f32_16x16x32_bf16 v[56:59], v[160:163], v[184:187], v[56:59]
	v_mfma_f32_16x16x32_bf16 v[44:47], v[144:147], v[192:195], v[44:47]
	v_mfma_f32_16x16x32_bf16 v[40:43], v[160:163], v[192:195], v[40:43]
	v_mfma_f32_16x16x32_bf16 v[28:31], v[144:147], v[200:203], v[28:31]
	v_mfma_f32_16x16x32_bf16 v[24:27], v[160:163], v[200:203], v[24:27]
	v_mfma_f32_16x16x32_bf16 v[12:15], v[144:147], v[208:211], v[12:15]
	v_mfma_f32_16x16x32_bf16 v[8:11], v[160:163], v[208:211], v[8:11]
	v_mfma_f32_16x16x32_bf16 v[60:63], v[156:159], v[188:191], v[60:63]
	v_mfma_f32_16x16x32_bf16 v[56:59], v[164:167], v[188:191], v[56:59]
	v_mfma_f32_16x16x32_bf16 v[44:47], v[156:159], v[196:199], v[44:47]
	v_mfma_f32_16x16x32_bf16 v[40:43], v[164:167], v[196:199], v[40:43]
	v_mfma_f32_16x16x32_bf16 v[28:31], v[156:159], v[204:207], v[28:31]
	v_mfma_f32_16x16x32_bf16 v[24:27], v[164:167], v[204:207], v[24:27]
	v_mfma_f32_16x16x32_bf16 v[12:15], v[156:159], v[212:215], v[12:15]
	v_mfma_f32_16x16x32_bf16 v[8:11], v[164:167], v[212:215], v[8:11]
	s_setprio 0
	s_setprio 1
	v_mfma_f32_16x16x32_bf16 v[52:55], v[168:171], v[184:187], v[52:55]
	v_mfma_f32_16x16x32_bf16 v[48:51], v[176:179], v[184:187], v[48:51]
	v_mfma_f32_16x16x32_bf16 v[36:39], v[168:171], v[192:195], v[36:39]
	v_mfma_f32_16x16x32_bf16 v[32:35], v[176:179], v[192:195], v[32:35]
	v_mfma_f32_16x16x32_bf16 v[20:23], v[168:171], v[200:203], v[20:23]
	v_mfma_f32_16x16x32_bf16 v[16:19], v[176:179], v[200:203], v[16:19]
	v_mfma_f32_16x16x32_bf16 v[4:7], v[168:171], v[208:211], v[4:7]
	v_mfma_f32_16x16x32_bf16 v[0:3], v[176:179], v[208:211], v[0:3]
	v_mfma_f32_16x16x32_bf16 v[52:55], v[172:175], v[188:191], v[52:55]
	v_mfma_f32_16x16x32_bf16 v[48:51], v[180:183], v[188:191], v[48:51]
	v_mfma_f32_16x16x32_bf16 v[36:39], v[172:175], v[196:199], v[36:39]
	v_mfma_f32_16x16x32_bf16 v[32:35], v[180:183], v[196:199], v[32:35]
	v_mfma_f32_16x16x32_bf16 v[20:23], v[172:175], v[204:207], v[20:23]
	v_mfma_f32_16x16x32_bf16 v[16:19], v[180:183], v[204:207], v[16:19]
	v_mfma_f32_16x16x32_bf16 v[4:7], v[172:175], v[212:215], v[4:7]
	v_mfma_f32_16x16x32_bf16 v[0:3], v[180:183], v[212:215], v[0:3]
	s_setprio 0
	s_add_i32 s76, s76, 2
	s_add_u32 s74, s74, 0x100
	s_addc_u32 s75, s75, 0
	s_cmpk_gt_u32 s76, 0x55
	s_mov_b64 s[58:59], s[60:61]
	s_barrier
	s_cbranch_scc0 .LBB0_1475
	s_and_b64 vcc, exec, s[40:41]
	s_cbranch_vccz .LBB0_1478
	s_barrier

; #define PG8_STAGE(bufoff, gbase, voff) do { _Pragma("unroll") for (int _i = 0; _i < 2; ++_i) \
;         __builtin_amdgcn_global_load_lds((const unsigned*)((const char*)(gbase) + (voff)[_i]), (PG8_LAS unsigned*)(lds + (bufoff) + ldsw + _i * 8192), 16, 0, 0); } while (0)
; #define PG8_LDA(dst, b, h) do { _Pragma("unroll") for (int m = 0; m < 4; ++m) _Pragma("unroll") for (int k = 0; k < 2; ++k) dst[m][k] = *(const PG8_LAS bf16x8*)(lds + PG8_SA(b, h) + aoff + m * 2048 + k * 1024); } while (0)
; #define PG8_LDB(dst, b, h) do { _Pragma("unroll") for (int n = 0; n < 2; ++n) _Pragma("unroll") for (int k = 0; k < 2; ++k) dst[n][k] = *(const PG8_LAS bf16x8*)(lds + PG8_SB(b, h) + boff + n * 2048 + k * 1024); } while (0)
; #define PG8_MMA(ai, bj, At, Bt) do { __builtin_amdgcn_s_setprio(1); _Pragma("unroll") for (int m = 0; m < 4; ++m) _Pragma("unroll") for (int n = 0; n < 2; ++n) _Pragma("unroll") for (int k = 0; k < 2; ++k) \
;         acc[ai][bj][m][n] = __builtin_amdgcn_mfma_f32_16x16x32_bf16(Bt[n][k], At[m][k], acc[ai][bj][m][n], 0, 0, 0); __builtin_amdgcn_s_setprio(0); } while (0)
; #define PG8_WAIT_V(n) asm volatile("s_waitcnt vmcnt(" #n ")" ::: "memory")
; #define PG8_WAIT_L(n) asm volatile("s_waitcnt lgkmcnt(" #n ")" ::: "memory")
; template <class Epi, class Sched, bool ALIGN_EPI = false, bool SP2 = false>
; __device__ __forceinline__ void gemm_phase(PG8_LAS unsigned char* lds, const Gemm g, const Sched& S, const Epi& E, const int wave_in) {
;     ...
;             const bool last = (t == nt - 2);
;             const char* a1 = cA + (size_t)(t + 1) * kstep;
;             const char* a2 = last ? nA : cA + (size_t)(t + 2) * kstep; const char* b2 = last ? nB : cB + (size_t)(t + 2) * kstep;
;             const char* a3 = a2 + kstep; const char* b3 = b2 + kstep;
;             if (last && has_next) S.a_ready(nxt);
;             if constexpr (SP2) {
;             PG8_LDB(B0, 0, 0); PG8_LDB(B1, 0, 1); PG8_SCHED; PG8_LDA(At, 0, 0); PG8_STAGE(PG8_SA(1, 1), a1 + hstepA, voffA);
;             PG8_WAIT_V(8); PG8_WAIT_L(0); PG8_BAR; PG8_MMA(0, 0, At, B0); PG8_MMA(0, 1, At, B1); PG8_BAR; PG8_SCHED;
;             PG8_LDA(At, 0, 1); PG8_STAGE(PG8_SB(0, 0), b2, voffB); PG8_STAGE(PG8_SB(0, 1), b2 + hstep, voffB); PG8_STAGE(PG8_SA(0, 0), a2, voffA);
;             PG8_WAIT_V(8); PG8_WAIT_L(0); PG8_BAR; PG8_MMA(1, 0, At, B0); PG8_MMA(1, 1, At, B1); PG8_BAR; PG8_SCHED;
.LBB0_1647:
	ds_read_b128 v[144:147], v151
	ds_read_b128 v[156:159], v151 offset:1024
	ds_read_b128 v[160:163], v151 offset:2048
	ds_read_b128 v[164:167], v151 offset:3072
	ds_read_b128 v[168:171], v152
	ds_read_b128 v[172:175], v152 offset:1024
	ds_read_b128 v[176:179], v152 offset:2048
	ds_read_b128 v[180:183], v152 offset:3072
	s_add_u32 s58, s56, 0x100
	s_addc_u32 s59, s57, 0
	s_cmpk_eq_i32 s74, 0x54
	s_cselect_b32 s63, s7, s59
	s_cselect_b32 s62, s6, s58
	s_cselect_b32 s61, s43, s73
	s_cselect_b32 s60, s42, s72
	v_lshl_add_u64 v[216:217], s[56:57], 0, v[136:137]
	s_add_i32 m0, s33, 0xc000
	ds_read_b128 v[184:187], v153
	ds_read_b128 v[188:191], v153 offset:1024
	ds_read_b128 v[192:195], v153 offset:2048
	ds_read_b128 v[196:199], v153 offset:3072
	ds_read_b128 v[200:203], v153 offset:4096
	ds_read_b128 v[204:207], v153 offset:5120
	ds_read_b128 v[208:211], v153 offset:6144
	ds_read_b128 v[212:215], v153 offset:7168
	global_load_lds_dwordx4 v[216:217], off
	v_lshl_add_u64 v[216:217], s[56:57], 0, v[138:139]
	s_add_i32 m0, s33, 0xe000
	s_nop 0
	global_load_lds_dwordx4 v[216:217], off
	s_waitcnt vmcnt(8)
	s_waitcnt lgkmcnt(0)
	s_barrier
	s_setprio 1
	s_waitcnt lgkmcnt(0)
	v_mfma_f32_16x16x32_bf16 v[124:127], v[144:147], v[184:187], v[124:127]
	v_mfma_f32_16x16x32_bf16 v[120:123], v[160:163], v[184:187], v[120:123]
	v_mfma_f32_16x16x32_bf16 v[108:111], v[144:147], v[192:195], v[108:111]
	v_mfma_f32_16x16x32_bf16 v[104:107], v[160:163], v[192:195], v[104:107]
	v_mfma_f32_16x16x32_bf16 v[92:95], v[144:147], v[200:203], v[92:95]
	v_mfma_f32_16x16x32_bf16 v[88:91], v[160:163], v[200:203], v[88:91]
	v_mfma_f32_16x16x32_bf16 v[76:79], v[144:147], v[208:211], v[76:79]
	v_mfma_f32_16x16x32_bf16 v[72:75], v[160:163], v[208:211], v[72:75]
	v_mfma_f32_16x16x32_bf16 v[124:127], v[156:159], v[188:191], v[124:127]
	v_mfma_f32_16x16x32_bf16 v[120:123], v[164:167], v[188:191], v[120:123]
	v_mfma_f32_16x16x32_bf16 v[108:111], v[156:159], v[196:199], v[108:111]
	v_mfma_f32_16x16x32_bf16 v[104:107], v[164:167], v[196:199], v[104:107]
	v_mfma_f32_16x16x32_bf16 v[92:95], v[156:159], v[204:207], v[92:95]
	v_mfma_f32_16x16x32_bf16 v[88:91], v[164:167], v[204:207], v[88:91]
	v_mfma_f32_16x16x32_bf16 v[76:79], v[156:159], v[212:215], v[76:79]
	v_mfma_f32_16x16x32_bf16 v[72:75], v[164:167], v[212:215], v[72:75]
	s_setprio 0
	s_setprio 1
	v_mfma_f32_16x16x32_bf16 v[116:119], v[168:171], v[184:187], v[116:119]
	v_mfma_f32_16x16x32_bf16 v[112:115], v[176:179], v[184:187], v[112:115]
	v_mfma_f32_16x16x32_bf16 v[100:103], v[168:171], v[192:195], v[100:103]
	v_mfma_f32_16x16x32_bf16 v[96:99], v[176:179], v[192:195], v[96:99]
	v_mfma_f32_16x16x32_bf16 v[84:87], v[168:171], v[200:203], v[84:87]
	v_mfma_f32_16x16x32_bf16 v[80:83], v[176:179], v[200:203], v[80:83]
	v_mfma_f32_16x16x32_bf16 v[68:71], v[168:171], v[208:211], v[68:71]
	v_mfma_f32_16x16x32_bf16 v[64:67], v[176:179], v[208:211], v[64:67]
	v_mfma_f32_16x16x32_bf16 v[116:119], v[172:175], v[188:191], v[116:119]
	v_mfma_f32_16x16x32_bf16 v[112:115], v[180:183], v[188:191], v[112:115]
	v_mfma_f32_16x16x32_bf16 v[100:103], v[172:175], v[196:199], v[100:103]
	v_mfma_f32_16x16x32_bf16 v[96:99], v[180:183], v[196:199], v[96:99]
	v_mfma_f32_16x16x32_bf16 v[84:87], v[172:175], v[204:207], v[84:87]
	v_mfma_f32_16x16x32_bf16 v[80:83], v[180:183], v[204:207], v[80:83]
	v_mfma_f32_16x16x32_bf16 v[68:71], v[172:175], v[212:215], v[68:71]
	v_mfma_f32_16x16x32_bf16 v[64:67], v[180:183], v[212:215], v[64:67]
	s_setprio 0
	s_barrier
	s_add_i32 s56, s68, s11
	v_lshl_add_u64 v[216:217], s[60:61], 0, v[130:131]
	s_mov_b32 m0, s56
	ds_read_b128 v[184:187], v153 offset:16384
	ds_read_b128 v[188:191], v153 offset:17408
	ds_read_b128 v[192:195], v153 offset:18432
	ds_read_b128 v[196:199], v153 offset:19456
	ds_read_b128 v[200:203], v153 offset:20480
	ds_read_b128 v[204:207], v153 offset:21504
	ds_read_b128 v[208:211], v153 offset:22528
	ds_read_b128 v[212:215], v153 offset:23552
	global_load_lds_dwordx4 v[216:217], off
	s_add_i32 m0, s56, 0x2000
	s_add_u32 s56, s60, 0x160000
	v_lshl_add_u64 v[218:219], s[60:61], 0, v[134:135]
	s_addc_u32 s57, s61, 0
	s_add_i32 s75, s69, s11
	global_load_lds_dwordx4 v[218:219], off
	v_lshl_add_u64 v[220:221], s[56:57], 0, v[130:131]
	s_mov_b32 m0, s75
	v_lshl_add_u64 v[222:223], s[62:63], 0, v[132:133]
	global_load_lds_dwordx4 v[220:221], off
	v_lshl_add_u64 v[220:221], s[56:57], 0, v[134:135]
	s_add_i32 m0, s75, 0x2000
	s_nop 0
	global_load_lds_dwordx4 v[220:221], off
	v_lshl_add_u64 v[220:221], s[62:63], 0, v[128:129]
	s_mov_b32 m0, s33
	s_nop 0
	global_load_lds_dwordx4 v[220:221], off
	s_mov_b32 m0, s35
	s_nop 0
	global_load_lds_dwordx4 v[222:223], off
	s_waitcnt vmcnt(8)
	s_waitcnt lgkmcnt(0)
	s_barrier
; #define PG8_STAGE(bufoff, gbase, voff) do { _Pragma("unroll") for (int _i = 0; _i < 2; ++_i) \
;         __builtin_amdgcn_global_load_lds((const unsigned*)((const char*)(gbase) + (voff)[_i]), (PG8_LAS unsigned*)(lds + (bufoff) + ldsw + _i * 8192), 16, 0, 0); } while (0)
; #define PG8_LDA(dst, b, h) do { _Pragma("unroll") for (int m = 0; m < 4; ++m) _Pragma("unroll") for (int k = 0; k < 2; ++k) dst[m][k] = *(const PG8_LAS bf16x8*)(lds + PG8_SA(b, h) + aoff + m * 2048 + k * 1024); } while (0)
; #define PG8_LDB(dst, b, h) do { _Pragma("unroll") for (int n = 0; n < 2; ++n) _Pragma("unroll") for (int k = 0; k < 2; ++k) dst[n][k] = *(const PG8_LAS bf16x8*)(lds + PG8_SB(b, h) + boff + n * 2048 + k * 1024); } while (0)
; #define PG8_MMA(ai, bj, At, Bt) do { __builtin_amdgcn_s_setprio(1); _Pragma("unroll") for (int m = 0; m < 4; ++m) _Pragma("unroll") for (int n = 0; n < 2; ++n) _Pragma("unroll") for (int k = 0; k < 2; ++k) \
;         acc[ai][bj][m][n] = __builtin_amdgcn_mfma_f32_16x16x32_bf16(Bt[n][k], At[m][k], acc[ai][bj][m][n], 0, 0, 0); __builtin_amdgcn_s_setprio(0); } while (0)
; #define PG8_WAIT_V(n) asm volatile("s_waitcnt vmcnt(" #n ")" ::: "memory")
; #define PG8_WAIT_L(n) asm volatile("s_waitcnt lgkmcnt(" #n ")" ::: "memory")
; #define PG8_BAR __builtin_amdgcn_s_barrier()
; #define PG8_SCHED __builtin_amdgcn_sched_barrier(0)
; template <class Epi, class Sched, bool ALIGN_EPI = false, bool SP2 = false>
; __device__ __forceinline__ void gemm_phase(PG8_LAS unsigned char* lds, const Gemm g, const Sched& S, const Epi& E, const int wave_in) {
;     ...
;             PG8_WAIT_V(8); PG8_WAIT_L(0); PG8_BAR; PG8_MMA(1, 0, At, B0); PG8_MMA(1, 1, At, B1); PG8_BAR; PG8_SCHED;
;             PG8_LDB(B0, 1, 0); PG8_LDB(B1, 1, 1); PG8_SCHED; PG8_LDA(At, 1, 0); PG8_STAGE(PG8_SA(0, 1), a2 + hstepA, voffA);
;             PG8_WAIT_V(8); PG8_WAIT_L(0); PG8_BAR; PG8_MMA(0, 0, At, B0); PG8_MMA(0, 1, At, B1); PG8_BAR; PG8_SCHED;
	s_setprio 1
	s_waitcnt lgkmcnt(0)
	v_mfma_f32_16x16x32_bf16 v[60:63], v[144:147], v[184:187], v[60:63]
	v_mfma_f32_16x16x32_bf16 v[56:59], v[160:163], v[184:187], v[56:59]
	v_mfma_f32_16x16x32_bf16 v[44:47], v[144:147], v[192:195], v[44:47]
	v_mfma_f32_16x16x32_bf16 v[40:43], v[160:163], v[192:195], v[40:43]
	v_mfma_f32_16x16x32_bf16 v[28:31], v[144:147], v[200:203], v[28:31]
	v_mfma_f32_16x16x32_bf16 v[24:27], v[160:163], v[200:203], v[24:27]
	v_mfma_f32_16x16x32_bf16 v[12:15], v[144:147], v[208:211], v[12:15]
	v_mfma_f32_16x16x32_bf16 v[8:11], v[160:163], v[208:211], v[8:11]
	v_mfma_f32_16x16x32_bf16 v[60:63], v[156:159], v[188:191], v[60:63]
	v_mfma_f32_16x16x32_bf16 v[56:59], v[164:167], v[188:191], v[56:59]
	v_mfma_f32_16x16x32_bf16 v[44:47], v[156:159], v[196:199], v[44:47]
	v_mfma_f32_16x16x32_bf16 v[40:43], v[164:167], v[196:199], v[40:43]
	v_mfma_f32_16x16x32_bf16 v[28:31], v[156:159], v[204:207], v[28:31]
	v_mfma_f32_16x16x32_bf16 v[24:27], v[164:167], v[204:207], v[24:27]
	v_mfma_f32_16x16x32_bf16 v[12:15], v[156:159], v[212:215], v[12:15]
	v_mfma_f32_16x16x32_bf16 v[8:11], v[164:167], v[212:215], v[8:11]
	s_setprio 0
	s_setprio 1
	v_mfma_f32_16x16x32_bf16 v[52:55], v[168:171], v[184:187], v[52:55]
	v_mfma_f32_16x16x32_bf16 v[48:51], v[176:179], v[184:187], v[48:51]
	v_mfma_f32_16x16x32_bf16 v[36:39], v[168:171], v[192:195], v[36:39]
	v_mfma_f32_16x16x32_bf16 v[32:35], v[176:179], v[192:195], v[32:35]
	v_mfma_f32_16x16x32_bf16 v[20:23], v[168:171], v[200:203], v[20:23]
	v_mfma_f32_16x16x32_bf16 v[16:19], v[176:179], v[200:203], v[16:19]
	v_mfma_f32_16x16x32_bf16 v[4:7], v[168:171], v[208:211], v[4:7]
	v_mfma_f32_16x16x32_bf16 v[0:3], v[176:179], v[208:211], v[0:3]
	v_mfma_f32_16x16x32_bf16 v[52:55], v[172:175], v[188:191], v[52:55]
	v_mfma_f32_16x16x32_bf16 v[48:51], v[180:183], v[188:191], v[48:51]
	v_mfma_f32_16x16x32_bf16 v[36:39], v[172:175], v[196:199], v[36:39]
	v_mfma_f32_16x16x32_bf16 v[32:35], v[180:183], v[196:199], v[32:35]
	v_mfma_f32_16x16x32_bf16 v[20:23], v[172:175], v[204:207], v[20:23]
	v_mfma_f32_16x16x32_bf16 v[16:19], v[180:183], v[204:207], v[16:19]
	v_mfma_f32_16x16x32_bf16 v[4:7], v[172:175], v[212:215], v[4:7]
	v_mfma_f32_16x16x32_bf16 v[0:3], v[180:183], v[212:215], v[0:3]
	s_setprio 0
	s_barrier
	s_add_i32 s75, 0, 0x18000
	v_add_u32_e32 v155, s75, v149
	s_add_i32 s76, 0, 0x1c000
	ds_read_b128 v[144:147], v155
	ds_read_b128 v[156:159], v155 offset:1024
	ds_read_b128 v[160:163], v155 offset:2048
	ds_read_b128 v[164:167], v155 offset:3072
	v_add_u32_e32 v155, s76, v149
	ds_read_b128 v[168:171], v155
	ds_read_b128 v[172:175], v155 offset:1024
	ds_read_b128 v[176:179], v155 offset:2048
	ds_read_b128 v[180:183], v155 offset:3072
	s_add_u32 s56, s62, 0x160000
	s_addc_u32 s57, s63, 0
	s_mov_b32 m0, s50
	v_lshl_add_u64 v[224:225], s[56:57], 0, v[128:129]
	ds_read_b128 v[184:187], v153 offset:32768
	ds_read_b128 v[188:191], v153 offset:33792
	ds_read_b128 v[192:195], v153 offset:34816
	ds_read_b128 v[196:199], v153 offset:35840
	ds_read_b128 v[200:203], v153 offset:36864
	ds_read_b128 v[204:207], v153 offset:37888
	ds_read_b128 v[208:211], v153 offset:38912
	ds_read_b128 v[212:215], v153 offset:39936
	global_load_lds_dwordx4 v[224:225], off
	v_lshl_add_u64 v[224:225], s[56:57], 0, v[132:133]
	s_mov_b32 m0, s51
	s_nop 0
	global_load_lds_dwordx4 v[224:225], off
	s_waitcnt vmcnt(8)
	s_waitcnt lgkmcnt(0)
	s_barrier
	s_setprio 1
	s_waitcnt lgkmcnt(0)
	v_mfma_f32_16x16x32_bf16 v[124:127], v[144:147], v[184:187], v[124:127]
	v_mfma_f32_16x16x32_bf16 v[120:123], v[160:163], v[184:187], v[120:123]
	v_mfma_f32_16x16x32_bf16 v[108:111], v[144:147], v[192:195], v[108:111]
	v_mfma_f32_16x16x32_bf16 v[104:107], v[160:163], v[192:195], v[104:107]
	v_mfma_f32_16x16x32_bf16 v[92:95], v[144:147], v[200:203], v[92:95]
	v_mfma_f32_16x16x32_bf16 v[88:91], v[160:163], v[200:203], v[88:91]
	v_mfma_f32_16x16x32_bf16 v[76:79], v[144:147], v[208:211], v[76:79]
	v_mfma_f32_16x16x32_bf16 v[72:75], v[160:163], v[208:211], v[72:75]
	v_mfma_f32_16x16x32_bf16 v[124:127], v[156:159], v[188:191], v[124:127]
	v_mfma_f32_16x16x32_bf16 v[120:123], v[164:167], v[188:191], v[120:123]
	v_mfma_f32_16x16x32_bf16 v[108:111], v[156:159], v[196:199], v[108:111]
	v_mfma_f32_16x16x32_bf16 v[104:107], v[164:167], v[196:199], v[104:107]
	v_mfma_f32_16x16x32_bf16 v[92:95], v[156:159], v[204:207], v[92:95]
	v_mfma_f32_16x16x32_bf16 v[88:91], v[164:167], v[204:207], v[88:91]
	v_mfma_f32_16x16x32_bf16 v[76:79], v[156:159], v[212:215], v[76:79]
	v_mfma_f32_16x16x32_bf16 v[72:75], v[164:167], v[212:215], v[72:75]
	s_setprio 0
	s_setprio 1
	v_mfma_f32_16x16x32_bf16 v[116:119], v[168:171], v[184:187], v[116:119]
	v_mfma_f32_16x16x32_bf16 v[112:115], v[176:179], v[184:187], v[112:115]
	v_mfma_f32_16x16x32_bf16 v[100:103], v[168:171], v[192:195], v[100:103]
	v_mfma_f32_16x16x32_bf16 v[96:99], v[176:179], v[192:195], v[96:99]
	v_mfma_f32_16x16x32_bf16 v[84:87], v[168:171], v[200:203], v[84:87]
	v_mfma_f32_16x16x32_bf16 v[80:83], v[176:179], v[200:203], v[80:83]
	v_mfma_f32_16x16x32_bf16 v[68:71], v[168:171], v[208:211], v[68:71]
	v_mfma_f32_16x16x32_bf16 v[64:67], v[176:179], v[208:211], v[64:67]
	v_mfma_f32_16x16x32_bf16 v[116:119], v[172:175], v[188:191], v[116:119]
	v_mfma_f32_16x16x32_bf16 v[112:115], v[180:183], v[188:191], v[112:115]
	v_mfma_f32_16x16x32_bf16 v[100:103], v[172:175], v[196:199], v[100:103]
	v_mfma_f32_16x16x32_bf16 v[96:99], v[180:183], v[196:199], v[96:99]
	v_mfma_f32_16x16x32_bf16 v[84:87], v[172:175], v[204:207], v[84:87]
	v_mfma_f32_16x16x32_bf16 v[80:83], v[180:183], v[204:207], v[80:83]
	v_mfma_f32_16x16x32_bf16 v[68:71], v[172:175], v[212:215], v[68:71]
	v_mfma_f32_16x16x32_bf16 v[64:67], v[180:183], v[212:215], v[64:67]
	s_setprio 0
	s_barrier
; #define PG8_STAGE(bufoff, gbase, voff) do { _Pragma("unroll") for (int _i = 0; _i < 2; ++_i) \
;         __builtin_amdgcn_global_load_lds((const unsigned*)((const char*)(gbase) + (voff)[_i]), (PG8_LAS unsigned*)(lds + (bufoff) + ldsw + _i * 8192), 16, 0, 0); } while (0)
; #define PG8_LDA(dst, b, h) do { _Pragma("unroll") for (int m = 0; m < 4; ++m) _Pragma("unroll") for (int k = 0; k < 2; ++k) dst[m][k] = *(const PG8_LAS bf16x8*)(lds + PG8_SA(b, h) + aoff + m * 2048 + k * 1024); } while (0)
; #define PG8_MMA(ai, bj, At, Bt) do { __builtin_amdgcn_s_setprio(1); _Pragma("unroll") for (int m = 0; m < 4; ++m) _Pragma("unroll") for (int n = 0; n < 2; ++n) _Pragma("unroll") for (int k = 0; k < 2; ++k) \
;         acc[ai][bj][m][n] = __builtin_amdgcn_mfma_f32_16x16x32_bf16(Bt[n][k], At[m][k], acc[ai][bj][m][n], 0, 0, 0); __builtin_amdgcn_s_setprio(0); } while (0)
; #define PG8_WAIT_V(n) asm volatile("s_waitcnt vmcnt(" #n ")" ::: "memory")
; #define PG8_WAIT_L(n) asm volatile("s_waitcnt lgkmcnt(" #n ")" ::: "memory")
; #define PG8_BAR __builtin_amdgcn_s_barrier()
; #define PG8_SCHED __builtin_amdgcn_sched_barrier(0)
; template <class Epi, class Sched, bool ALIGN_EPI = false, bool SP2 = false>
; __device__ __forceinline__ void gemm_phase(PG8_LAS unsigned char* lds, const Gemm g, const Sched& S, const Epi& E, const int wave_in) {
;     ...
;         for (int t = 0; t < nt; t += 2) {
;             const bool last = (t == nt - 2);
;     ...
;             PG8_LDA(At, 1, 1); PG8_STAGE(PG8_SB(1, 0), b3, voffB); PG8_STAGE(PG8_SB(1, 1), b3 + hstep, voffB); PG8_STAGE(PG8_SA(1, 0), a3, voffA);
;             PG8_WAIT_V(8); PG8_WAIT_L(0); PG8_BAR; PG8_MMA(1, 0, At, B0); PG8_MMA(1, 1, At, B1); PG8_BAR; PG8_SCHED;
	s_add_i32 s56, s75, s11
	v_lshl_add_u64 v[216:217], v[216:217], 0, s[38:39]
	s_mov_b32 m0, s56
	ds_read_b128 v[184:187], v153 offset:49152
	ds_read_b128 v[188:191], v153 offset:50176
	ds_read_b128 v[192:195], v153 offset:51200
	ds_read_b128 v[196:199], v153 offset:52224
	ds_read_b128 v[200:203], v153 offset:53248
	ds_read_b128 v[204:207], v153 offset:54272
	ds_read_b128 v[208:211], v153 offset:55296
	ds_read_b128 v[212:215], v153 offset:56320
	global_load_lds_dwordx4 v[216:217], off
	s_add_i32 m0, s56, 0x2000
	s_add_u32 s56, s60, 0x160080
	v_lshl_add_u64 v[216:217], v[218:219], 0, s[38:39]
	s_addc_u32 s57, s61, 0
	s_add_i32 s60, s76, s11
	global_load_lds_dwordx4 v[216:217], off
	v_lshl_add_u64 v[216:217], s[56:57], 0, v[130:131]
	s_mov_b32 m0, s60
	s_nop 0
	global_load_lds_dwordx4 v[216:217], off
	v_lshl_add_u64 v[216:217], s[56:57], 0, v[134:135]
	s_add_i32 m0, s60, 0x2000
	s_nop 0
	global_load_lds_dwordx4 v[216:217], off
	v_lshl_add_u64 v[216:217], v[220:221], 0, s[38:39]
	s_mov_b32 m0, s65
	s_nop 0
	global_load_lds_dwordx4 v[216:217], off
	v_lshl_add_u64 v[216:217], v[222:223], 0, s[38:39]
	s_mov_b32 m0, s66
	s_nop 0
	global_load_lds_dwordx4 v[216:217], off
	s_waitcnt vmcnt(8)
	s_waitcnt lgkmcnt(0)
	s_barrier
	s_setprio 1
	s_waitcnt lgkmcnt(0)
	v_mfma_f32_16x16x32_bf16 v[60:63], v[144:147], v[184:187], v[60:63]
	v_mfma_f32_16x16x32_bf16 v[56:59], v[160:163], v[184:187], v[56:59]
	v_mfma_f32_16x16x32_bf16 v[44:47], v[144:147], v[192:195], v[44:47]
	v_mfma_f32_16x16x32_bf16 v[40:43], v[160:163], v[192:195], v[40:43]
	v_mfma_f32_16x16x32_bf16 v[28:31], v[144:147], v[200:203], v[28:31]
	v_mfma_f32_16x16x32_bf16 v[24:27], v[160:163], v[200:203], v[24:27]
	v_mfma_f32_16x16x32_bf16 v[12:15], v[144:147], v[208:211], v[12:15]
	v_mfma_f32_16x16x32_bf16 v[8:11], v[160:163], v[208:211], v[8:11]
	v_mfma_f32_16x16x32_bf16 v[60:63], v[156:159], v[188:191], v[60:63]
	v_mfma_f32_16x16x32_bf16 v[56:59], v[164:167], v[188:191], v[56:59]
	v_mfma_f32_16x16x32_bf16 v[44:47], v[156:159], v[196:199], v[44:47]
	v_mfma_f32_16x16x32_bf16 v[40:43], v[164:167], v[196:199], v[40:43]
	v_mfma_f32_16x16x32_bf16 v[28:31], v[156:159], v[204:207], v[28:31]
	v_mfma_f32_16x16x32_bf16 v[24:27], v[164:167], v[204:207], v[24:27]
	v_mfma_f32_16x16x32_bf16 v[12:15], v[156:159], v[212:215], v[12:15]
	v_mfma_f32_16x16x32_bf16 v[8:11], v[164:167], v[212:215], v[8:11]
	s_setprio 0
	s_setprio 1
	v_mfma_f32_16x16x32_bf16 v[52:55], v[168:171], v[184:187], v[52:55]
	v_mfma_f32_16x16x32_bf16 v[48:51], v[176:179], v[184:187], v[48:51]
	v_mfma_f32_16x16x32_bf16 v[36:39], v[168:171], v[192:195], v[36:39]
	v_mfma_f32_16x16x32_bf16 v[32:35], v[176:179], v[192:195], v[32:35]
	v_mfma_f32_16x16x32_bf16 v[20:23], v[168:171], v[200:203], v[20:23]
	v_mfma_f32_16x16x32_bf16 v[16:19], v[176:179], v[200:203], v[16:19]
	v_mfma_f32_16x16x32_bf16 v[4:7], v[168:171], v[208:211], v[4:7]
	v_mfma_f32_16x16x32_bf16 v[0:3], v[176:179], v[208:211], v[0:3]
	v_mfma_f32_16x16x32_bf16 v[52:55], v[172:175], v[188:191], v[52:55]
	v_mfma_f32_16x16x32_bf16 v[48:51], v[180:183], v[188:191], v[48:51]
	v_mfma_f32_16x16x32_bf16 v[36:39], v[172:175], v[196:199], v[36:39]
	v_mfma_f32_16x16x32_bf16 v[32:35], v[180:183], v[196:199], v[32:35]
	v_mfma_f32_16x16x32_bf16 v[20:23], v[172:175], v[204:207], v[20:23]
	v_mfma_f32_16x16x32_bf16 v[16:19], v[180:183], v[204:207], v[16:19]
	v_mfma_f32_16x16x32_bf16 v[4:7], v[172:175], v[212:215], v[4:7]
	v_mfma_f32_16x16x32_bf16 v[0:3], v[180:183], v[212:215], v[0:3]
	s_setprio 0
	s_add_i32 s74, s74, 2
	s_add_u32 s72, s72, 0x100
	s_addc_u32 s73, s73, 0
	s_cmpk_gt_u32 s74, 0x55
	s_mov_b64 s[56:57], s[58:59]
	s_barrier
	s_cbranch_scc0 .LBB0_1647
	s_and_b64 vcc, exec, s[40:41]
	s_cbranch_vccz .LBB0_1650
	s_barrier

; #define PG8_STAGE(bufoff, gbase, voff) do { _Pragma("unroll") for (int _i = 0; _i < 2; ++_i) \
;         __builtin_amdgcn_global_load_lds((const unsigned*)((const char*)(gbase) + (voff)[_i]), (PG8_LAS unsigned*)(lds + (bufoff) + ldsw + _i * 8192), 16, 0, 0); } while (0)
; #define PG8_LDA(dst, b, h) do { _Pragma("unroll") for (int m = 0; m < 4; ++m) _Pragma("unroll") for (int k = 0; k < 2; ++k) dst[m][k] = *(const PG8_LAS bf16x8*)(lds + PG8_SA(b, h) + aoff + m * 2048 + k * 1024); } while (0)
; #define PG8_LDB(dst, b, h) do { _Pragma("unroll") for (int n = 0; n < 2; ++n) _Pragma("unroll") for (int k = 0; k < 2; ++k) dst[n][k] = *(const PG8_LAS bf16x8*)(lds + PG8_SB(b, h) + boff + n * 2048 + k * 1024); } while (0)
; #define PG8_MMA(ai, bj, At, Bt) do { __builtin_amdgcn_s_setprio(1); _Pragma("unroll") for (int m = 0; m < 4; ++m) _Pragma("unroll") for (int n = 0; n < 2; ++n) _Pragma("unroll") for (int k = 0; k < 2; ++k) \
;         acc[ai][bj][m][n] = __builtin_amdgcn_mfma_f32_16x16x32_bf16(Bt[n][k], At[m][k], acc[ai][bj][m][n], 0, 0, 0); __builtin_amdgcn_s_setprio(0); } while (0)
; #define PG8_WAIT_V(n) asm volatile("s_waitcnt vmcnt(" #n ")" ::: "memory")
; #define PG8_WAIT_L(n) asm volatile("s_waitcnt lgkmcnt(" #n ")" ::: "memory")
; template <class Epi, class Sched, bool ALIGN_EPI = false, bool SP2 = false>
; __device__ __forceinline__ void gemm_phase(PG8_LAS unsigned char* lds, const Gemm g, const Sched& S, const Epi& E, const int wave_in) {
;     ...
;             const bool last = (t == nt - 2);
;             const char* a1 = cA + (size_t)(t + 1) * kstep;
;             const char* a2 = last ? nA : cA + (size_t)(t + 2) * kstep; const char* b2 = last ? nB : cB + (size_t)(t + 2) * kstep;
;             const char* a3 = a2 + kstep; const char* b3 = b2 + kstep;
;             if (last && has_next) S.a_ready(nxt);
;             if constexpr (SP2) {
;             PG8_LDB(B0, 0, 0); PG8_LDB(B1, 0, 1); PG8_SCHED; PG8_LDA(At, 0, 0); PG8_STAGE(PG8_SA(1, 1), a1 + hstepA, voffA);
;             PG8_WAIT_V(8); PG8_WAIT_L(0); PG8_BAR; PG8_MMA(0, 0, At, B0); PG8_MMA(0, 1, At, B1); PG8_BAR; PG8_SCHED;
;             PG8_LDA(At, 0, 1); PG8_STAGE(PG8_SB(0, 0), b2, voffB); PG8_STAGE(PG8_SB(0, 1), b2 + hstep, voffB); PG8_STAGE(PG8_SA(0, 0), a2, voffA);
;             PG8_WAIT_V(8); PG8_WAIT_L(0); PG8_BAR; PG8_MMA(1, 0, At, B0); PG8_MMA(1, 1, At, B1); PG8_BAR; PG8_SCHED;
.LBB0_1734:
	ds_read_b128 v[144:147], v155
	ds_read_b128 v[148:151], v155 offset:1024
	ds_read_b128 v[160:163], v155 offset:2048
	ds_read_b128 v[164:167], v155 offset:3072
	ds_read_b128 v[168:171], v156
	ds_read_b128 v[172:175], v156 offset:1024
	ds_read_b128 v[176:179], v156 offset:2048
	ds_read_b128 v[180:183], v156 offset:3072
	s_add_u32 s60, s58, 0xfff80080
	s_addc_u32 s61, s59, -1
	s_cmp_eq_u32 s74, 28
	s_cselect_b32 s63, s39, s61
	s_cselect_b32 s62, s70, s60
	s_cselect_b32 s61, s37, s73
	s_cselect_b32 s60, s71, s72
	v_lshl_add_u64 v[216:217], s[58:59], 0, v[136:137]
	s_add_i32 m0, s48, 0xc000
	ds_read_b128 v[184:187], v157
	ds_read_b128 v[188:191], v157 offset:1024
	ds_read_b128 v[192:195], v157 offset:2048
	ds_read_b128 v[196:199], v157 offset:3072
	ds_read_b128 v[200:203], v157 offset:4096
	ds_read_b128 v[204:207], v157 offset:5120
	ds_read_b128 v[208:211], v157 offset:6144
	ds_read_b128 v[212:215], v157 offset:7168
	global_load_lds_dwordx4 v[216:217], off
	v_lshl_add_u64 v[216:217], s[58:59], 0, v[138:139]
	s_add_i32 m0, s48, 0xe000
	s_nop 0
	global_load_lds_dwordx4 v[216:217], off
	s_waitcnt vmcnt(8)
	s_waitcnt lgkmcnt(0)
	s_barrier
	s_setprio 1
	s_waitcnt lgkmcnt(0)
	v_mfma_f32_16x16x32_bf16 v[124:127], v[144:147], v[184:187], v[124:127]
	v_mfma_f32_16x16x32_bf16 v[120:123], v[160:163], v[184:187], v[120:123]
	v_mfma_f32_16x16x32_bf16 v[108:111], v[144:147], v[192:195], v[108:111]
	v_mfma_f32_16x16x32_bf16 v[104:107], v[160:163], v[192:195], v[104:107]
	v_mfma_f32_16x16x32_bf16 v[92:95], v[144:147], v[200:203], v[92:95]
	v_mfma_f32_16x16x32_bf16 v[88:91], v[160:163], v[200:203], v[88:91]
	v_mfma_f32_16x16x32_bf16 v[76:79], v[144:147], v[208:211], v[76:79]
	v_mfma_f32_16x16x32_bf16 v[72:75], v[160:163], v[208:211], v[72:75]
	v_mfma_f32_16x16x32_bf16 v[124:127], v[148:151], v[188:191], v[124:127]
	v_mfma_f32_16x16x32_bf16 v[120:123], v[164:167], v[188:191], v[120:123]
	v_mfma_f32_16x16x32_bf16 v[108:111], v[148:151], v[196:199], v[108:111]
	v_mfma_f32_16x16x32_bf16 v[104:107], v[164:167], v[196:199], v[104:107]
	v_mfma_f32_16x16x32_bf16 v[92:95], v[148:151], v[204:207], v[92:95]
	v_mfma_f32_16x16x32_bf16 v[88:91], v[164:167], v[204:207], v[88:91]
	v_mfma_f32_16x16x32_bf16 v[76:79], v[148:151], v[212:215], v[76:79]
	v_mfma_f32_16x16x32_bf16 v[72:75], v[164:167], v[212:215], v[72:75]
	s_setprio 0
	s_setprio 1
	v_mfma_f32_16x16x32_bf16 v[116:119], v[168:171], v[184:187], v[116:119]
	v_mfma_f32_16x16x32_bf16 v[112:115], v[176:179], v[184:187], v[112:115]
	v_mfma_f32_16x16x32_bf16 v[100:103], v[168:171], v[192:195], v[100:103]
	v_mfma_f32_16x16x32_bf16 v[96:99], v[176:179], v[192:195], v[96:99]
	v_mfma_f32_16x16x32_bf16 v[84:87], v[168:171], v[200:203], v[84:87]
	v_mfma_f32_16x16x32_bf16 v[80:83], v[176:179], v[200:203], v[80:83]
	v_mfma_f32_16x16x32_bf16 v[68:71], v[168:171], v[208:211], v[68:71]
	v_mfma_f32_16x16x32_bf16 v[64:67], v[176:179], v[208:211], v[64:67]
	v_mfma_f32_16x16x32_bf16 v[116:119], v[172:175], v[188:191], v[116:119]
	v_mfma_f32_16x16x32_bf16 v[112:115], v[180:183], v[188:191], v[112:115]
	v_mfma_f32_16x16x32_bf16 v[100:103], v[172:175], v[196:199], v[100:103]
	v_mfma_f32_16x16x32_bf16 v[96:99], v[180:183], v[196:199], v[96:99]
	v_mfma_f32_16x16x32_bf16 v[84:87], v[172:175], v[204:207], v[84:87]
	v_mfma_f32_16x16x32_bf16 v[80:83], v[180:183], v[204:207], v[80:83]
	v_mfma_f32_16x16x32_bf16 v[68:71], v[172:175], v[212:215], v[68:71]
	v_mfma_f32_16x16x32_bf16 v[64:67], v[180:183], v[212:215], v[64:67]
	s_setprio 0
	s_barrier
	s_add_i32 s75, s66, s11
	v_lshl_add_u64 v[216:217], s[60:61], 0, v[132:133]
	s_mov_b32 m0, s75
	ds_read_b128 v[184:187], v157 offset:16384
	ds_read_b128 v[188:191], v157 offset:17408
	ds_read_b128 v[192:195], v157 offset:18432
	ds_read_b128 v[196:199], v157 offset:19456
	ds_read_b128 v[200:203], v157 offset:20480
	ds_read_b128 v[204:207], v157 offset:21504
	ds_read_b128 v[208:211], v157 offset:22528
	ds_read_b128 v[212:215], v157 offset:23552
	global_load_lds_dwordx4 v[216:217], off
	s_add_i32 m0, s75, 0x2000
	s_add_u32 s76, s60, 0x80000
	v_lshl_add_u64 v[218:219], s[60:61], 0, v[128:129]
	s_addc_u32 s77, s61, 0
	s_add_i32 s75, s67, s11
	global_load_lds_dwordx4 v[218:219], off
	v_lshl_add_u64 v[220:221], s[76:77], 0, v[132:133]
	s_mov_b32 m0, s75
	v_lshl_add_u64 v[222:223], s[62:63], 0, v[130:131]
	global_load_lds_dwordx4 v[220:221], off
	v_lshl_add_u64 v[220:221], s[76:77], 0, v[128:129]
	s_add_i32 m0, s75, 0x2000
	s_nop 0
	global_load_lds_dwordx4 v[220:221], off
	v_lshl_add_u64 v[220:221], s[62:63], 0, v[134:135]
	s_mov_b32 m0, s48
	s_nop 0
	global_load_lds_dwordx4 v[220:221], off
	s_mov_b32 m0, s49
	s_nop 0
	global_load_lds_dwordx4 v[222:223], off
	s_waitcnt vmcnt(8)
	s_waitcnt lgkmcnt(0)
	s_barrier
; #define PG8_STAGE(bufoff, gbase, voff) do { _Pragma("unroll") for (int _i = 0; _i < 2; ++_i) \
;         __builtin_amdgcn_global_load_lds((const unsigned*)((const char*)(gbase) + (voff)[_i]), (PG8_LAS unsigned*)(lds + (bufoff) + ldsw + _i * 8192), 16, 0, 0); } while (0)
; #define PG8_LDA(dst, b, h) do { _Pragma("unroll") for (int m = 0; m < 4; ++m) _Pragma("unroll") for (int k = 0; k < 2; ++k) dst[m][k] = *(const PG8_LAS bf16x8*)(lds + PG8_SA(b, h) + aoff + m * 2048 + k * 1024); } while (0)
; #define PG8_LDB(dst, b, h) do { _Pragma("unroll") for (int n = 0; n < 2; ++n) _Pragma("unroll") for (int k = 0; k < 2; ++k) dst[n][k] = *(const PG8_LAS bf16x8*)(lds + PG8_SB(b, h) + boff + n * 2048 + k * 1024); } while (0)
; #define PG8_MMA(ai, bj, At, Bt) do { __builtin_amdgcn_s_setprio(1); _Pragma("unroll") for (int m = 0; m < 4; ++m) _Pragma("unroll") for (int n = 0; n < 2; ++n) _Pragma("unroll") for (int k = 0; k < 2; ++k) \
;         acc[ai][bj][m][n] = __builtin_amdgcn_mfma_f32_16x16x32_bf16(Bt[n][k], At[m][k], acc[ai][bj][m][n], 0, 0, 0); __builtin_amdgcn_s_setprio(0); } while (0)
; #define PG8_WAIT_V(n) asm volatile("s_waitcnt vmcnt(" #n ")" ::: "memory")
; #define PG8_WAIT_L(n) asm volatile("s_waitcnt lgkmcnt(" #n ")" ::: "memory")
; #define PG8_BAR __builtin_amdgcn_s_barrier()
; #define PG8_SCHED __builtin_amdgcn_sched_barrier(0)
; template <class Epi, class Sched, bool ALIGN_EPI = false, bool SP2 = false>
; __device__ __forceinline__ void gemm_phase(PG8_LAS unsigned char* lds, const Gemm g, const Sched& S, const Epi& E, const int wave_in) {
;     ...
;             PG8_WAIT_V(8); PG8_WAIT_L(0); PG8_BAR; PG8_MMA(1, 0, At, B0); PG8_MMA(1, 1, At, B1); PG8_BAR; PG8_SCHED;
;             PG8_LDB(B0, 1, 0); PG8_LDB(B1, 1, 1); PG8_SCHED; PG8_LDA(At, 1, 0); PG8_STAGE(PG8_SA(0, 1), a2 + hstepA, voffA);
;             PG8_WAIT_V(8); PG8_WAIT_L(0); PG8_BAR; PG8_MMA(0, 0, At, B0); PG8_MMA(0, 1, At, B1); PG8_BAR; PG8_SCHED;
	s_setprio 1
	s_waitcnt lgkmcnt(0)
	v_mfma_f32_16x16x32_bf16 v[60:63], v[144:147], v[184:187], v[60:63]
	v_mfma_f32_16x16x32_bf16 v[56:59], v[160:163], v[184:187], v[56:59]
	v_mfma_f32_16x16x32_bf16 v[44:47], v[144:147], v[192:195], v[44:47]
	v_mfma_f32_16x16x32_bf16 v[40:43], v[160:163], v[192:195], v[40:43]
	v_mfma_f32_16x16x32_bf16 v[28:31], v[144:147], v[200:203], v[28:31]
	v_mfma_f32_16x16x32_bf16 v[24:27], v[160:163], v[200:203], v[24:27]
	v_mfma_f32_16x16x32_bf16 v[12:15], v[144:147], v[208:211], v[12:15]
	v_mfma_f32_16x16x32_bf16 v[8:11], v[160:163], v[208:211], v[8:11]
	v_mfma_f32_16x16x32_bf16 v[60:63], v[148:151], v[188:191], v[60:63]
	v_mfma_f32_16x16x32_bf16 v[56:59], v[164:167], v[188:191], v[56:59]
	v_mfma_f32_16x16x32_bf16 v[44:47], v[148:151], v[196:199], v[44:47]
	v_mfma_f32_16x16x32_bf16 v[40:43], v[164:167], v[196:199], v[40:43]
	v_mfma_f32_16x16x32_bf16 v[28:31], v[148:151], v[204:207], v[28:31]
	v_mfma_f32_16x16x32_bf16 v[24:27], v[164:167], v[204:207], v[24:27]
	v_mfma_f32_16x16x32_bf16 v[12:15], v[148:151], v[212:215], v[12:15]
	v_mfma_f32_16x16x32_bf16 v[8:11], v[164:167], v[212:215], v[8:11]
	s_setprio 0
	s_setprio 1
	v_mfma_f32_16x16x32_bf16 v[52:55], v[168:171], v[184:187], v[52:55]
	v_mfma_f32_16x16x32_bf16 v[48:51], v[176:179], v[184:187], v[48:51]
	v_mfma_f32_16x16x32_bf16 v[36:39], v[168:171], v[192:195], v[36:39]
	v_mfma_f32_16x16x32_bf16 v[32:35], v[176:179], v[192:195], v[32:35]
	v_mfma_f32_16x16x32_bf16 v[20:23], v[168:171], v[200:203], v[20:23]
	v_mfma_f32_16x16x32_bf16 v[16:19], v[176:179], v[200:203], v[16:19]
	v_mfma_f32_16x16x32_bf16 v[4:7], v[168:171], v[208:211], v[4:7]
	v_mfma_f32_16x16x32_bf16 v[0:3], v[176:179], v[208:211], v[0:3]
	v_mfma_f32_16x16x32_bf16 v[52:55], v[172:175], v[188:191], v[52:55]
	v_mfma_f32_16x16x32_bf16 v[48:51], v[180:183], v[188:191], v[48:51]
	v_mfma_f32_16x16x32_bf16 v[36:39], v[172:175], v[196:199], v[36:39]
	v_mfma_f32_16x16x32_bf16 v[32:35], v[180:183], v[196:199], v[32:35]
	v_mfma_f32_16x16x32_bf16 v[20:23], v[172:175], v[204:207], v[20:23]
	v_mfma_f32_16x16x32_bf16 v[16:19], v[180:183], v[204:207], v[16:19]
	v_mfma_f32_16x16x32_bf16 v[4:7], v[172:175], v[212:215], v[4:7]
	v_mfma_f32_16x16x32_bf16 v[0:3], v[180:183], v[212:215], v[0:3]
	s_setprio 0
	s_barrier
	s_add_i32 s75, 0, 0x18000
	v_add_u32_e32 v159, s75, v153
	s_add_i32 s76, 0, 0x1c000
	ds_read_b128 v[144:147], v159
	ds_read_b128 v[148:151], v159 offset:1024
	ds_read_b128 v[160:163], v159 offset:2048
	ds_read_b128 v[164:167], v159 offset:3072
	v_add_u32_e32 v159, s76, v153
	ds_read_b128 v[168:171], v159
	ds_read_b128 v[172:175], v159 offset:1024
	ds_read_b128 v[176:179], v159 offset:2048
	ds_read_b128 v[180:183], v159 offset:3072
	s_add_u32 s62, s62, 0x80000
	s_addc_u32 s63, s63, 0
	s_mov_b32 m0, s50
	v_lshl_add_u64 v[224:225], s[62:63], 0, v[134:135]
	ds_read_b128 v[184:187], v157 offset:32768
	ds_read_b128 v[188:191], v157 offset:33792
	ds_read_b128 v[192:195], v157 offset:34816
	ds_read_b128 v[196:199], v157 offset:35840
	ds_read_b128 v[200:203], v157 offset:36864
	ds_read_b128 v[204:207], v157 offset:37888
	ds_read_b128 v[208:211], v157 offset:38912
	ds_read_b128 v[212:215], v157 offset:39936
	global_load_lds_dwordx4 v[224:225], off
	v_lshl_add_u64 v[224:225], s[62:63], 0, v[130:131]
	s_mov_b32 m0, s51
	s_nop 0
	global_load_lds_dwordx4 v[224:225], off
	s_waitcnt vmcnt(8)
	s_waitcnt lgkmcnt(0)
	s_barrier
	s_setprio 1
	s_waitcnt lgkmcnt(0)
	v_mfma_f32_16x16x32_bf16 v[124:127], v[144:147], v[184:187], v[124:127]
	v_mfma_f32_16x16x32_bf16 v[120:123], v[160:163], v[184:187], v[120:123]
	v_mfma_f32_16x16x32_bf16 v[108:111], v[144:147], v[192:195], v[108:111]
	v_mfma_f32_16x16x32_bf16 v[104:107], v[160:163], v[192:195], v[104:107]
	v_mfma_f32_16x16x32_bf16 v[92:95], v[144:147], v[200:203], v[92:95]
	v_mfma_f32_16x16x32_bf16 v[88:91], v[160:163], v[200:203], v[88:91]
	v_mfma_f32_16x16x32_bf16 v[76:79], v[144:147], v[208:211], v[76:79]
	v_mfma_f32_16x16x32_bf16 v[72:75], v[160:163], v[208:211], v[72:75]
	v_mfma_f32_16x16x32_bf16 v[124:127], v[148:151], v[188:191], v[124:127]
	v_mfma_f32_16x16x32_bf16 v[120:123], v[164:167], v[188:191], v[120:123]
	v_mfma_f32_16x16x32_bf16 v[108:111], v[148:151], v[196:199], v[108:111]
	v_mfma_f32_16x16x32_bf16 v[104:107], v[164:167], v[196:199], v[104:107]
	v_mfma_f32_16x16x32_bf16 v[92:95], v[148:151], v[204:207], v[92:95]
	v_mfma_f32_16x16x32_bf16 v[88:91], v[164:167], v[204:207], v[88:91]
	v_mfma_f32_16x16x32_bf16 v[76:79], v[148:151], v[212:215], v[76:79]
	v_mfma_f32_16x16x32_bf16 v[72:75], v[164:167], v[212:215], v[72:75]
	s_setprio 0
	s_setprio 1
	v_mfma_f32_16x16x32_bf16 v[116:119], v[168:171], v[184:187], v[116:119]
	v_mfma_f32_16x16x32_bf16 v[112:115], v[176:179], v[184:187], v[112:115]
	v_mfma_f32_16x16x32_bf16 v[100:103], v[168:171], v[192:195], v[100:103]
	v_mfma_f32_16x16x32_bf16 v[96:99], v[176:179], v[192:195], v[96:99]
	v_mfma_f32_16x16x32_bf16 v[84:87], v[168:171], v[200:203], v[84:87]
	v_mfma_f32_16x16x32_bf16 v[80:83], v[176:179], v[200:203], v[80:83]
	v_mfma_f32_16x16x32_bf16 v[68:71], v[168:171], v[208:211], v[68:71]
	v_mfma_f32_16x16x32_bf16 v[64:67], v[176:179], v[208:211], v[64:67]
	v_mfma_f32_16x16x32_bf16 v[116:119], v[172:175], v[188:191], v[116:119]
	v_mfma_f32_16x16x32_bf16 v[112:115], v[180:183], v[188:191], v[112:115]
	v_mfma_f32_16x16x32_bf16 v[100:103], v[172:175], v[196:199], v[100:103]
	v_mfma_f32_16x16x32_bf16 v[96:99], v[180:183], v[196:199], v[96:99]
	v_mfma_f32_16x16x32_bf16 v[84:87], v[172:175], v[204:207], v[84:87]
	v_mfma_f32_16x16x32_bf16 v[80:83], v[180:183], v[204:207], v[80:83]
	v_mfma_f32_16x16x32_bf16 v[68:71], v[172:175], v[212:215], v[68:71]
	v_mfma_f32_16x16x32_bf16 v[64:67], v[180:183], v[212:215], v[64:67]
	s_setprio 0
	s_barrier
; #define PG8_STAGE(bufoff, gbase, voff) do { _Pragma("unroll") for (int _i = 0; _i < 2; ++_i) \
;         __builtin_amdgcn_global_load_lds((const unsigned*)((const char*)(gbase) + (voff)[_i]), (PG8_LAS unsigned*)(lds + (bufoff) + ldsw + _i * 8192), 16, 0, 0); } while (0)
; #define PG8_LDA(dst, b, h) do { _Pragma("unroll") for (int m = 0; m < 4; ++m) _Pragma("unroll") for (int k = 0; k < 2; ++k) dst[m][k] = *(const PG8_LAS bf16x8*)(lds + PG8_SA(b, h) + aoff + m * 2048 + k * 1024); } while (0)
; #define PG8_MMA(ai, bj, At, Bt) do { __builtin_amdgcn_s_setprio(1); _Pragma("unroll") for (int m = 0; m < 4; ++m) _Pragma("unroll") for (int n = 0; n < 2; ++n) _Pragma("unroll") for (int k = 0; k < 2; ++k) \
;         acc[ai][bj][m][n] = __builtin_amdgcn_mfma_f32_16x16x32_bf16(Bt[n][k], At[m][k], acc[ai][bj][m][n], 0, 0, 0); __builtin_amdgcn_s_setprio(0); } while (0)
; #define PG8_WAIT_V(n) asm volatile("s_waitcnt vmcnt(" #n ")" ::: "memory")
; #define PG8_WAIT_L(n) asm volatile("s_waitcnt lgkmcnt(" #n ")" ::: "memory")
; #define PG8_BAR __builtin_amdgcn_s_barrier()
; #define PG8_SCHED __builtin_amdgcn_sched_barrier(0)
; template <class Epi, class Sched, bool ALIGN_EPI = false, bool SP2 = false>
; __device__ __forceinline__ void gemm_phase(PG8_LAS unsigned char* lds, const Gemm g, const Sched& S, const Epi& E, const int wave_in) {
;     ...
;         for (int t = 0; t < nt; t += 2) {
;             const bool last = (t == nt - 2);
;     ...
;             PG8_LDA(At, 1, 1); PG8_STAGE(PG8_SB(1, 0), b3, voffB); PG8_STAGE(PG8_SB(1, 1), b3 + hstep, voffB); PG8_STAGE(PG8_SA(1, 0), a3, voffA);
;             PG8_WAIT_V(8); PG8_WAIT_L(0); PG8_BAR; PG8_MMA(1, 0, At, B0); PG8_MMA(1, 1, At, B1); PG8_BAR; PG8_SCHED;
	s_add_i32 s62, s75, s11
	v_lshl_add_u64 v[216:217], v[216:217], 0, s[6:7]
	s_mov_b32 m0, s62
	ds_read_b128 v[184:187], v157 offset:49152
	ds_read_b128 v[188:191], v157 offset:50176
	ds_read_b128 v[192:195], v157 offset:51200
	ds_read_b128 v[196:199], v157 offset:52224
	ds_read_b128 v[200:203], v157 offset:53248
	ds_read_b128 v[204:207], v157 offset:54272
	ds_read_b128 v[208:211], v157 offset:55296
	ds_read_b128 v[212:215], v157 offset:56320
	global_load_lds_dwordx4 v[216:217], off
	s_add_i32 m0, s62, 0x2000
	s_add_u32 s60, s60, 0x80080
	v_lshl_add_u64 v[216:217], v[218:219], 0, s[6:7]
	s_addc_u32 s61, s61, 0
	s_add_i32 s62, s76, s11
	global_load_lds_dwordx4 v[216:217], off
	v_lshl_add_u64 v[216:217], s[60:61], 0, v[132:133]
	s_mov_b32 m0, s62
	s_nop 0
	global_load_lds_dwordx4 v[216:217], off
	v_lshl_add_u64 v[216:217], s[60:61], 0, v[128:129]
	s_add_i32 m0, s62, 0x2000
	s_nop 0
	global_load_lds_dwordx4 v[216:217], off
	v_lshl_add_u64 v[216:217], v[220:221], 0, s[6:7]
	s_mov_b32 m0, s64
	s_nop 0
	global_load_lds_dwordx4 v[216:217], off
	v_lshl_add_u64 v[216:217], v[222:223], 0, s[6:7]
	s_mov_b32 m0, s65
	s_nop 0
	global_load_lds_dwordx4 v[216:217], off
	s_waitcnt vmcnt(8)
	s_waitcnt lgkmcnt(0)
	s_barrier
	s_setprio 1
	s_waitcnt lgkmcnt(0)
	v_mfma_f32_16x16x32_bf16 v[60:63], v[144:147], v[184:187], v[60:63]
	v_mfma_f32_16x16x32_bf16 v[56:59], v[160:163], v[184:187], v[56:59]
	v_mfma_f32_16x16x32_bf16 v[44:47], v[144:147], v[192:195], v[44:47]
	v_mfma_f32_16x16x32_bf16 v[40:43], v[160:163], v[192:195], v[40:43]
	v_mfma_f32_16x16x32_bf16 v[28:31], v[144:147], v[200:203], v[28:31]
	v_mfma_f32_16x16x32_bf16 v[24:27], v[160:163], v[200:203], v[24:27]
	v_mfma_f32_16x16x32_bf16 v[12:15], v[144:147], v[208:211], v[12:15]
	v_mfma_f32_16x16x32_bf16 v[8:11], v[160:163], v[208:211], v[8:11]
	v_mfma_f32_16x16x32_bf16 v[60:63], v[148:151], v[188:191], v[60:63]
	v_mfma_f32_16x16x32_bf16 v[56:59], v[164:167], v[188:191], v[56:59]
	v_mfma_f32_16x16x32_bf16 v[44:47], v[148:151], v[196:199], v[44:47]
	v_mfma_f32_16x16x32_bf16 v[40:43], v[164:167], v[196:199], v[40:43]
	v_mfma_f32_16x16x32_bf16 v[28:31], v[148:151], v[204:207], v[28:31]
	v_mfma_f32_16x16x32_bf16 v[24:27], v[164:167], v[204:207], v[24:27]
	v_mfma_f32_16x16x32_bf16 v[12:15], v[148:151], v[212:215], v[12:15]
	v_mfma_f32_16x16x32_bf16 v[8:11], v[164:167], v[212:215], v[8:11]
	s_setprio 0
	s_setprio 1
	v_mfma_f32_16x16x32_bf16 v[52:55], v[168:171], v[184:187], v[52:55]
	v_mfma_f32_16x16x32_bf16 v[48:51], v[176:179], v[184:187], v[48:51]
	v_mfma_f32_16x16x32_bf16 v[36:39], v[168:171], v[192:195], v[36:39]
	v_mfma_f32_16x16x32_bf16 v[32:35], v[176:179], v[192:195], v[32:35]
	v_mfma_f32_16x16x32_bf16 v[20:23], v[168:171], v[200:203], v[20:23]
	v_mfma_f32_16x16x32_bf16 v[16:19], v[176:179], v[200:203], v[16:19]
	v_mfma_f32_16x16x32_bf16 v[4:7], v[168:171], v[208:211], v[4:7]
	v_mfma_f32_16x16x32_bf16 v[0:3], v[176:179], v[208:211], v[0:3]
	v_mfma_f32_16x16x32_bf16 v[52:55], v[172:175], v[188:191], v[52:55]
	v_mfma_f32_16x16x32_bf16 v[48:51], v[180:183], v[188:191], v[48:51]
	v_mfma_f32_16x16x32_bf16 v[36:39], v[172:175], v[196:199], v[36:39]
	v_mfma_f32_16x16x32_bf16 v[32:35], v[180:183], v[196:199], v[32:35]
	v_mfma_f32_16x16x32_bf16 v[20:23], v[172:175], v[204:207], v[20:23]
	v_mfma_f32_16x16x32_bf16 v[16:19], v[180:183], v[204:207], v[16:19]
	v_mfma_f32_16x16x32_bf16 v[4:7], v[172:175], v[212:215], v[4:7]
	v_mfma_f32_16x16x32_bf16 v[0:3], v[180:183], v[212:215], v[0:3]
	s_setprio 0
	s_add_i32 s74, s74, 2
	s_add_u32 s58, s58, 0x100
	s_addc_u32 s59, s59, 0
	s_add_u32 s72, s72, 0x100
	s_addc_u32 s73, s73, 0
	s_cmp_gt_u32 s74, 29
	s_barrier
	s_cbranch_scc0 .LBB0_1734
	s_and_b64 vcc, exec, s[18:19]
	s_cbranch_vccz .LBB0_1737
	s_barrier

; #define PG8_STAGE(bufoff, gbase, voff) do { _Pragma("unroll") for (int _i = 0; _i < 2; ++_i) \
;         __builtin_amdgcn_global_load_lds((const unsigned*)((const char*)(gbase) + (voff)[_i]), (PG8_LAS unsigned*)(lds + (bufoff) + ldsw + _i * 8192), 16, 0, 0); } while (0)
; #define PG8_LDA(dst, b, h) do { _Pragma("unroll") for (int m = 0; m < 4; ++m) _Pragma("unroll") for (int k = 0; k < 2; ++k) dst[m][k] = *(const PG8_LAS bf16x8*)(lds + PG8_SA(b, h) + aoff + m * 2048 + k * 1024); } while (0)
; #define PG8_LDB(dst, b, h) do { _Pragma("unroll") for (int n = 0; n < 2; ++n) _Pragma("unroll") for (int k = 0; k < 2; ++k) dst[n][k] = *(const PG8_LAS bf16x8*)(lds + PG8_SB(b, h) + boff + n * 2048 + k * 1024); } while (0)
; #define PG8_MMA(ai, bj, At, Bt) do { __builtin_amdgcn_s_setprio(1); _Pragma("unroll") for (int m = 0; m < 4; ++m) _Pragma("unroll") for (int n = 0; n < 2; ++n) _Pragma("unroll") for (int k = 0; k < 2; ++k) \
;         acc[ai][bj][m][n] = __builtin_amdgcn_mfma_f32_16x16x32_bf16(Bt[n][k], At[m][k], acc[ai][bj][m][n], 0, 0, 0); __builtin_amdgcn_s_setprio(0); } while (0)
; #define PG8_WAIT_V(n) asm volatile("s_waitcnt vmcnt(" #n ")" ::: "memory")
; #define PG8_WAIT_L(n) asm volatile("s_waitcnt lgkmcnt(" #n ")" ::: "memory")
; template <class Epi, class Sched, bool ALIGN_EPI = false, bool SP2 = false>
; __device__ __forceinline__ void gemm_phase(PG8_LAS unsigned char* lds, const Gemm g, const Sched& S, const Epi& E, const int wave_in) {
;     ...
;             const bool last = (t == nt - 2);
;             const char* a1 = cA + (size_t)(t + 1) * kstep;
;             const char* a2 = last ? nA : cA + (size_t)(t + 2) * kstep; const char* b2 = last ? nB : cB + (size_t)(t + 2) * kstep;
;             const char* a3 = a2 + kstep; const char* b3 = b2 + kstep;
;             if (last && has_next) S.a_ready(nxt);
;             if constexpr (SP2) {
;             PG8_LDB(B0, 0, 0); PG8_LDB(B1, 0, 1); PG8_SCHED; PG8_LDA(At, 0, 0); PG8_STAGE(PG8_SA(1, 1), a1 + hstepA, voffA);
;             PG8_WAIT_V(8); PG8_WAIT_L(0); PG8_BAR; PG8_MMA(0, 0, At, B0); PG8_MMA(0, 1, At, B1); PG8_BAR; PG8_SCHED;
;             PG8_LDA(At, 0, 1); PG8_STAGE(PG8_SB(0, 0), b2, voffB); PG8_STAGE(PG8_SB(0, 1), b2 + hstep, voffB); PG8_STAGE(PG8_SA(0, 0), a2, voffA);
;             PG8_WAIT_V(8); PG8_WAIT_L(0); PG8_BAR; PG8_MMA(1, 0, At, B0); PG8_MMA(1, 1, At, B1); PG8_BAR; PG8_SCHED;
.LBB0_2082:
	ds_read_b128 v[144:147], v151
	ds_read_b128 v[156:159], v151 offset:1024
	ds_read_b128 v[160:163], v151 offset:2048
	ds_read_b128 v[164:167], v151 offset:3072
	ds_read_b128 v[168:171], v152
	ds_read_b128 v[172:175], v152 offset:1024
	ds_read_b128 v[176:179], v152 offset:2048
	ds_read_b128 v[180:183], v152 offset:3072
	s_add_u32 s40, s38, 0xfff80080
	s_addc_u32 s41, s39, -1
	s_cmp_eq_u32 s58, 28
	s_cselect_b32 s43, s19, s41
	s_cselect_b32 s42, s25, s40
	s_cselect_b32 s41, s17, s57
	s_cselect_b32 s40, s55, s56
	v_lshl_add_u64 v[216:217], s[38:39], 0, v[136:137]
	s_add_i32 m0, s33, 0xc000
	ds_read_b128 v[184:187], v153
	ds_read_b128 v[188:191], v153 offset:1024
	ds_read_b128 v[192:195], v153 offset:2048
	ds_read_b128 v[196:199], v153 offset:3072
	ds_read_b128 v[200:203], v153 offset:4096
	ds_read_b128 v[204:207], v153 offset:5120
	ds_read_b128 v[208:211], v153 offset:6144
	ds_read_b128 v[212:215], v153 offset:7168
	global_load_lds_dwordx4 v[216:217], off
	v_lshl_add_u64 v[216:217], s[38:39], 0, v[138:139]
	s_add_i32 m0, s33, 0xe000
	s_nop 0
	global_load_lds_dwordx4 v[216:217], off
	s_waitcnt vmcnt(8)
	s_waitcnt lgkmcnt(0)
	s_barrier
	s_setprio 1
	s_waitcnt lgkmcnt(0)
	v_mfma_f32_16x16x32_bf16 v[124:127], v[144:147], v[184:187], v[124:127]
	v_mfma_f32_16x16x32_bf16 v[120:123], v[160:163], v[184:187], v[120:123]
	v_mfma_f32_16x16x32_bf16 v[108:111], v[144:147], v[192:195], v[108:111]
	v_mfma_f32_16x16x32_bf16 v[104:107], v[160:163], v[192:195], v[104:107]
	v_mfma_f32_16x16x32_bf16 v[92:95], v[144:147], v[200:203], v[92:95]
	v_mfma_f32_16x16x32_bf16 v[88:91], v[160:163], v[200:203], v[88:91]
	v_mfma_f32_16x16x32_bf16 v[76:79], v[144:147], v[208:211], v[76:79]
	v_mfma_f32_16x16x32_bf16 v[72:75], v[160:163], v[208:211], v[72:75]
	v_mfma_f32_16x16x32_bf16 v[124:127], v[156:159], v[188:191], v[124:127]
	v_mfma_f32_16x16x32_bf16 v[120:123], v[164:167], v[188:191], v[120:123]
	v_mfma_f32_16x16x32_bf16 v[108:111], v[156:159], v[196:199], v[108:111]
	v_mfma_f32_16x16x32_bf16 v[104:107], v[164:167], v[196:199], v[104:107]
	v_mfma_f32_16x16x32_bf16 v[92:95], v[156:159], v[204:207], v[92:95]
	v_mfma_f32_16x16x32_bf16 v[88:91], v[164:167], v[204:207], v[88:91]
	v_mfma_f32_16x16x32_bf16 v[76:79], v[156:159], v[212:215], v[76:79]
	v_mfma_f32_16x16x32_bf16 v[72:75], v[164:167], v[212:215], v[72:75]
	s_setprio 0
	s_setprio 1
	v_mfma_f32_16x16x32_bf16 v[116:119], v[168:171], v[184:187], v[116:119]
	v_mfma_f32_16x16x32_bf16 v[112:115], v[176:179], v[184:187], v[112:115]
	v_mfma_f32_16x16x32_bf16 v[100:103], v[168:171], v[192:195], v[100:103]
	v_mfma_f32_16x16x32_bf16 v[96:99], v[176:179], v[192:195], v[96:99]
	v_mfma_f32_16x16x32_bf16 v[84:87], v[168:171], v[200:203], v[84:87]
	v_mfma_f32_16x16x32_bf16 v[80:83], v[176:179], v[200:203], v[80:83]
	v_mfma_f32_16x16x32_bf16 v[68:71], v[168:171], v[208:211], v[68:71]
	v_mfma_f32_16x16x32_bf16 v[64:67], v[176:179], v[208:211], v[64:67]
	v_mfma_f32_16x16x32_bf16 v[116:119], v[172:175], v[188:191], v[116:119]
	v_mfma_f32_16x16x32_bf16 v[112:115], v[180:183], v[188:191], v[112:115]
	v_mfma_f32_16x16x32_bf16 v[100:103], v[172:175], v[196:199], v[100:103]
	v_mfma_f32_16x16x32_bf16 v[96:99], v[180:183], v[196:199], v[96:99]
	v_mfma_f32_16x16x32_bf16 v[84:87], v[172:175], v[204:207], v[84:87]
	v_mfma_f32_16x16x32_bf16 v[80:83], v[180:183], v[204:207], v[80:83]
	v_mfma_f32_16x16x32_bf16 v[68:71], v[172:175], v[212:215], v[68:71]
	v_mfma_f32_16x16x32_bf16 v[64:67], v[180:183], v[212:215], v[64:67]
	s_setprio 0
	s_barrier
	s_add_i32 s59, s53, s11
	v_lshl_add_u64 v[216:217], s[40:41], 0, v[130:131]
	s_mov_b32 m0, s59
	ds_read_b128 v[184:187], v153 offset:16384
	ds_read_b128 v[188:191], v153 offset:17408
	ds_read_b128 v[192:195], v153 offset:18432
	ds_read_b128 v[196:199], v153 offset:19456
	ds_read_b128 v[200:203], v153 offset:20480
	ds_read_b128 v[204:207], v153 offset:21504
	ds_read_b128 v[208:211], v153 offset:22528
	ds_read_b128 v[212:215], v153 offset:23552
	global_load_lds_dwordx4 v[216:217], off
	s_add_i32 m0, s59, 0x2000
	s_add_u32 s60, s40, 0x80000
	v_lshl_add_u64 v[218:219], s[40:41], 0, v[134:135]
	s_addc_u32 s61, s41, 0
	s_add_i32 s59, s54, s11
	global_load_lds_dwordx4 v[218:219], off
	v_lshl_add_u64 v[220:221], s[60:61], 0, v[130:131]
	s_mov_b32 m0, s59
	v_lshl_add_u64 v[222:223], s[42:43], 0, v[132:133]
	global_load_lds_dwordx4 v[220:221], off
	v_lshl_add_u64 v[220:221], s[60:61], 0, v[134:135]
	s_add_i32 m0, s59, 0x2000
	s_nop 0
	global_load_lds_dwordx4 v[220:221], off
	v_lshl_add_u64 v[220:221], s[42:43], 0, v[128:129]
	s_mov_b32 m0, s33
	s_nop 0
	global_load_lds_dwordx4 v[220:221], off
	s_mov_b32 m0, s35
	s_nop 0
	global_load_lds_dwordx4 v[222:223], off
	s_waitcnt vmcnt(8)
	s_waitcnt lgkmcnt(0)
	s_barrier
; #define PG8_STAGE(bufoff, gbase, voff) do { _Pragma("unroll") for (int _i = 0; _i < 2; ++_i) \
;         __builtin_amdgcn_global_load_lds((const unsigned*)((const char*)(gbase) + (voff)[_i]), (PG8_LAS unsigned*)(lds + (bufoff) + ldsw + _i * 8192), 16, 0, 0); } while (0)
; #define PG8_LDA(dst, b, h) do { _Pragma("unroll") for (int m = 0; m < 4; ++m) _Pragma("unroll") for (int k = 0; k < 2; ++k) dst[m][k] = *(const PG8_LAS bf16x8*)(lds + PG8_SA(b, h) + aoff + m * 2048 + k * 1024); } while (0)
; #define PG8_LDB(dst, b, h) do { _Pragma("unroll") for (int n = 0; n < 2; ++n) _Pragma("unroll") for (int k = 0; k < 2; ++k) dst[n][k] = *(const PG8_LAS bf16x8*)(lds + PG8_SB(b, h) + boff + n * 2048 + k * 1024); } while (0)
; #define PG8_MMA(ai, bj, At, Bt) do { __builtin_amdgcn_s_setprio(1); _Pragma("unroll") for (int m = 0; m < 4; ++m) _Pragma("unroll") for (int n = 0; n < 2; ++n) _Pragma("unroll") for (int k = 0; k < 2; ++k) \
;         acc[ai][bj][m][n] = __builtin_amdgcn_mfma_f32_16x16x32_bf16(Bt[n][k], At[m][k], acc[ai][bj][m][n], 0, 0, 0); __builtin_amdgcn_s_setprio(0); } while (0)
; #define PG8_WAIT_V(n) asm volatile("s_waitcnt vmcnt(" #n ")" ::: "memory")
; #define PG8_WAIT_L(n) asm volatile("s_waitcnt lgkmcnt(" #n ")" ::: "memory")
; #define PG8_BAR __builtin_amdgcn_s_barrier()
; #define PG8_SCHED __builtin_amdgcn_sched_barrier(0)
; template <class Epi, class Sched, bool ALIGN_EPI = false, bool SP2 = false>
; __device__ __forceinline__ void gemm_phase(PG8_LAS unsigned char* lds, const Gemm g, const Sched& S, const Epi& E, const int wave_in) {
;     ...
;             PG8_WAIT_V(8); PG8_WAIT_L(0); PG8_BAR; PG8_MMA(1, 0, At, B0); PG8_MMA(1, 1, At, B1); PG8_BAR; PG8_SCHED;
;             PG8_LDB(B0, 1, 0); PG8_LDB(B1, 1, 1); PG8_SCHED; PG8_LDA(At, 1, 0); PG8_STAGE(PG8_SA(0, 1), a2 + hstepA, voffA);
;             PG8_WAIT_V(8); PG8_WAIT_L(0); PG8_BAR; PG8_MMA(0, 0, At, B0); PG8_MMA(0, 1, At, B1); PG8_BAR; PG8_SCHED;
	s_setprio 1
	s_waitcnt lgkmcnt(0)
	v_mfma_f32_16x16x32_bf16 v[60:63], v[144:147], v[184:187], v[60:63]
	v_mfma_f32_16x16x32_bf16 v[56:59], v[160:163], v[184:187], v[56:59]
	v_mfma_f32_16x16x32_bf16 v[44:47], v[144:147], v[192:195], v[44:47]
	v_mfma_f32_16x16x32_bf16 v[40:43], v[160:163], v[192:195], v[40:43]
	v_mfma_f32_16x16x32_bf16 v[28:31], v[144:147], v[200:203], v[28:31]
	v_mfma_f32_16x16x32_bf16 v[24:27], v[160:163], v[200:203], v[24:27]
	v_mfma_f32_16x16x32_bf16 v[12:15], v[144:147], v[208:211], v[12:15]
	v_mfma_f32_16x16x32_bf16 v[8:11], v[160:163], v[208:211], v[8:11]
	v_mfma_f32_16x16x32_bf16 v[60:63], v[156:159], v[188:191], v[60:63]
	v_mfma_f32_16x16x32_bf16 v[56:59], v[164:167], v[188:191], v[56:59]
	v_mfma_f32_16x16x32_bf16 v[44:47], v[156:159], v[196:199], v[44:47]
	v_mfma_f32_16x16x32_bf16 v[40:43], v[164:167], v[196:199], v[40:43]
	v_mfma_f32_16x16x32_bf16 v[28:31], v[156:159], v[204:207], v[28:31]
	v_mfma_f32_16x16x32_bf16 v[24:27], v[164:167], v[204:207], v[24:27]
	v_mfma_f32_16x16x32_bf16 v[12:15], v[156:159], v[212:215], v[12:15]
	v_mfma_f32_16x16x32_bf16 v[8:11], v[164:167], v[212:215], v[8:11]
	s_setprio 0
	s_setprio 1
	v_mfma_f32_16x16x32_bf16 v[52:55], v[168:171], v[184:187], v[52:55]
	v_mfma_f32_16x16x32_bf16 v[48:51], v[176:179], v[184:187], v[48:51]
	v_mfma_f32_16x16x32_bf16 v[36:39], v[168:171], v[192:195], v[36:39]
	v_mfma_f32_16x16x32_bf16 v[32:35], v[176:179], v[192:195], v[32:35]
	v_mfma_f32_16x16x32_bf16 v[20:23], v[168:171], v[200:203], v[20:23]
	v_mfma_f32_16x16x32_bf16 v[16:19], v[176:179], v[200:203], v[16:19]
	v_mfma_f32_16x16x32_bf16 v[4:7], v[168:171], v[208:211], v[4:7]
	v_mfma_f32_16x16x32_bf16 v[0:3], v[176:179], v[208:211], v[0:3]
	v_mfma_f32_16x16x32_bf16 v[52:55], v[172:175], v[188:191], v[52:55]
	v_mfma_f32_16x16x32_bf16 v[48:51], v[180:183], v[188:191], v[48:51]
	v_mfma_f32_16x16x32_bf16 v[36:39], v[172:175], v[196:199], v[36:39]
	v_mfma_f32_16x16x32_bf16 v[32:35], v[180:183], v[196:199], v[32:35]
	v_mfma_f32_16x16x32_bf16 v[20:23], v[172:175], v[204:207], v[20:23]
	v_mfma_f32_16x16x32_bf16 v[16:19], v[180:183], v[204:207], v[16:19]
	v_mfma_f32_16x16x32_bf16 v[4:7], v[172:175], v[212:215], v[4:7]
	v_mfma_f32_16x16x32_bf16 v[0:3], v[180:183], v[212:215], v[0:3]
	s_setprio 0
	s_barrier
	s_add_i32 s59, 0, 0x18000
	v_add_u32_e32 v155, s59, v149
	s_add_i32 s60, 0, 0x1c000
	ds_read_b128 v[144:147], v155
	ds_read_b128 v[156:159], v155 offset:1024
	ds_read_b128 v[160:163], v155 offset:2048
	ds_read_b128 v[164:167], v155 offset:3072
	v_add_u32_e32 v155, s60, v149
	ds_read_b128 v[168:171], v155
	ds_read_b128 v[172:175], v155 offset:1024
	ds_read_b128 v[176:179], v155 offset:2048
	ds_read_b128 v[180:183], v155 offset:3072
	s_add_u32 s42, s42, 0x80000
	s_addc_u32 s43, s43, 0
	s_mov_b32 m0, s37
	v_lshl_add_u64 v[224:225], s[42:43], 0, v[128:129]
	ds_read_b128 v[184:187], v153 offset:32768
	ds_read_b128 v[188:191], v153 offset:33792
	ds_read_b128 v[192:195], v153 offset:34816
	ds_read_b128 v[196:199], v153 offset:35840
	ds_read_b128 v[200:203], v153 offset:36864
	ds_read_b128 v[204:207], v153 offset:37888
	ds_read_b128 v[208:211], v153 offset:38912
	ds_read_b128 v[212:215], v153 offset:39936
	global_load_lds_dwordx4 v[224:225], off
	v_lshl_add_u64 v[224:225], s[42:43], 0, v[132:133]
	s_mov_b32 m0, s48
	s_nop 0
	global_load_lds_dwordx4 v[224:225], off
	s_waitcnt vmcnt(8)
	s_waitcnt lgkmcnt(0)
	s_barrier
	s_setprio 1
	s_waitcnt lgkmcnt(0)
	v_mfma_f32_16x16x32_bf16 v[124:127], v[144:147], v[184:187], v[124:127]
	v_mfma_f32_16x16x32_bf16 v[120:123], v[160:163], v[184:187], v[120:123]
	v_mfma_f32_16x16x32_bf16 v[108:111], v[144:147], v[192:195], v[108:111]
	v_mfma_f32_16x16x32_bf16 v[104:107], v[160:163], v[192:195], v[104:107]
	v_mfma_f32_16x16x32_bf16 v[92:95], v[144:147], v[200:203], v[92:95]
	v_mfma_f32_16x16x32_bf16 v[88:91], v[160:163], v[200:203], v[88:91]
	v_mfma_f32_16x16x32_bf16 v[76:79], v[144:147], v[208:211], v[76:79]
	v_mfma_f32_16x16x32_bf16 v[72:75], v[160:163], v[208:211], v[72:75]
	v_mfma_f32_16x16x32_bf16 v[124:127], v[156:159], v[188:191], v[124:127]
	v_mfma_f32_16x16x32_bf16 v[120:123], v[164:167], v[188:191], v[120:123]
	v_mfma_f32_16x16x32_bf16 v[108:111], v[156:159], v[196:199], v[108:111]
	v_mfma_f32_16x16x32_bf16 v[104:107], v[164:167], v[196:199], v[104:107]
	v_mfma_f32_16x16x32_bf16 v[92:95], v[156:159], v[204:207], v[92:95]
	v_mfma_f32_16x16x32_bf16 v[88:91], v[164:167], v[204:207], v[88:91]
	v_mfma_f32_16x16x32_bf16 v[76:79], v[156:159], v[212:215], v[76:79]
	v_mfma_f32_16x16x32_bf16 v[72:75], v[164:167], v[212:215], v[72:75]
	s_setprio 0
	s_setprio 1
	v_mfma_f32_16x16x32_bf16 v[116:119], v[168:171], v[184:187], v[116:119]
	v_mfma_f32_16x16x32_bf16 v[112:115], v[176:179], v[184:187], v[112:115]
	v_mfma_f32_16x16x32_bf16 v[100:103], v[168:171], v[192:195], v[100:103]
	v_mfma_f32_16x16x32_bf16 v[96:99], v[176:179], v[192:195], v[96:99]
	v_mfma_f32_16x16x32_bf16 v[84:87], v[168:171], v[200:203], v[84:87]
	v_mfma_f32_16x16x32_bf16 v[80:83], v[176:179], v[200:203], v[80:83]
	v_mfma_f32_16x16x32_bf16 v[68:71], v[168:171], v[208:211], v[68:71]
	v_mfma_f32_16x16x32_bf16 v[64:67], v[176:179], v[208:211], v[64:67]
	v_mfma_f32_16x16x32_bf16 v[116:119], v[172:175], v[188:191], v[116:119]
	v_mfma_f32_16x16x32_bf16 v[112:115], v[180:183], v[188:191], v[112:115]
	v_mfma_f32_16x16x32_bf16 v[100:103], v[172:175], v[196:199], v[100:103]
	v_mfma_f32_16x16x32_bf16 v[96:99], v[180:183], v[196:199], v[96:99]
	v_mfma_f32_16x16x32_bf16 v[84:87], v[172:175], v[204:207], v[84:87]
	v_mfma_f32_16x16x32_bf16 v[80:83], v[180:183], v[204:207], v[80:83]
	v_mfma_f32_16x16x32_bf16 v[68:71], v[172:175], v[212:215], v[68:71]
	v_mfma_f32_16x16x32_bf16 v[64:67], v[180:183], v[212:215], v[64:67]
	s_setprio 0
	s_barrier
; #define PG8_STAGE(bufoff, gbase, voff) do { _Pragma("unroll") for (int _i = 0; _i < 2; ++_i) \
;         __builtin_amdgcn_global_load_lds((const unsigned*)((const char*)(gbase) + (voff)[_i]), (PG8_LAS unsigned*)(lds + (bufoff) + ldsw + _i * 8192), 16, 0, 0); } while (0)
; #define PG8_LDA(dst, b, h) do { _Pragma("unroll") for (int m = 0; m < 4; ++m) _Pragma("unroll") for (int k = 0; k < 2; ++k) dst[m][k] = *(const PG8_LAS bf16x8*)(lds + PG8_SA(b, h) + aoff + m * 2048 + k * 1024); } while (0)
; #define PG8_MMA(ai, bj, At, Bt) do { __builtin_amdgcn_s_setprio(1); _Pragma("unroll") for (int m = 0; m < 4; ++m) _Pragma("unroll") for (int n = 0; n < 2; ++n) _Pragma("unroll") for (int k = 0; k < 2; ++k) \
;         acc[ai][bj][m][n] = __builtin_amdgcn_mfma_f32_16x16x32_bf16(Bt[n][k], At[m][k], acc[ai][bj][m][n], 0, 0, 0); __builtin_amdgcn_s_setprio(0); } while (0)
; #define PG8_WAIT_V(n) asm volatile("s_waitcnt vmcnt(" #n ")" ::: "memory")
; #define PG8_WAIT_L(n) asm volatile("s_waitcnt lgkmcnt(" #n ")" ::: "memory")
; #define PG8_BAR __builtin_amdgcn_s_barrier()
; #define PG8_SCHED __builtin_amdgcn_sched_barrier(0)
; template <class Epi, class Sched, bool ALIGN_EPI = false, bool SP2 = false>
; __device__ __forceinline__ void gemm_phase(PG8_LAS unsigned char* lds, const Gemm g, const Sched& S, const Epi& E, const int wave_in) {
;     ...
;         for (int t = 0; t < nt; t += 2) {
;             const bool last = (t == nt - 2);
;     ...
;             PG8_LDA(At, 1, 1); PG8_STAGE(PG8_SB(1, 0), b3, voffB); PG8_STAGE(PG8_SB(1, 1), b3 + hstep, voffB); PG8_STAGE(PG8_SA(1, 0), a3, voffA);
;             PG8_WAIT_V(8); PG8_WAIT_L(0); PG8_BAR; PG8_MMA(1, 0, At, B0); PG8_MMA(1, 1, At, B1); PG8_BAR; PG8_SCHED;
	s_add_i32 s42, s59, s11
	v_lshl_add_u64 v[216:217], v[216:217], 0, s[12:13]
	s_mov_b32 m0, s42
	ds_read_b128 v[184:187], v153 offset:49152
	ds_read_b128 v[188:191], v153 offset:50176
	ds_read_b128 v[192:195], v153 offset:51200
	ds_read_b128 v[196:199], v153 offset:52224
	ds_read_b128 v[200:203], v153 offset:53248
	ds_read_b128 v[204:207], v153 offset:54272
	ds_read_b128 v[208:211], v153 offset:55296
	ds_read_b128 v[212:215], v153 offset:56320
	global_load_lds_dwordx4 v[216:217], off
	s_add_i32 m0, s42, 0x2000
	s_add_u32 s40, s40, 0x80080
	v_lshl_add_u64 v[216:217], v[218:219], 0, s[12:13]
	s_addc_u32 s41, s41, 0
	s_add_i32 s42, s60, s11
	global_load_lds_dwordx4 v[216:217], off
	v_lshl_add_u64 v[216:217], s[40:41], 0, v[130:131]
	s_mov_b32 m0, s42
	s_nop 0
	global_load_lds_dwordx4 v[216:217], off
	v_lshl_add_u64 v[216:217], s[40:41], 0, v[134:135]
	s_add_i32 m0, s42, 0x2000
	s_nop 0
	global_load_lds_dwordx4 v[216:217], off
	v_lshl_add_u64 v[216:217], v[220:221], 0, s[12:13]
	s_mov_b32 m0, s50
	s_nop 0
	global_load_lds_dwordx4 v[216:217], off
	v_lshl_add_u64 v[216:217], v[222:223], 0, s[12:13]
	s_mov_b32 m0, s51
	s_nop 0
	global_load_lds_dwordx4 v[216:217], off
	s_waitcnt vmcnt(8)
	s_waitcnt lgkmcnt(0)
	s_barrier
	s_setprio 1
	s_waitcnt lgkmcnt(0)
	v_mfma_f32_16x16x32_bf16 v[60:63], v[144:147], v[184:187], v[60:63]
	v_mfma_f32_16x16x32_bf16 v[56:59], v[160:163], v[184:187], v[56:59]
	v_mfma_f32_16x16x32_bf16 v[44:47], v[144:147], v[192:195], v[44:47]
	v_mfma_f32_16x16x32_bf16 v[40:43], v[160:163], v[192:195], v[40:43]
	v_mfma_f32_16x16x32_bf16 v[28:31], v[144:147], v[200:203], v[28:31]
	v_mfma_f32_16x16x32_bf16 v[24:27], v[160:163], v[200:203], v[24:27]
	v_mfma_f32_16x16x32_bf16 v[12:15], v[144:147], v[208:211], v[12:15]
	v_mfma_f32_16x16x32_bf16 v[8:11], v[160:163], v[208:211], v[8:11]
	v_mfma_f32_16x16x32_bf16 v[60:63], v[156:159], v[188:191], v[60:63]
	v_mfma_f32_16x16x32_bf16 v[56:59], v[164:167], v[188:191], v[56:59]
	v_mfma_f32_16x16x32_bf16 v[44:47], v[156:159], v[196:199], v[44:47]
	v_mfma_f32_16x16x32_bf16 v[40:43], v[164:167], v[196:199], v[40:43]
	v_mfma_f32_16x16x32_bf16 v[28:31], v[156:159], v[204:207], v[28:31]
	v_mfma_f32_16x16x32_bf16 v[24:27], v[164:167], v[204:207], v[24:27]
	v_mfma_f32_16x16x32_bf16 v[12:15], v[156:159], v[212:215], v[12:15]
	v_mfma_f32_16x16x32_bf16 v[8:11], v[164:167], v[212:215], v[8:11]
	s_setprio 0
	s_setprio 1
	v_mfma_f32_16x16x32_bf16 v[52:55], v[168:171], v[184:187], v[52:55]
	v_mfma_f32_16x16x32_bf16 v[48:51], v[176:179], v[184:187], v[48:51]
	v_mfma_f32_16x16x32_bf16 v[36:39], v[168:171], v[192:195], v[36:39]
	v_mfma_f32_16x16x32_bf16 v[32:35], v[176:179], v[192:195], v[32:35]
	v_mfma_f32_16x16x32_bf16 v[20:23], v[168:171], v[200:203], v[20:23]
	v_mfma_f32_16x16x32_bf16 v[16:19], v[176:179], v[200:203], v[16:19]
	v_mfma_f32_16x16x32_bf16 v[4:7], v[168:171], v[208:211], v[4:7]
	v_mfma_f32_16x16x32_bf16 v[0:3], v[176:179], v[208:211], v[0:3]
	v_mfma_f32_16x16x32_bf16 v[52:55], v[172:175], v[188:191], v[52:55]
	v_mfma_f32_16x16x32_bf16 v[48:51], v[180:183], v[188:191], v[48:51]
	v_mfma_f32_16x16x32_bf16 v[36:39], v[172:175], v[196:199], v[36:39]
	v_mfma_f32_16x16x32_bf16 v[32:35], v[180:183], v[196:199], v[32:35]
	v_mfma_f32_16x16x32_bf16 v[20:23], v[172:175], v[204:207], v[20:23]
	v_mfma_f32_16x16x32_bf16 v[16:19], v[180:183], v[204:207], v[16:19]
	v_mfma_f32_16x16x32_bf16 v[4:7], v[172:175], v[212:215], v[4:7]
	v_mfma_f32_16x16x32_bf16 v[0:3], v[180:183], v[212:215], v[0:3]
	s_setprio 0
	s_add_i32 s58, s58, 2
	s_add_u32 s38, s38, 0x100
	s_addc_u32 s39, s39, 0
	s_add_u32 s56, s56, 0x100
	s_addc_u32 s57, s57, 0
	s_cmp_gt_u32 s58, 29
	s_barrier
	s_cbranch_scc0 .LBB0_2082
	s_and_b64 vcc, exec, s[14:15]
	s_cbranch_vccz .LBB0_2085
	s_barrier

; #define PG8_STAGE(bufoff, gbase, voff) do { _Pragma("unroll") for (int _i = 0; _i < 2; ++_i) \
;         __builtin_amdgcn_global_load_lds((const unsigned*)((const char*)(gbase) + (voff)[_i]), (PG8_LAS unsigned*)(lds + (bufoff) + ldsw + _i * 8192), 16, 0, 0); } while (0)
; #define PG8_LDA(dst, b, h) do { _Pragma("unroll") for (int m = 0; m < 4; ++m) _Pragma("unroll") for (int k = 0; k < 2; ++k) dst[m][k] = *(const PG8_LAS bf16x8*)(lds + PG8_SA(b, h) + aoff + m * 2048 + k * 1024); } while (0)
; #define PG8_LDB(dst, b, h) do { _Pragma("unroll") for (int n = 0; n < 2; ++n) _Pragma("unroll") for (int k = 0; k < 2; ++k) dst[n][k] = *(const PG8_LAS bf16x8*)(lds + PG8_SB(b, h) + boff + n * 2048 + k * 1024); } while (0)
; #define PG8_MMA(ai, bj, At, Bt) do { __builtin_amdgcn_s_setprio(1); _Pragma("unroll") for (int m = 0; m < 4; ++m) _Pragma("unroll") for (int n = 0; n < 2; ++n) _Pragma("unroll") for (int k = 0; k < 2; ++k) \
;         acc[ai][bj][m][n] = __builtin_amdgcn_mfma_f32_16x16x32_bf16(Bt[n][k], At[m][k], acc[ai][bj][m][n], 0, 0, 0); __builtin_amdgcn_s_setprio(0); } while (0)
; #define PG8_WAIT_V(n) asm volatile("s_waitcnt vmcnt(" #n ")" ::: "memory")
; #define PG8_WAIT_L(n) asm volatile("s_waitcnt lgkmcnt(" #n ")" ::: "memory")
; template <class Epi, class Sched, bool ALIGN_EPI = false, bool SP2 = false>
; __device__ __forceinline__ void gemm_phase(PG8_LAS unsigned char* lds, const Gemm g, const Sched& S, const Epi& E, const int wave_in) {
;     ...
;             const bool last = (t == nt - 2);
;             const char* a1 = cA + (size_t)(t + 1) * kstep;
;             const char* a2 = last ? nA : cA + (size_t)(t + 2) * kstep; const char* b2 = last ? nB : cB + (size_t)(t + 2) * kstep;
;             const char* a3 = a2 + kstep; const char* b3 = b2 + kstep;
;             if (last && has_next) S.a_ready(nxt);
;             if constexpr (SP2) {
;             PG8_LDB(B0, 0, 0); PG8_LDB(B1, 0, 1); PG8_SCHED; PG8_LDA(At, 0, 0); PG8_STAGE(PG8_SA(1, 1), a1 + hstepA, voffA);
;             PG8_WAIT_V(8); PG8_WAIT_L(0); PG8_BAR; PG8_MMA(0, 0, At, B0); PG8_MMA(0, 1, At, B1); PG8_BAR; PG8_SCHED;
;             PG8_LDA(At, 0, 1); PG8_STAGE(PG8_SB(0, 0), b2, voffB); PG8_STAGE(PG8_SB(0, 1), b2 + hstep, voffB); PG8_STAGE(PG8_SA(0, 0), a2, voffA);
;             PG8_WAIT_V(8); PG8_WAIT_L(0); PG8_BAR; PG8_MMA(1, 0, At, B0); PG8_MMA(1, 1, At, B1); PG8_BAR; PG8_SCHED;
.LBB0_2169:
	ds_read_b128 v[144:147], v151
	ds_read_b128 v[156:159], v151 offset:1024
	ds_read_b128 v[160:163], v151 offset:2048
	ds_read_b128 v[164:167], v151 offset:3072
	ds_read_b128 v[168:171], v152
	ds_read_b128 v[172:175], v152 offset:1024
	ds_read_b128 v[176:179], v152 offset:2048
	ds_read_b128 v[180:183], v152 offset:3072
	s_add_u32 s36, s24, 0xfff80080
	s_addc_u32 s37, s25, -1
	s_cmp_eq_u32 s58, 28
	s_cselect_b32 s39, s17, s37
	s_cselect_b32 s38, s54, s36
	s_cselect_b32 s37, s15, s57
	s_cselect_b32 s36, s55, s56
	v_lshl_add_u64 v[216:217], s[24:25], 0, v[136:137]
	s_add_i32 m0, s23, 0xc000
	ds_read_b128 v[184:187], v153
	ds_read_b128 v[188:191], v153 offset:1024
	ds_read_b128 v[192:195], v153 offset:2048
	ds_read_b128 v[196:199], v153 offset:3072
	ds_read_b128 v[200:203], v153 offset:4096
	ds_read_b128 v[204:207], v153 offset:5120
	ds_read_b128 v[208:211], v153 offset:6144
	ds_read_b128 v[212:215], v153 offset:7168
	global_load_lds_dwordx4 v[216:217], off
	v_lshl_add_u64 v[216:217], s[24:25], 0, v[138:139]
	s_add_i32 m0, s23, 0xe000
	s_nop 0
	global_load_lds_dwordx4 v[216:217], off
	s_waitcnt vmcnt(8)
	s_waitcnt lgkmcnt(0)
	s_barrier
	s_setprio 1
	s_waitcnt lgkmcnt(0)
	v_mfma_f32_16x16x32_bf16 v[116:119], v[144:147], v[184:187], v[116:119]
	v_mfma_f32_16x16x32_bf16 v[112:115], v[160:163], v[184:187], v[112:115]
	v_mfma_f32_16x16x32_bf16 v[100:103], v[144:147], v[192:195], v[100:103]
	v_mfma_f32_16x16x32_bf16 v[96:99], v[160:163], v[192:195], v[96:99]
	v_mfma_f32_16x16x32_bf16 v[84:87], v[144:147], v[200:203], v[84:87]
	v_mfma_f32_16x16x32_bf16 v[80:83], v[160:163], v[200:203], v[80:83]
	v_mfma_f32_16x16x32_bf16 v[68:71], v[144:147], v[208:211], v[68:71]
	v_mfma_f32_16x16x32_bf16 v[64:67], v[160:163], v[208:211], v[64:67]
	v_mfma_f32_16x16x32_bf16 v[116:119], v[156:159], v[188:191], v[116:119]
	v_mfma_f32_16x16x32_bf16 v[112:115], v[164:167], v[188:191], v[112:115]
	v_mfma_f32_16x16x32_bf16 v[100:103], v[156:159], v[196:199], v[100:103]
	v_mfma_f32_16x16x32_bf16 v[96:99], v[164:167], v[196:199], v[96:99]
	v_mfma_f32_16x16x32_bf16 v[84:87], v[156:159], v[204:207], v[84:87]
	v_mfma_f32_16x16x32_bf16 v[80:83], v[164:167], v[204:207], v[80:83]
	v_mfma_f32_16x16x32_bf16 v[68:71], v[156:159], v[212:215], v[68:71]
	v_mfma_f32_16x16x32_bf16 v[64:67], v[164:167], v[212:215], v[64:67]
	s_setprio 0
	s_setprio 1
	v_mfma_f32_16x16x32_bf16 v[124:127], v[168:171], v[184:187], v[124:127]
	v_mfma_f32_16x16x32_bf16 v[120:123], v[176:179], v[184:187], v[120:123]
	v_mfma_f32_16x16x32_bf16 v[108:111], v[168:171], v[192:195], v[108:111]
	v_mfma_f32_16x16x32_bf16 v[104:107], v[176:179], v[192:195], v[104:107]
	v_mfma_f32_16x16x32_bf16 v[92:95], v[168:171], v[200:203], v[92:95]
	v_mfma_f32_16x16x32_bf16 v[88:91], v[176:179], v[200:203], v[88:91]
	v_mfma_f32_16x16x32_bf16 v[76:79], v[168:171], v[208:211], v[76:79]
	v_mfma_f32_16x16x32_bf16 v[72:75], v[176:179], v[208:211], v[72:75]
	v_mfma_f32_16x16x32_bf16 v[124:127], v[172:175], v[188:191], v[124:127]
	v_mfma_f32_16x16x32_bf16 v[120:123], v[180:183], v[188:191], v[120:123]
	v_mfma_f32_16x16x32_bf16 v[108:111], v[172:175], v[196:199], v[108:111]
	v_mfma_f32_16x16x32_bf16 v[104:107], v[180:183], v[196:199], v[104:107]
	v_mfma_f32_16x16x32_bf16 v[92:95], v[172:175], v[204:207], v[92:95]
	v_mfma_f32_16x16x32_bf16 v[88:91], v[180:183], v[204:207], v[88:91]
	v_mfma_f32_16x16x32_bf16 v[76:79], v[172:175], v[212:215], v[76:79]
	v_mfma_f32_16x16x32_bf16 v[72:75], v[180:183], v[212:215], v[72:75]
	s_setprio 0
	s_barrier
	s_add_i32 s59, s50, s11
	v_lshl_add_u64 v[216:217], s[36:37], 0, v[132:133]
	s_mov_b32 m0, s59
	ds_read_b128 v[184:187], v153 offset:16384
	ds_read_b128 v[188:191], v153 offset:17408
	ds_read_b128 v[192:195], v153 offset:18432
	ds_read_b128 v[196:199], v153 offset:19456
	ds_read_b128 v[200:203], v153 offset:20480
	ds_read_b128 v[204:207], v153 offset:21504
	ds_read_b128 v[208:211], v153 offset:22528
	ds_read_b128 v[212:215], v153 offset:23552
	global_load_lds_dwordx4 v[216:217], off
	s_add_i32 m0, s59, 0x2000
	s_add_u32 s60, s36, 0x80000
	v_lshl_add_u64 v[218:219], s[36:37], 0, v[128:129]
	s_addc_u32 s61, s37, 0
	s_add_i32 s59, s51, s11
	global_load_lds_dwordx4 v[218:219], off
	v_lshl_add_u64 v[220:221], s[60:61], 0, v[132:133]
	s_mov_b32 m0, s59
	v_lshl_add_u64 v[222:223], s[38:39], 0, v[130:131]
	global_load_lds_dwordx4 v[220:221], off
	v_lshl_add_u64 v[220:221], s[60:61], 0, v[128:129]
	s_add_i32 m0, s59, 0x2000
	s_nop 0
	global_load_lds_dwordx4 v[220:221], off
	v_lshl_add_u64 v[220:221], s[38:39], 0, v[134:135]
	s_mov_b32 m0, s23
	s_nop 0
	global_load_lds_dwordx4 v[220:221], off
	s_mov_b32 m0, s40
	s_nop 0
	global_load_lds_dwordx4 v[222:223], off
	s_waitcnt vmcnt(8)
	s_waitcnt lgkmcnt(0)
	s_barrier
; #define PG8_STAGE(bufoff, gbase, voff) do { _Pragma("unroll") for (int _i = 0; _i < 2; ++_i) \
;         __builtin_amdgcn_global_load_lds((const unsigned*)((const char*)(gbase) + (voff)[_i]), (PG8_LAS unsigned*)(lds + (bufoff) + ldsw + _i * 8192), 16, 0, 0); } while (0)
; #define PG8_LDA(dst, b, h) do { _Pragma("unroll") for (int m = 0; m < 4; ++m) _Pragma("unroll") for (int k = 0; k < 2; ++k) dst[m][k] = *(const PG8_LAS bf16x8*)(lds + PG8_SA(b, h) + aoff + m * 2048 + k * 1024); } while (0)
; #define PG8_LDB(dst, b, h) do { _Pragma("unroll") for (int n = 0; n < 2; ++n) _Pragma("unroll") for (int k = 0; k < 2; ++k) dst[n][k] = *(const PG8_LAS bf16x8*)(lds + PG8_SB(b, h) + boff + n * 2048 + k * 1024); } while (0)
; #define PG8_MMA(ai, bj, At, Bt) do { __builtin_amdgcn_s_setprio(1); _Pragma("unroll") for (int m = 0; m < 4; ++m) _Pragma("unroll") for (int n = 0; n < 2; ++n) _Pragma("unroll") for (int k = 0; k < 2; ++k) \
;         acc[ai][bj][m][n] = __builtin_amdgcn_mfma_f32_16x16x32_bf16(Bt[n][k], At[m][k], acc[ai][bj][m][n], 0, 0, 0); __builtin_amdgcn_s_setprio(0); } while (0)
; #define PG8_WAIT_V(n) asm volatile("s_waitcnt vmcnt(" #n ")" ::: "memory")
; #define PG8_WAIT_L(n) asm volatile("s_waitcnt lgkmcnt(" #n ")" ::: "memory")
; #define PG8_BAR __builtin_amdgcn_s_barrier()
; #define PG8_SCHED __builtin_amdgcn_sched_barrier(0)
; template <class Epi, class Sched, bool ALIGN_EPI = false, bool SP2 = false>
; __device__ __forceinline__ void gemm_phase(PG8_LAS unsigned char* lds, const Gemm g, const Sched& S, const Epi& E, const int wave_in) {
;     ...
;             PG8_WAIT_V(8); PG8_WAIT_L(0); PG8_BAR; PG8_MMA(1, 0, At, B0); PG8_MMA(1, 1, At, B1); PG8_BAR; PG8_SCHED;
;             PG8_LDB(B0, 1, 0); PG8_LDB(B1, 1, 1); PG8_SCHED; PG8_LDA(At, 1, 0); PG8_STAGE(PG8_SA(0, 1), a2 + hstepA, voffA);
;             PG8_WAIT_V(8); PG8_WAIT_L(0); PG8_BAR; PG8_MMA(0, 0, At, B0); PG8_MMA(0, 1, At, B1); PG8_BAR; PG8_SCHED;
	s_setprio 1
	s_waitcnt lgkmcnt(0)
	v_mfma_f32_16x16x32_bf16 v[52:55], v[144:147], v[184:187], v[52:55]
	v_mfma_f32_16x16x32_bf16 v[48:51], v[160:163], v[184:187], v[48:51]
	v_mfma_f32_16x16x32_bf16 v[36:39], v[144:147], v[192:195], v[36:39]
	v_mfma_f32_16x16x32_bf16 v[32:35], v[160:163], v[192:195], v[32:35]
	v_mfma_f32_16x16x32_bf16 v[20:23], v[144:147], v[200:203], v[20:23]
	v_mfma_f32_16x16x32_bf16 v[16:19], v[160:163], v[200:203], v[16:19]
	v_mfma_f32_16x16x32_bf16 v[4:7], v[144:147], v[208:211], v[4:7]
	v_mfma_f32_16x16x32_bf16 v[0:3], v[160:163], v[208:211], v[0:3]
	v_mfma_f32_16x16x32_bf16 v[52:55], v[156:159], v[188:191], v[52:55]
	v_mfma_f32_16x16x32_bf16 v[48:51], v[164:167], v[188:191], v[48:51]
	v_mfma_f32_16x16x32_bf16 v[36:39], v[156:159], v[196:199], v[36:39]
	v_mfma_f32_16x16x32_bf16 v[32:35], v[164:167], v[196:199], v[32:35]
	v_mfma_f32_16x16x32_bf16 v[20:23], v[156:159], v[204:207], v[20:23]
	v_mfma_f32_16x16x32_bf16 v[16:19], v[164:167], v[204:207], v[16:19]
	v_mfma_f32_16x16x32_bf16 v[4:7], v[156:159], v[212:215], v[4:7]
	v_mfma_f32_16x16x32_bf16 v[0:3], v[164:167], v[212:215], v[0:3]
	s_setprio 0
	s_setprio 1
	v_mfma_f32_16x16x32_bf16 v[60:63], v[168:171], v[184:187], v[60:63]
	v_mfma_f32_16x16x32_bf16 v[56:59], v[176:179], v[184:187], v[56:59]
	v_mfma_f32_16x16x32_bf16 v[44:47], v[168:171], v[192:195], v[44:47]
	v_mfma_f32_16x16x32_bf16 v[40:43], v[176:179], v[192:195], v[40:43]
	v_mfma_f32_16x16x32_bf16 v[28:31], v[168:171], v[200:203], v[28:31]
	v_mfma_f32_16x16x32_bf16 v[24:27], v[176:179], v[200:203], v[24:27]
	v_mfma_f32_16x16x32_bf16 v[12:15], v[168:171], v[208:211], v[12:15]
	v_mfma_f32_16x16x32_bf16 v[8:11], v[176:179], v[208:211], v[8:11]
	v_mfma_f32_16x16x32_bf16 v[60:63], v[172:175], v[188:191], v[60:63]
	v_mfma_f32_16x16x32_bf16 v[56:59], v[180:183], v[188:191], v[56:59]
	v_mfma_f32_16x16x32_bf16 v[44:47], v[172:175], v[196:199], v[44:47]
	v_mfma_f32_16x16x32_bf16 v[40:43], v[180:183], v[196:199], v[40:43]
	v_mfma_f32_16x16x32_bf16 v[28:31], v[172:175], v[204:207], v[28:31]
	v_mfma_f32_16x16x32_bf16 v[24:27], v[180:183], v[204:207], v[24:27]
	v_mfma_f32_16x16x32_bf16 v[12:15], v[172:175], v[212:215], v[12:15]
	v_mfma_f32_16x16x32_bf16 v[8:11], v[180:183], v[212:215], v[8:11]
	s_setprio 0
	s_barrier
	s_add_i32 s59, 0, 0x18000
	v_add_u32_e32 v155, s59, v149
	s_add_i32 s60, 0, 0x1c000
	ds_read_b128 v[144:147], v155
	ds_read_b128 v[156:159], v155 offset:1024
	ds_read_b128 v[160:163], v155 offset:2048
	ds_read_b128 v[164:167], v155 offset:3072
	v_add_u32_e32 v155, s60, v149
	ds_read_b128 v[168:171], v155
	ds_read_b128 v[172:175], v155 offset:1024
	ds_read_b128 v[176:179], v155 offset:2048
	ds_read_b128 v[180:183], v155 offset:3072
	s_add_u32 s38, s38, 0x80000
	s_addc_u32 s39, s39, 0
	s_mov_b32 m0, s41
	v_lshl_add_u64 v[224:225], s[38:39], 0, v[134:135]
	ds_read_b128 v[184:187], v153 offset:32768
	ds_read_b128 v[188:191], v153 offset:33792
	ds_read_b128 v[192:195], v153 offset:34816
	ds_read_b128 v[196:199], v153 offset:35840
	ds_read_b128 v[200:203], v153 offset:36864
	ds_read_b128 v[204:207], v153 offset:37888
	ds_read_b128 v[208:211], v153 offset:38912
	ds_read_b128 v[212:215], v153 offset:39936
	global_load_lds_dwordx4 v[224:225], off
	v_lshl_add_u64 v[224:225], s[38:39], 0, v[130:131]
	s_mov_b32 m0, s42
	s_nop 0
	global_load_lds_dwordx4 v[224:225], off
	s_waitcnt vmcnt(8)
	s_waitcnt lgkmcnt(0)
	s_barrier
	s_setprio 1
	s_waitcnt lgkmcnt(0)
	v_mfma_f32_16x16x32_bf16 v[116:119], v[144:147], v[184:187], v[116:119]
	v_mfma_f32_16x16x32_bf16 v[112:115], v[160:163], v[184:187], v[112:115]
	v_mfma_f32_16x16x32_bf16 v[100:103], v[144:147], v[192:195], v[100:103]
	v_mfma_f32_16x16x32_bf16 v[96:99], v[160:163], v[192:195], v[96:99]
	v_mfma_f32_16x16x32_bf16 v[84:87], v[144:147], v[200:203], v[84:87]
	v_mfma_f32_16x16x32_bf16 v[80:83], v[160:163], v[200:203], v[80:83]
	v_mfma_f32_16x16x32_bf16 v[68:71], v[144:147], v[208:211], v[68:71]
	v_mfma_f32_16x16x32_bf16 v[64:67], v[160:163], v[208:211], v[64:67]
	v_mfma_f32_16x16x32_bf16 v[116:119], v[156:159], v[188:191], v[116:119]
	v_mfma_f32_16x16x32_bf16 v[112:115], v[164:167], v[188:191], v[112:115]
	v_mfma_f32_16x16x32_bf16 v[100:103], v[156:159], v[196:199], v[100:103]
	v_mfma_f32_16x16x32_bf16 v[96:99], v[164:167], v[196:199], v[96:99]
	v_mfma_f32_16x16x32_bf16 v[84:87], v[156:159], v[204:207], v[84:87]
	v_mfma_f32_16x16x32_bf16 v[80:83], v[164:167], v[204:207], v[80:83]
	v_mfma_f32_16x16x32_bf16 v[68:71], v[156:159], v[212:215], v[68:71]
	v_mfma_f32_16x16x32_bf16 v[64:67], v[164:167], v[212:215], v[64:67]
	s_setprio 0
	s_setprio 1
	v_mfma_f32_16x16x32_bf16 v[124:127], v[168:171], v[184:187], v[124:127]
	v_mfma_f32_16x16x32_bf16 v[120:123], v[176:179], v[184:187], v[120:123]
	v_mfma_f32_16x16x32_bf16 v[108:111], v[168:171], v[192:195], v[108:111]
	v_mfma_f32_16x16x32_bf16 v[104:107], v[176:179], v[192:195], v[104:107]
	v_mfma_f32_16x16x32_bf16 v[92:95], v[168:171], v[200:203], v[92:95]
	v_mfma_f32_16x16x32_bf16 v[88:91], v[176:179], v[200:203], v[88:91]
	v_mfma_f32_16x16x32_bf16 v[76:79], v[168:171], v[208:211], v[76:79]
	v_mfma_f32_16x16x32_bf16 v[72:75], v[176:179], v[208:211], v[72:75]
	v_mfma_f32_16x16x32_bf16 v[124:127], v[172:175], v[188:191], v[124:127]
	v_mfma_f32_16x16x32_bf16 v[120:123], v[180:183], v[188:191], v[120:123]
	v_mfma_f32_16x16x32_bf16 v[108:111], v[172:175], v[196:199], v[108:111]
	v_mfma_f32_16x16x32_bf16 v[104:107], v[180:183], v[196:199], v[104:107]
	v_mfma_f32_16x16x32_bf16 v[92:95], v[172:175], v[204:207], v[92:95]
	v_mfma_f32_16x16x32_bf16 v[88:91], v[180:183], v[204:207], v[88:91]
	v_mfma_f32_16x16x32_bf16 v[76:79], v[172:175], v[212:215], v[76:79]
	v_mfma_f32_16x16x32_bf16 v[72:75], v[180:183], v[212:215], v[72:75]
	s_setprio 0
	s_barrier
; #define PG8_STAGE(bufoff, gbase, voff) do { _Pragma("unroll") for (int _i = 0; _i < 2; ++_i) \
;         __builtin_amdgcn_global_load_lds((const unsigned*)((const char*)(gbase) + (voff)[_i]), (PG8_LAS unsigned*)(lds + (bufoff) + ldsw + _i * 8192), 16, 0, 0); } while (0)
; #define PG8_LDA(dst, b, h) do { _Pragma("unroll") for (int m = 0; m < 4; ++m) _Pragma("unroll") for (int k = 0; k < 2; ++k) dst[m][k] = *(const PG8_LAS bf16x8*)(lds + PG8_SA(b, h) + aoff + m * 2048 + k * 1024); } while (0)
; #define PG8_MMA(ai, bj, At, Bt) do { __builtin_amdgcn_s_setprio(1); _Pragma("unroll") for (int m = 0; m < 4; ++m) _Pragma("unroll") for (int n = 0; n < 2; ++n) _Pragma("unroll") for (int k = 0; k < 2; ++k) \
;         acc[ai][bj][m][n] = __builtin_amdgcn_mfma_f32_16x16x32_bf16(Bt[n][k], At[m][k], acc[ai][bj][m][n], 0, 0, 0); __builtin_amdgcn_s_setprio(0); } while (0)
; #define PG8_WAIT_V(n) asm volatile("s_waitcnt vmcnt(" #n ")" ::: "memory")
; #define PG8_WAIT_L(n) asm volatile("s_waitcnt lgkmcnt(" #n ")" ::: "memory")
; #define PG8_BAR __builtin_amdgcn_s_barrier()
; #define PG8_SCHED __builtin_amdgcn_sched_barrier(0)
; template <class Epi, class Sched, bool ALIGN_EPI = false, bool SP2 = false>
; __device__ __forceinline__ void gemm_phase(PG8_LAS unsigned char* lds, const Gemm g, const Sched& S, const Epi& E, const int wave_in) {
;     ...
;         for (int t = 0; t < nt; t += 2) {
;             const bool last = (t == nt - 2);
;     ...
;             PG8_LDA(At, 1, 1); PG8_STAGE(PG8_SB(1, 0), b3, voffB); PG8_STAGE(PG8_SB(1, 1), b3 + hstep, voffB); PG8_STAGE(PG8_SA(1, 0), a3, voffA);
;             PG8_WAIT_V(8); PG8_WAIT_L(0); PG8_BAR; PG8_MMA(1, 0, At, B0); PG8_MMA(1, 1, At, B1); PG8_BAR; PG8_SCHED;
	s_add_i32 s38, s59, s11
	v_lshl_add_u64 v[216:217], v[216:217], 0, s[6:7]
	s_mov_b32 m0, s38
	ds_read_b128 v[184:187], v153 offset:49152
	ds_read_b128 v[188:191], v153 offset:50176
	ds_read_b128 v[192:195], v153 offset:51200
	ds_read_b128 v[196:199], v153 offset:52224
	ds_read_b128 v[200:203], v153 offset:53248
	ds_read_b128 v[204:207], v153 offset:54272
	ds_read_b128 v[208:211], v153 offset:55296
	ds_read_b128 v[212:215], v153 offset:56320
	global_load_lds_dwordx4 v[216:217], off
	s_add_i32 m0, s38, 0x2000
	s_add_u32 s36, s36, 0x80080
	v_lshl_add_u64 v[216:217], v[218:219], 0, s[6:7]
	s_addc_u32 s37, s37, 0
	s_add_i32 s38, s60, s11
	global_load_lds_dwordx4 v[216:217], off
	v_lshl_add_u64 v[216:217], s[36:37], 0, v[132:133]
	s_mov_b32 m0, s38
	s_nop 0
	global_load_lds_dwordx4 v[216:217], off
	v_lshl_add_u64 v[216:217], s[36:37], 0, v[128:129]
	s_add_i32 m0, s38, 0x2000
	s_nop 0
	global_load_lds_dwordx4 v[216:217], off
	v_lshl_add_u64 v[216:217], v[220:221], 0, s[6:7]
	s_mov_b32 m0, s48
	s_nop 0
	global_load_lds_dwordx4 v[216:217], off
	v_lshl_add_u64 v[216:217], v[222:223], 0, s[6:7]
	s_mov_b32 m0, s49
	s_nop 0
	global_load_lds_dwordx4 v[216:217], off
	s_waitcnt vmcnt(8)
	s_waitcnt lgkmcnt(0)
	s_barrier
	s_setprio 1
	s_waitcnt lgkmcnt(0)
	v_mfma_f32_16x16x32_bf16 v[52:55], v[144:147], v[184:187], v[52:55]
	v_mfma_f32_16x16x32_bf16 v[48:51], v[160:163], v[184:187], v[48:51]
	v_mfma_f32_16x16x32_bf16 v[36:39], v[144:147], v[192:195], v[36:39]
	v_mfma_f32_16x16x32_bf16 v[32:35], v[160:163], v[192:195], v[32:35]
	v_mfma_f32_16x16x32_bf16 v[20:23], v[144:147], v[200:203], v[20:23]
	v_mfma_f32_16x16x32_bf16 v[16:19], v[160:163], v[200:203], v[16:19]
	v_mfma_f32_16x16x32_bf16 v[4:7], v[144:147], v[208:211], v[4:7]
	v_mfma_f32_16x16x32_bf16 v[0:3], v[160:163], v[208:211], v[0:3]
	v_mfma_f32_16x16x32_bf16 v[52:55], v[156:159], v[188:191], v[52:55]
	v_mfma_f32_16x16x32_bf16 v[48:51], v[164:167], v[188:191], v[48:51]
	v_mfma_f32_16x16x32_bf16 v[36:39], v[156:159], v[196:199], v[36:39]
	v_mfma_f32_16x16x32_bf16 v[32:35], v[164:167], v[196:199], v[32:35]
	v_mfma_f32_16x16x32_bf16 v[20:23], v[156:159], v[204:207], v[20:23]
	v_mfma_f32_16x16x32_bf16 v[16:19], v[164:167], v[204:207], v[16:19]
	v_mfma_f32_16x16x32_bf16 v[4:7], v[156:159], v[212:215], v[4:7]
	v_mfma_f32_16x16x32_bf16 v[0:3], v[164:167], v[212:215], v[0:3]
	s_setprio 0
	s_setprio 1
	v_mfma_f32_16x16x32_bf16 v[60:63], v[168:171], v[184:187], v[60:63]
	v_mfma_f32_16x16x32_bf16 v[56:59], v[176:179], v[184:187], v[56:59]
	v_mfma_f32_16x16x32_bf16 v[44:47], v[168:171], v[192:195], v[44:47]
	v_mfma_f32_16x16x32_bf16 v[40:43], v[176:179], v[192:195], v[40:43]
	v_mfma_f32_16x16x32_bf16 v[28:31], v[168:171], v[200:203], v[28:31]
	v_mfma_f32_16x16x32_bf16 v[24:27], v[176:179], v[200:203], v[24:27]
	v_mfma_f32_16x16x32_bf16 v[12:15], v[168:171], v[208:211], v[12:15]
	v_mfma_f32_16x16x32_bf16 v[8:11], v[176:179], v[208:211], v[8:11]
	v_mfma_f32_16x16x32_bf16 v[60:63], v[172:175], v[188:191], v[60:63]
	v_mfma_f32_16x16x32_bf16 v[56:59], v[180:183], v[188:191], v[56:59]
	v_mfma_f32_16x16x32_bf16 v[44:47], v[172:175], v[196:199], v[44:47]
	v_mfma_f32_16x16x32_bf16 v[40:43], v[180:183], v[196:199], v[40:43]
	v_mfma_f32_16x16x32_bf16 v[28:31], v[172:175], v[204:207], v[28:31]
	v_mfma_f32_16x16x32_bf16 v[24:27], v[180:183], v[204:207], v[24:27]
	v_mfma_f32_16x16x32_bf16 v[12:15], v[172:175], v[212:215], v[12:15]
	v_mfma_f32_16x16x32_bf16 v[8:11], v[180:183], v[212:215], v[8:11]
	s_setprio 0
	s_add_i32 s58, s58, 2
	s_add_u32 s24, s24, 0x100
	s_addc_u32 s25, s25, 0
	s_add_u32 s56, s56, 0x100
	s_addc_u32 s57, s57, 0
	s_cmp_gt_u32 s58, 29
	s_barrier
	s_cbranch_scc0 .LBB0_2169
	s_and_b64 vcc, exec, s[12:13]
	s_cbranch_vccz .LBB0_2172
	s_barrier

; #define PG8_STAGE(bufoff, gbase, voff) do { _Pragma("unroll") for (int _i = 0; _i < 2; ++_i) \
;         __builtin_amdgcn_global_load_lds((const unsigned*)((const char*)(gbase) + (voff)[_i]), (PG8_LAS unsigned*)(lds + (bufoff) + ldsw + _i * 8192), 16, 0, 0); } while (0)
; #define PG8_LDA(dst, b, h) do { _Pragma("unroll") for (int m = 0; m < 4; ++m) _Pragma("unroll") for (int k = 0; k < 2; ++k) dst[m][k] = *(const PG8_LAS bf16x8*)(lds + PG8_SA(b, h) + aoff + m * 2048 + k * 1024); } while (0)
; #define PG8_LDB(dst, b, h) do { _Pragma("unroll") for (int n = 0; n < 2; ++n) _Pragma("unroll") for (int k = 0; k < 2; ++k) dst[n][k] = *(const PG8_LAS bf16x8*)(lds + PG8_SB(b, h) + boff + n * 2048 + k * 1024); } while (0)
; #define PG8_MMA(ai, bj, At, Bt) do { __builtin_amdgcn_s_setprio(1); _Pragma("unroll") for (int m = 0; m < 4; ++m) _Pragma("unroll") for (int n = 0; n < 2; ++n) _Pragma("unroll") for (int k = 0; k < 2; ++k) \
;         acc[ai][bj][m][n] = __builtin_amdgcn_mfma_f32_16x16x32_bf16(Bt[n][k], At[m][k], acc[ai][bj][m][n], 0, 0, 0); __builtin_amdgcn_s_setprio(0); } while (0)
; #define PG8_WAIT_V(n) asm volatile("s_waitcnt vmcnt(" #n ")" ::: "memory")
; #define PG8_WAIT_L(n) asm volatile("s_waitcnt lgkmcnt(" #n ")" ::: "memory")
; template <class Epi, class Sched, bool ALIGN_EPI = false, bool SP2 = false>
; __device__ __forceinline__ void gemm_phase(PG8_LAS unsigned char* lds, const Gemm g, const Sched& S, const Epi& E, const int wave_in) {
;     ...
;             const bool last = (t == nt - 2);
;             const char* a1 = cA + (size_t)(t + 1) * kstep;
;             const char* a2 = last ? nA : cA + (size_t)(t + 2) * kstep; const char* b2 = last ? nB : cB + (size_t)(t + 2) * kstep;
;             const char* a3 = a2 + kstep; const char* b3 = b2 + kstep;
;             if (last && has_next) S.a_ready(nxt);
;             if constexpr (SP2) {
;             PG8_LDB(B0, 0, 0); PG8_LDB(B1, 0, 1); PG8_SCHED; PG8_LDA(At, 0, 0); PG8_STAGE(PG8_SA(1, 1), a1 + hstepA, voffA);
;             PG8_WAIT_V(8); PG8_WAIT_L(0); PG8_BAR; PG8_MMA(0, 0, At, B0); PG8_MMA(0, 1, At, B1); PG8_BAR; PG8_SCHED;
;             PG8_LDA(At, 0, 1); PG8_STAGE(PG8_SB(0, 0), b2, voffB); PG8_STAGE(PG8_SB(0, 1), b2 + hstep, voffB); PG8_STAGE(PG8_SA(0, 0), a2, voffA);
;             PG8_WAIT_V(8); PG8_WAIT_L(0); PG8_BAR; PG8_MMA(1, 0, At, B0); PG8_MMA(1, 1, At, B1); PG8_BAR; PG8_SCHED;
.LBB0_2254:
	ds_read_b128 v[144:147], v151
	ds_read_b128 v[156:159], v151 offset:1024
	ds_read_b128 v[160:163], v151 offset:2048
	ds_read_b128 v[164:167], v151 offset:3072
	ds_read_b128 v[168:171], v152
	ds_read_b128 v[172:175], v152 offset:1024
	ds_read_b128 v[176:179], v152 offset:2048
	ds_read_b128 v[180:183], v152 offset:3072
	s_add_u32 s22, s20, 0x100
	s_addc_u32 s23, s21, 0
	s_cmpk_eq_i32 s53, 0x54
	s_cselect_b32 s37, s7, s23
	s_cselect_b32 s36, s6, s22
	s_cselect_b32 s25, s19, s52
	s_cselect_b32 s24, s18, s51
	v_lshl_add_u64 v[216:217], s[20:21], 0, v[136:137]
	s_add_i32 m0, s33, 0xc000
	ds_read_b128 v[184:187], v153
	ds_read_b128 v[188:191], v153 offset:1024
	ds_read_b128 v[192:195], v153 offset:2048
	ds_read_b128 v[196:199], v153 offset:3072
	ds_read_b128 v[200:203], v153 offset:4096
	ds_read_b128 v[204:207], v153 offset:5120
	ds_read_b128 v[208:211], v153 offset:6144
	ds_read_b128 v[212:215], v153 offset:7168
	global_load_lds_dwordx4 v[216:217], off
	v_lshl_add_u64 v[216:217], s[20:21], 0, v[138:139]
	s_add_i32 m0, s33, 0xe000
	s_nop 0
	global_load_lds_dwordx4 v[216:217], off
	s_waitcnt vmcnt(8)
	s_waitcnt lgkmcnt(0)
	s_barrier
	s_setprio 1
	s_waitcnt lgkmcnt(0)
	v_mfma_f32_16x16x32_bf16 v[124:127], v[144:147], v[184:187], v[124:127]
	v_mfma_f32_16x16x32_bf16 v[120:123], v[160:163], v[184:187], v[120:123]
	v_mfma_f32_16x16x32_bf16 v[108:111], v[144:147], v[192:195], v[108:111]
	v_mfma_f32_16x16x32_bf16 v[104:107], v[160:163], v[192:195], v[104:107]
	v_mfma_f32_16x16x32_bf16 v[92:95], v[144:147], v[200:203], v[92:95]
	v_mfma_f32_16x16x32_bf16 v[88:91], v[160:163], v[200:203], v[88:91]
	v_mfma_f32_16x16x32_bf16 v[76:79], v[144:147], v[208:211], v[76:79]
	v_mfma_f32_16x16x32_bf16 v[72:75], v[160:163], v[208:211], v[72:75]
	v_mfma_f32_16x16x32_bf16 v[124:127], v[156:159], v[188:191], v[124:127]
	v_mfma_f32_16x16x32_bf16 v[120:123], v[164:167], v[188:191], v[120:123]
	v_mfma_f32_16x16x32_bf16 v[108:111], v[156:159], v[196:199], v[108:111]
	v_mfma_f32_16x16x32_bf16 v[104:107], v[164:167], v[196:199], v[104:107]
	v_mfma_f32_16x16x32_bf16 v[92:95], v[156:159], v[204:207], v[92:95]
	v_mfma_f32_16x16x32_bf16 v[88:91], v[164:167], v[204:207], v[88:91]
	v_mfma_f32_16x16x32_bf16 v[76:79], v[156:159], v[212:215], v[76:79]
	v_mfma_f32_16x16x32_bf16 v[72:75], v[164:167], v[212:215], v[72:75]
	s_setprio 0
	s_setprio 1
	v_mfma_f32_16x16x32_bf16 v[116:119], v[168:171], v[184:187], v[116:119]
	v_mfma_f32_16x16x32_bf16 v[112:115], v[176:179], v[184:187], v[112:115]
	v_mfma_f32_16x16x32_bf16 v[100:103], v[168:171], v[192:195], v[100:103]
	v_mfma_f32_16x16x32_bf16 v[96:99], v[176:179], v[192:195], v[96:99]
	v_mfma_f32_16x16x32_bf16 v[84:87], v[168:171], v[200:203], v[84:87]
	v_mfma_f32_16x16x32_bf16 v[80:83], v[176:179], v[200:203], v[80:83]
	v_mfma_f32_16x16x32_bf16 v[68:71], v[168:171], v[208:211], v[68:71]
	v_mfma_f32_16x16x32_bf16 v[64:67], v[176:179], v[208:211], v[64:67]
	v_mfma_f32_16x16x32_bf16 v[116:119], v[172:175], v[188:191], v[116:119]
	v_mfma_f32_16x16x32_bf16 v[112:115], v[180:183], v[188:191], v[112:115]
	v_mfma_f32_16x16x32_bf16 v[100:103], v[172:175], v[196:199], v[100:103]
	v_mfma_f32_16x16x32_bf16 v[96:99], v[180:183], v[196:199], v[96:99]
	v_mfma_f32_16x16x32_bf16 v[84:87], v[172:175], v[204:207], v[84:87]
	v_mfma_f32_16x16x32_bf16 v[80:83], v[180:183], v[204:207], v[80:83]
	v_mfma_f32_16x16x32_bf16 v[68:71], v[172:175], v[212:215], v[68:71]
	v_mfma_f32_16x16x32_bf16 v[64:67], v[180:183], v[212:215], v[64:67]
	s_setprio 0
	s_barrier
	s_add_i32 s20, s43, s11
	v_lshl_add_u64 v[216:217], s[24:25], 0, v[130:131]
	s_mov_b32 m0, s20
	ds_read_b128 v[184:187], v153 offset:16384
	ds_read_b128 v[188:191], v153 offset:17408
	ds_read_b128 v[192:195], v153 offset:18432
	ds_read_b128 v[196:199], v153 offset:19456
	ds_read_b128 v[200:203], v153 offset:20480
	ds_read_b128 v[204:207], v153 offset:21504
	ds_read_b128 v[208:211], v153 offset:22528
	ds_read_b128 v[212:215], v153 offset:23552
	global_load_lds_dwordx4 v[216:217], off
	s_add_i32 m0, s20, 0x2000
	s_add_u32 s20, s24, 0x160000
	v_lshl_add_u64 v[218:219], s[24:25], 0, v[134:135]
	s_addc_u32 s21, s25, 0
	s_add_i32 s54, s46, s11
	global_load_lds_dwordx4 v[218:219], off
	v_lshl_add_u64 v[220:221], s[20:21], 0, v[130:131]
	s_mov_b32 m0, s54
	v_lshl_add_u64 v[222:223], s[36:37], 0, v[132:133]
	global_load_lds_dwordx4 v[220:221], off
	v_lshl_add_u64 v[220:221], s[20:21], 0, v[134:135]
	s_add_i32 m0, s54, 0x2000
	s_nop 0
	global_load_lds_dwordx4 v[220:221], off
	v_lshl_add_u64 v[220:221], s[36:37], 0, v[128:129]
	s_mov_b32 m0, s33
	s_nop 0
	global_load_lds_dwordx4 v[220:221], off
	s_mov_b32 m0, s35
	s_nop 0
	global_load_lds_dwordx4 v[222:223], off
	s_waitcnt vmcnt(8)
	s_waitcnt lgkmcnt(0)
	s_barrier
; #define PG8_STAGE(bufoff, gbase, voff) do { _Pragma("unroll") for (int _i = 0; _i < 2; ++_i) \
;         __builtin_amdgcn_global_load_lds((const unsigned*)((const char*)(gbase) + (voff)[_i]), (PG8_LAS unsigned*)(lds + (bufoff) + ldsw + _i * 8192), 16, 0, 0); } while (0)
; #define PG8_LDA(dst, b, h) do { _Pragma("unroll") for (int m = 0; m < 4; ++m) _Pragma("unroll") for (int k = 0; k < 2; ++k) dst[m][k] = *(const PG8_LAS bf16x8*)(lds + PG8_SA(b, h) + aoff + m * 2048 + k * 1024); } while (0)
; #define PG8_LDB(dst, b, h) do { _Pragma("unroll") for (int n = 0; n < 2; ++n) _Pragma("unroll") for (int k = 0; k < 2; ++k) dst[n][k] = *(const PG8_LAS bf16x8*)(lds + PG8_SB(b, h) + boff + n * 2048 + k * 1024); } while (0)
; #define PG8_MMA(ai, bj, At, Bt) do { __builtin_amdgcn_s_setprio(1); _Pragma("unroll") for (int m = 0; m < 4; ++m) _Pragma("unroll") for (int n = 0; n < 2; ++n) _Pragma("unroll") for (int k = 0; k < 2; ++k) \
;         acc[ai][bj][m][n] = __builtin_amdgcn_mfma_f32_16x16x32_bf16(Bt[n][k], At[m][k], acc[ai][bj][m][n], 0, 0, 0); __builtin_amdgcn_s_setprio(0); } while (0)
; #define PG8_WAIT_V(n) asm volatile("s_waitcnt vmcnt(" #n ")" ::: "memory")
; #define PG8_WAIT_L(n) asm volatile("s_waitcnt lgkmcnt(" #n ")" ::: "memory")
; #define PG8_BAR __builtin_amdgcn_s_barrier()
; #define PG8_SCHED __builtin_amdgcn_sched_barrier(0)
; template <class Epi, class Sched, bool ALIGN_EPI = false, bool SP2 = false>
; __device__ __forceinline__ void gemm_phase(PG8_LAS unsigned char* lds, const Gemm g, const Sched& S, const Epi& E, const int wave_in) {
;     ...
;             PG8_WAIT_V(8); PG8_WAIT_L(0); PG8_BAR; PG8_MMA(1, 0, At, B0); PG8_MMA(1, 1, At, B1); PG8_BAR; PG8_SCHED;
;             PG8_LDB(B0, 1, 0); PG8_LDB(B1, 1, 1); PG8_SCHED; PG8_LDA(At, 1, 0); PG8_STAGE(PG8_SA(0, 1), a2 + hstepA, voffA);
;             PG8_WAIT_V(8); PG8_WAIT_L(0); PG8_BAR; PG8_MMA(0, 0, At, B0); PG8_MMA(0, 1, At, B1); PG8_BAR; PG8_SCHED;
	s_setprio 1
	s_waitcnt lgkmcnt(0)
	v_mfma_f32_16x16x32_bf16 v[60:63], v[144:147], v[184:187], v[60:63]
	v_mfma_f32_16x16x32_bf16 v[56:59], v[160:163], v[184:187], v[56:59]
	v_mfma_f32_16x16x32_bf16 v[44:47], v[144:147], v[192:195], v[44:47]
	v_mfma_f32_16x16x32_bf16 v[40:43], v[160:163], v[192:195], v[40:43]
	v_mfma_f32_16x16x32_bf16 v[28:31], v[144:147], v[200:203], v[28:31]
	v_mfma_f32_16x16x32_bf16 v[24:27], v[160:163], v[200:203], v[24:27]
	v_mfma_f32_16x16x32_bf16 v[12:15], v[144:147], v[208:211], v[12:15]
	v_mfma_f32_16x16x32_bf16 v[8:11], v[160:163], v[208:211], v[8:11]
	v_mfma_f32_16x16x32_bf16 v[60:63], v[156:159], v[188:191], v[60:63]
	v_mfma_f32_16x16x32_bf16 v[56:59], v[164:167], v[188:191], v[56:59]
	v_mfma_f32_16x16x32_bf16 v[44:47], v[156:159], v[196:199], v[44:47]
	v_mfma_f32_16x16x32_bf16 v[40:43], v[164:167], v[196:199], v[40:43]
	v_mfma_f32_16x16x32_bf16 v[28:31], v[156:159], v[204:207], v[28:31]
	v_mfma_f32_16x16x32_bf16 v[24:27], v[164:167], v[204:207], v[24:27]
	v_mfma_f32_16x16x32_bf16 v[12:15], v[156:159], v[212:215], v[12:15]
	v_mfma_f32_16x16x32_bf16 v[8:11], v[164:167], v[212:215], v[8:11]
	s_setprio 0
	s_setprio 1
	v_mfma_f32_16x16x32_bf16 v[52:55], v[168:171], v[184:187], v[52:55]
	v_mfma_f32_16x16x32_bf16 v[48:51], v[176:179], v[184:187], v[48:51]
	v_mfma_f32_16x16x32_bf16 v[36:39], v[168:171], v[192:195], v[36:39]
	v_mfma_f32_16x16x32_bf16 v[32:35], v[176:179], v[192:195], v[32:35]
	v_mfma_f32_16x16x32_bf16 v[20:23], v[168:171], v[200:203], v[20:23]
	v_mfma_f32_16x16x32_bf16 v[16:19], v[176:179], v[200:203], v[16:19]
	v_mfma_f32_16x16x32_bf16 v[4:7], v[168:171], v[208:211], v[4:7]
	v_mfma_f32_16x16x32_bf16 v[0:3], v[176:179], v[208:211], v[0:3]
	v_mfma_f32_16x16x32_bf16 v[52:55], v[172:175], v[188:191], v[52:55]
	v_mfma_f32_16x16x32_bf16 v[48:51], v[180:183], v[188:191], v[48:51]
	v_mfma_f32_16x16x32_bf16 v[36:39], v[172:175], v[196:199], v[36:39]
	v_mfma_f32_16x16x32_bf16 v[32:35], v[180:183], v[196:199], v[32:35]
	v_mfma_f32_16x16x32_bf16 v[20:23], v[172:175], v[204:207], v[20:23]
	v_mfma_f32_16x16x32_bf16 v[16:19], v[180:183], v[204:207], v[16:19]
	v_mfma_f32_16x16x32_bf16 v[4:7], v[172:175], v[212:215], v[4:7]
	v_mfma_f32_16x16x32_bf16 v[0:3], v[180:183], v[212:215], v[0:3]
	s_setprio 0
	s_barrier
	s_add_i32 s54, 0, 0x18000
	v_add_u32_e32 v155, s54, v149
	s_add_i32 s55, 0, 0x1c000
	ds_read_b128 v[144:147], v155
	ds_read_b128 v[156:159], v155 offset:1024
	ds_read_b128 v[160:163], v155 offset:2048
	ds_read_b128 v[164:167], v155 offset:3072
	v_add_u32_e32 v155, s55, v149
	ds_read_b128 v[168:171], v155
	ds_read_b128 v[172:175], v155 offset:1024
	ds_read_b128 v[176:179], v155 offset:2048
	ds_read_b128 v[180:183], v155 offset:3072
	s_add_u32 s20, s36, 0x160000
	s_addc_u32 s21, s37, 0
	s_mov_b32 m0, s38
	v_lshl_add_u64 v[224:225], s[20:21], 0, v[128:129]
	ds_read_b128 v[184:187], v153 offset:32768
	ds_read_b128 v[188:191], v153 offset:33792
	ds_read_b128 v[192:195], v153 offset:34816
	ds_read_b128 v[196:199], v153 offset:35840
	ds_read_b128 v[200:203], v153 offset:36864
	ds_read_b128 v[204:207], v153 offset:37888
	ds_read_b128 v[208:211], v153 offset:38912
	ds_read_b128 v[212:215], v153 offset:39936
	global_load_lds_dwordx4 v[224:225], off
	v_lshl_add_u64 v[224:225], s[20:21], 0, v[132:133]
	s_mov_b32 m0, s39
	s_nop 0
	global_load_lds_dwordx4 v[224:225], off
	s_waitcnt vmcnt(8)
	s_waitcnt lgkmcnt(0)
	s_barrier
	s_setprio 1
	s_waitcnt lgkmcnt(0)
	v_mfma_f32_16x16x32_bf16 v[124:127], v[144:147], v[184:187], v[124:127]
	v_mfma_f32_16x16x32_bf16 v[120:123], v[160:163], v[184:187], v[120:123]
	v_mfma_f32_16x16x32_bf16 v[108:111], v[144:147], v[192:195], v[108:111]
	v_mfma_f32_16x16x32_bf16 v[104:107], v[160:163], v[192:195], v[104:107]
	v_mfma_f32_16x16x32_bf16 v[92:95], v[144:147], v[200:203], v[92:95]
	v_mfma_f32_16x16x32_bf16 v[88:91], v[160:163], v[200:203], v[88:91]
	v_mfma_f32_16x16x32_bf16 v[76:79], v[144:147], v[208:211], v[76:79]
	v_mfma_f32_16x16x32_bf16 v[72:75], v[160:163], v[208:211], v[72:75]
	v_mfma_f32_16x16x32_bf16 v[124:127], v[156:159], v[188:191], v[124:127]
	v_mfma_f32_16x16x32_bf16 v[120:123], v[164:167], v[188:191], v[120:123]
	v_mfma_f32_16x16x32_bf16 v[108:111], v[156:159], v[196:199], v[108:111]
	v_mfma_f32_16x16x32_bf16 v[104:107], v[164:167], v[196:199], v[104:107]
	v_mfma_f32_16x16x32_bf16 v[92:95], v[156:159], v[204:207], v[92:95]
	v_mfma_f32_16x16x32_bf16 v[88:91], v[164:167], v[204:207], v[88:91]
	v_mfma_f32_16x16x32_bf16 v[76:79], v[156:159], v[212:215], v[76:79]
	v_mfma_f32_16x16x32_bf16 v[72:75], v[164:167], v[212:215], v[72:75]
	s_setprio 0
	s_setprio 1
	v_mfma_f32_16x16x32_bf16 v[116:119], v[168:171], v[184:187], v[116:119]
	v_mfma_f32_16x16x32_bf16 v[112:115], v[176:179], v[184:187], v[112:115]
	v_mfma_f32_16x16x32_bf16 v[100:103], v[168:171], v[192:195], v[100:103]
	v_mfma_f32_16x16x32_bf16 v[96:99], v[176:179], v[192:195], v[96:99]
	v_mfma_f32_16x16x32_bf16 v[84:87], v[168:171], v[200:203], v[84:87]
	v_mfma_f32_16x16x32_bf16 v[80:83], v[176:179], v[200:203], v[80:83]
	v_mfma_f32_16x16x32_bf16 v[68:71], v[168:171], v[208:211], v[68:71]
	v_mfma_f32_16x16x32_bf16 v[64:67], v[176:179], v[208:211], v[64:67]
	v_mfma_f32_16x16x32_bf16 v[116:119], v[172:175], v[188:191], v[116:119]
	v_mfma_f32_16x16x32_bf16 v[112:115], v[180:183], v[188:191], v[112:115]
	v_mfma_f32_16x16x32_bf16 v[100:103], v[172:175], v[196:199], v[100:103]
	v_mfma_f32_16x16x32_bf16 v[96:99], v[180:183], v[196:199], v[96:99]
	v_mfma_f32_16x16x32_bf16 v[84:87], v[172:175], v[204:207], v[84:87]
	v_mfma_f32_16x16x32_bf16 v[80:83], v[180:183], v[204:207], v[80:83]
	v_mfma_f32_16x16x32_bf16 v[68:71], v[172:175], v[212:215], v[68:71]
	v_mfma_f32_16x16x32_bf16 v[64:67], v[180:183], v[212:215], v[64:67]
	s_setprio 0
	s_barrier
; #define PG8_STAGE(bufoff, gbase, voff) do { _Pragma("unroll") for (int _i = 0; _i < 2; ++_i) \
;         __builtin_amdgcn_global_load_lds((const unsigned*)((const char*)(gbase) + (voff)[_i]), (PG8_LAS unsigned*)(lds + (bufoff) + ldsw + _i * 8192), 16, 0, 0); } while (0)
; #define PG8_LDA(dst, b, h) do { _Pragma("unroll") for (int m = 0; m < 4; ++m) _Pragma("unroll") for (int k = 0; k < 2; ++k) dst[m][k] = *(const PG8_LAS bf16x8*)(lds + PG8_SA(b, h) + aoff + m * 2048 + k * 1024); } while (0)
; #define PG8_MMA(ai, bj, At, Bt) do { __builtin_amdgcn_s_setprio(1); _Pragma("unroll") for (int m = 0; m < 4; ++m) _Pragma("unroll") for (int n = 0; n < 2; ++n) _Pragma("unroll") for (int k = 0; k < 2; ++k) \
;         acc[ai][bj][m][n] = __builtin_amdgcn_mfma_f32_16x16x32_bf16(Bt[n][k], At[m][k], acc[ai][bj][m][n], 0, 0, 0); __builtin_amdgcn_s_setprio(0); } while (0)
; #define PG8_WAIT_V(n) asm volatile("s_waitcnt vmcnt(" #n ")" ::: "memory")
; #define PG8_WAIT_L(n) asm volatile("s_waitcnt lgkmcnt(" #n ")" ::: "memory")
; #define PG8_BAR __builtin_amdgcn_s_barrier()
; #define PG8_SCHED __builtin_amdgcn_sched_barrier(0)
; template <class Epi, class Sched, bool ALIGN_EPI = false, bool SP2 = false>
; __device__ __forceinline__ void gemm_phase(PG8_LAS unsigned char* lds, const Gemm g, const Sched& S, const Epi& E, const int wave_in) {
;     ...
;         for (int t = 0; t < nt; t += 2) {
;             const bool last = (t == nt - 2);
;     ...
;             PG8_LDA(At, 1, 1); PG8_STAGE(PG8_SB(1, 0), b3, voffB); PG8_STAGE(PG8_SB(1, 1), b3 + hstep, voffB); PG8_STAGE(PG8_SA(1, 0), a3, voffA);
;             PG8_WAIT_V(8); PG8_WAIT_L(0); PG8_BAR; PG8_MMA(1, 0, At, B0); PG8_MMA(1, 1, At, B1); PG8_BAR; PG8_SCHED;
	s_add_i32 s20, s54, s11
	v_lshl_add_u64 v[216:217], v[216:217], 0, s[14:15]
	s_mov_b32 m0, s20
	ds_read_b128 v[184:187], v153 offset:49152
	ds_read_b128 v[188:191], v153 offset:50176
	ds_read_b128 v[192:195], v153 offset:51200
	ds_read_b128 v[196:199], v153 offset:52224
	ds_read_b128 v[200:203], v153 offset:53248
	ds_read_b128 v[204:207], v153 offset:54272
	ds_read_b128 v[208:211], v153 offset:55296
	ds_read_b128 v[212:215], v153 offset:56320
	global_load_lds_dwordx4 v[216:217], off
	s_add_i32 m0, s20, 0x2000
	s_add_u32 s20, s24, 0x160080
	v_lshl_add_u64 v[216:217], v[218:219], 0, s[14:15]
	s_addc_u32 s21, s25, 0
	s_add_i32 s24, s55, s11
	global_load_lds_dwordx4 v[216:217], off
	v_lshl_add_u64 v[216:217], s[20:21], 0, v[130:131]
	s_mov_b32 m0, s24
	s_nop 0
	global_load_lds_dwordx4 v[216:217], off
	v_lshl_add_u64 v[216:217], s[20:21], 0, v[134:135]
	s_add_i32 m0, s24, 0x2000
	s_nop 0
	global_load_lds_dwordx4 v[216:217], off
	v_lshl_add_u64 v[216:217], v[220:221], 0, s[14:15]
	s_mov_b32 m0, s41
	s_nop 0
	global_load_lds_dwordx4 v[216:217], off
	v_lshl_add_u64 v[216:217], v[222:223], 0, s[14:15]
	s_mov_b32 m0, s42
	s_nop 0
	global_load_lds_dwordx4 v[216:217], off
	s_waitcnt vmcnt(8)
	s_waitcnt lgkmcnt(0)
	s_barrier
	s_setprio 1
	s_waitcnt lgkmcnt(0)
	v_mfma_f32_16x16x32_bf16 v[60:63], v[144:147], v[184:187], v[60:63]
	v_mfma_f32_16x16x32_bf16 v[56:59], v[160:163], v[184:187], v[56:59]
	v_mfma_f32_16x16x32_bf16 v[44:47], v[144:147], v[192:195], v[44:47]
	v_mfma_f32_16x16x32_bf16 v[40:43], v[160:163], v[192:195], v[40:43]
	v_mfma_f32_16x16x32_bf16 v[28:31], v[144:147], v[200:203], v[28:31]
	v_mfma_f32_16x16x32_bf16 v[24:27], v[160:163], v[200:203], v[24:27]
	v_mfma_f32_16x16x32_bf16 v[12:15], v[144:147], v[208:211], v[12:15]
	v_mfma_f32_16x16x32_bf16 v[8:11], v[160:163], v[208:211], v[8:11]
	v_mfma_f32_16x16x32_bf16 v[60:63], v[156:159], v[188:191], v[60:63]
	v_mfma_f32_16x16x32_bf16 v[56:59], v[164:167], v[188:191], v[56:59]
	v_mfma_f32_16x16x32_bf16 v[44:47], v[156:159], v[196:199], v[44:47]
	v_mfma_f32_16x16x32_bf16 v[40:43], v[164:167], v[196:199], v[40:43]
	v_mfma_f32_16x16x32_bf16 v[28:31], v[156:159], v[204:207], v[28:31]
	v_mfma_f32_16x16x32_bf16 v[24:27], v[164:167], v[204:207], v[24:27]
	v_mfma_f32_16x16x32_bf16 v[12:15], v[156:159], v[212:215], v[12:15]
	v_mfma_f32_16x16x32_bf16 v[8:11], v[164:167], v[212:215], v[8:11]
	s_setprio 0
	s_setprio 1
	v_mfma_f32_16x16x32_bf16 v[52:55], v[168:171], v[184:187], v[52:55]
	v_mfma_f32_16x16x32_bf16 v[48:51], v[176:179], v[184:187], v[48:51]
	v_mfma_f32_16x16x32_bf16 v[36:39], v[168:171], v[192:195], v[36:39]
	v_mfma_f32_16x16x32_bf16 v[32:35], v[176:179], v[192:195], v[32:35]
	v_mfma_f32_16x16x32_bf16 v[20:23], v[168:171], v[200:203], v[20:23]
	v_mfma_f32_16x16x32_bf16 v[16:19], v[176:179], v[200:203], v[16:19]
	v_mfma_f32_16x16x32_bf16 v[4:7], v[168:171], v[208:211], v[4:7]
	v_mfma_f32_16x16x32_bf16 v[0:3], v[176:179], v[208:211], v[0:3]
	v_mfma_f32_16x16x32_bf16 v[52:55], v[172:175], v[188:191], v[52:55]
	v_mfma_f32_16x16x32_bf16 v[48:51], v[180:183], v[188:191], v[48:51]
	v_mfma_f32_16x16x32_bf16 v[36:39], v[172:175], v[196:199], v[36:39]
	v_mfma_f32_16x16x32_bf16 v[32:35], v[180:183], v[196:199], v[32:35]
	v_mfma_f32_16x16x32_bf16 v[20:23], v[172:175], v[204:207], v[20:23]
	v_mfma_f32_16x16x32_bf16 v[16:19], v[180:183], v[204:207], v[16:19]
	v_mfma_f32_16x16x32_bf16 v[4:7], v[172:175], v[212:215], v[4:7]
	v_mfma_f32_16x16x32_bf16 v[0:3], v[180:183], v[212:215], v[0:3]
	s_setprio 0
	s_add_i32 s53, s53, 2
	s_add_u32 s51, s51, 0x100
	s_addc_u32 s52, s52, 0
	s_cmpk_gt_u32 s53, 0x55
	s_mov_b64 s[20:21], s[22:23]
	s_barrier
	s_cbranch_scc0 .LBB0_2254
	s_and_b64 vcc, exec, s[16:17]
	s_cbranch_vccz .LBB0_2257
	s_barrier
